# EVIN epilogue: one straight-line variant per column group, sigmoid/silu via v_rcp_f32 in batches of 8, saddr global stores
# baseline (speedup 1.0000x reference)
; template <int MODE> __device__ __forceinline__ void gemm_epilogue(f32x4 (&acc)[2][2][4][2], const GD& g, const pg8::Unit& u, int wr, int wc, int fr, int fq, LAS unsigned char* lds, const float (&rsv)[2][4]) {
;     ...
;     } else if constexpr (MODE == EP_EVIN) {
;         const int sel = u.pn >> 2; const int col0 = (u.pn & 3) * 256 + ct;
;         if (sel == 2) {
;             const float* LB = g.f0; float* LOGF = (float*)g.o2;
;             f32x4 lb[2][2];
; #pragma unroll
;             for (int bj = 0; bj < 2; ++bj)
; #pragma unroll
;                 for (int n = 0; n < 2; ++n) lb[bj][n] = *(const f32x4*)(LB + col0 + bj * 128 + 4 * n);
; #pragma unroll
;             for (int ai = 0; ai < 2; ++ai)
; #pragma unroll
;                 for (int m = 0; m < 4; ++m) { float* rowp = LOGF + (size_t)(rt + ai * 128 + m * 16) * 1024 + col0;
; #pragma unroll
;                     for (int bj = 0; bj < 2; ++bj)
;                     {
; #pragma unroll
;                         for (int n = 0; n < 2; ++n) { f32x4 v = acc[ai][bj][m][n], o;
; #pragma unroll
;                             for (int j = 0; j < 4; ++j) { const float sg = 1.f / (1.f + __expf(-v[j])); const float f = lb[bj][n][j] + (1.f - lb[bj][n][j]) * sg; o[j] = __logf(f); }
;                             *(f32x4*)(rowp + bj * 128 + 4 * n) = o; } } }
;         } else {
;             bf16_t* O = (bf16_t*)((char*)g.o0 + (size_t)(sel - (sel > 2 ? 1 : 0)) * (32 * MiB));
; #pragma unroll
;             for (int ai = 0; ai < 2; ++ai)
; #pragma unroll
;                 for (int m = 0; m < 4; ++m) { bf16_t* rowp = O + (size_t)(rt + ai * 128 + m * 16) * 1024 + col0;
; #pragma unroll
;                     for (int bj = 0; bj < 2; ++bj) { f32x4 v0 = acc[ai][bj][m][0], v1 = acc[ai][bj][m][1];
;                         if (sel == 1) {
; #pragma unroll
;                             for (int j = 0; j < 4; ++j) { v0[j] = siluf(v0[j]) * 0.08838834764831845f; v1[j] = siluf(v1[j]) * 0.08838834764831845f; } }
;                         if (sel == 4) {
; #pragma unroll
;                             for (int j = 0; j < 4; ++j) { v0[j] = siluf(v0[j]); v1[j] = siluf(v1[j]); } }
;                         u32x4 w; w.x = cvt_pk_bf16(v0[0], v0[1]); w.y = cvt_pk_bf16(v0[2], v0[3]); w.z = cvt_pk_bf16(v1[0], v1[1]); w.w = cvt_pk_bf16(v1[2], v1[3]);
;                         *(u32x4*)(rowp + bj * 128) = w; } }
.LBB0_410:
	v_lshl_add_u32 v158, s1, 8, v164
	s_ashr_i32 s1, s0, 2
	s_lshl_b32 s0, s0, 8
	s_and_b32 s0, s0, 0x300
	v_or_b32_e32 v1, s0, v174
	v_mov_b32_e32 v160, 0xbfb8aa3b
	v_mov_b32_e32 v161, 0xbfb8aa3b
	s_cmp_eq_u32 s1, 2
	s_cbranch_scc1 .Levin_log
	s_cmp_gt_i32 s1, 2
	s_cselect_b32 s0, 1, 0
	s_sub_i32 s0, s1, s0
	v_readlane_b32 s2, v254, 42
	v_readlane_b32 s3, v254, 43
	s_lshl_b32 s0, s0, 25
	v_lshlrev_b32_e32 v159, 11, v158
	s_add_u32 s2, s2, s0
	s_addc_u32 s3, s3, 0
	v_lshl_add_u32 v159, v1, 1, v159
	v_mov_b32_e32 v162, 0x3db504f3
	v_mov_b32_e32 v163, 0x3db504f3
	s_cmp_eq_u32 s1, 1
	s_cbranch_scc1 .Levin_qs
	s_cmp_eq_u32 s1, 4
	s_cbranch_scc1 .Levin_gs
	v_cvt_pk_bf16_f32 v138, v126, v127
	v_cvt_pk_bf16_f32 v139, v128, v129
	v_cvt_pk_bf16_f32 v140, v122, v123
	v_cvt_pk_bf16_f32 v141, v124, v125
	global_store_dwordx4 v159, v[138:141], s[2:3]
	v_cvt_pk_bf16_f32 v142, v118, v119
	v_cvt_pk_bf16_f32 v143, v120, v121
	v_cvt_pk_bf16_f32 v144, v114, v115
	v_cvt_pk_bf16_f32 v145, v116, v117
	global_store_dwordx4 v159, v[142:145], s[2:3] offset:256
	v_add_u32_e32 v159, 0x8000, v159
	v_cvt_pk_bf16_f32 v138, v110, v111
	v_cvt_pk_bf16_f32 v139, v112, v113
	v_cvt_pk_bf16_f32 v140, v106, v107
	v_cvt_pk_bf16_f32 v141, v108, v109
	global_store_dwordx4 v159, v[138:141], s[2:3]
	v_cvt_pk_bf16_f32 v142, v102, v103
	v_cvt_pk_bf16_f32 v143, v104, v105
	v_cvt_pk_bf16_f32 v144, v98, v99
	v_cvt_pk_bf16_f32 v145, v100, v101
	global_store_dwordx4 v159, v[142:145], s[2:3] offset:256
	v_add_u32_e32 v159, 0x8000, v159
	v_cvt_pk_bf16_f32 v138, v94, v95
	v_cvt_pk_bf16_f32 v139, v96, v97
	v_cvt_pk_bf16_f32 v140, v90, v91
	v_cvt_pk_bf16_f32 v141, v92, v93
	global_store_dwordx4 v159, v[138:141], s[2:3]
	v_cvt_pk_bf16_f32 v142, v86, v87
	v_cvt_pk_bf16_f32 v143, v88, v89
	v_cvt_pk_bf16_f32 v144, v82, v83
	v_cvt_pk_bf16_f32 v145, v84, v85
	global_store_dwordx4 v159, v[142:145], s[2:3] offset:256
	v_add_u32_e32 v159, 0x8000, v159
	v_cvt_pk_bf16_f32 v138, v78, v79
	v_cvt_pk_bf16_f32 v139, v80, v81
	v_cvt_pk_bf16_f32 v140, v74, v75
	v_cvt_pk_bf16_f32 v141, v76, v77
	global_store_dwordx4 v159, v[138:141], s[2:3]
	v_cvt_pk_bf16_f32 v142, v70, v71
	v_cvt_pk_bf16_f32 v143, v72, v73
	v_cvt_pk_bf16_f32 v144, v66, v67
	v_cvt_pk_bf16_f32 v145, v68, v69
	global_store_dwordx4 v159, v[142:145], s[2:3] offset:256
	v_add_u32_e32 v159, 0x28000, v159
	v_cvt_pk_bf16_f32 v138, v62, v63
	v_cvt_pk_bf16_f32 v139, v64, v65
	v_cvt_pk_bf16_f32 v140, v58, v59
	v_cvt_pk_bf16_f32 v141, v60, v61
	global_store_dwordx4 v159, v[138:141], s[2:3]
	v_cvt_pk_bf16_f32 v142, v54, v55
	v_cvt_pk_bf16_f32 v143, v56, v57
	v_cvt_pk_bf16_f32 v144, v50, v51
	v_cvt_pk_bf16_f32 v145, v52, v53
	global_store_dwordx4 v159, v[142:145], s[2:3] offset:256
	v_add_u32_e32 v159, 0x8000, v159
	v_cvt_pk_bf16_f32 v138, v46, v47
	v_cvt_pk_bf16_f32 v139, v48, v49
	v_cvt_pk_bf16_f32 v140, v42, v43
	v_cvt_pk_bf16_f32 v141, v44, v45
	global_store_dwordx4 v159, v[138:141], s[2:3]
	v_cvt_pk_bf16_f32 v142, v38, v39
	v_cvt_pk_bf16_f32 v143, v40, v41
	v_cvt_pk_bf16_f32 v144, v34, v35
	v_cvt_pk_bf16_f32 v145, v36, v37
	global_store_dwordx4 v159, v[142:145], s[2:3] offset:256
	v_add_u32_e32 v159, 0x8000, v159
	v_cvt_pk_bf16_f32 v138, v30, v31
	v_cvt_pk_bf16_f32 v139, v32, v33
	v_cvt_pk_bf16_f32 v140, v26, v27
	v_cvt_pk_bf16_f32 v141, v28, v29
	global_store_dwordx4 v159, v[138:141], s[2:3]
	v_cvt_pk_bf16_f32 v142, v22, v23
	v_cvt_pk_bf16_f32 v143, v24, v25
	v_cvt_pk_bf16_f32 v144, v18, v19
	v_cvt_pk_bf16_f32 v145, v20, v21
	global_store_dwordx4 v159, v[142:145], s[2:3] offset:256
	v_add_u32_e32 v159, 0x8000, v159
	v_cvt_pk_bf16_f32 v138, v14, v15
	v_cvt_pk_bf16_f32 v139, v16, v17
	v_cvt_pk_bf16_f32 v140, v10, v11
	v_cvt_pk_bf16_f32 v141, v12, v13
	global_store_dwordx4 v159, v[138:141], s[2:3]
	v_cvt_pk_bf16_f32 v142, v6, v7
	v_cvt_pk_bf16_f32 v143, v8, v9
	v_cvt_pk_bf16_f32 v144, v2, v3
	v_cvt_pk_bf16_f32 v145, v4, v5
	global_store_dwordx4 v159, v[142:145], s[2:3] offset:256
	s_branch .Levin_done
.Levin_qs:
	v_pk_mul_f32 v[130:131], v[126:127], v[160:161]
	v_pk_mul_f32 v[132:133], v[128:129], v[160:161]
	v_pk_mul_f32 v[134:135], v[122:123], v[160:161]
	v_pk_mul_f32 v[136:137], v[124:125], v[160:161]
	v_exp_f32_e32 v130, v130
	v_exp_f32_e32 v131, v131
	v_exp_f32_e32 v132, v132
	v_exp_f32_e32 v133, v133
	v_exp_f32_e32 v134, v134
	v_exp_f32_e32 v135, v135
	v_exp_f32_e32 v136, v136
	v_exp_f32_e32 v137, v137
	v_pk_add_f32 v[130:131], v[130:131], 1.0 op_sel_hi:[1,0]
	v_pk_add_f32 v[132:133], v[132:133], 1.0 op_sel_hi:[1,0]
	v_pk_add_f32 v[134:135], v[134:135], 1.0 op_sel_hi:[1,0]
	v_pk_add_f32 v[136:137], v[136:137], 1.0 op_sel_hi:[1,0]
	v_rcp_f32_e32 v130, v130
	v_rcp_f32_e32 v131, v131
	v_rcp_f32_e32 v132, v132
	v_rcp_f32_e32 v133, v133
	v_rcp_f32_e32 v134, v134
	v_rcp_f32_e32 v135, v135
	v_rcp_f32_e32 v136, v136
	v_rcp_f32_e32 v137, v137
	v_pk_mul_f32 v[130:131], v[130:131], v[126:127]
	v_pk_mul_f32 v[132:133], v[132:133], v[128:129]
	v_pk_mul_f32 v[134:135], v[134:135], v[122:123]
	v_pk_mul_f32 v[136:137], v[136:137], v[124:125]
	v_pk_mul_f32 v[130:131], v[130:131], v[162:163]
	v_pk_mul_f32 v[132:133], v[132:133], v[162:163]
	v_pk_mul_f32 v[134:135], v[134:135], v[162:163]
	v_pk_mul_f32 v[136:137], v[136:137], v[162:163]
	v_cvt_pk_bf16_f32 v138, v130, v131
	v_cvt_pk_bf16_f32 v139, v132, v133
	v_cvt_pk_bf16_f32 v140, v134, v135
	v_cvt_pk_bf16_f32 v141, v136, v137
	global_store_dwordx4 v159, v[138:141], s[2:3]
	v_pk_mul_f32 v[130:131], v[118:119], v[160:161]
	v_pk_mul_f32 v[132:133], v[120:121], v[160:161]
	v_pk_mul_f32 v[134:135], v[114:115], v[160:161]
	v_pk_mul_f32 v[136:137], v[116:117], v[160:161]
	v_exp_f32_e32 v130, v130
	v_exp_f32_e32 v131, v131
; __device__ __forceinline__ unsigned cvt_pk_bf16(float lo, float hi) { f32x2 v = {lo, hi}; bf16x2_t b = __builtin_convertvector(v, bf16x2_t); return __builtin_bit_cast(unsigned, b); }
; __device__ __forceinline__ float siluf(float v) { return v / (1.f + __expf(-v)); }
; template <int MODE> __device__ __forceinline__ void gemm_epilogue(f32x4 (&acc)[2][2][4][2], const GD& g, const pg8::Unit& u, int wr, int wc, int fr, int fq, LAS unsigned char* lds, const float (&rsv)[2][4]) {
;     ...
;                     for (int bj = 0; bj < 2; ++bj) { f32x4 v0 = acc[ai][bj][m][0], v1 = acc[ai][bj][m][1];
;                         if (sel == 1) {
; #pragma unroll
;                             for (int j = 0; j < 4; ++j) { v0[j] = siluf(v0[j]) * 0.08838834764831845f; v1[j] = siluf(v1[j]) * 0.08838834764831845f; } }
;                         if (sel == 4) {
; #pragma unroll
;                             for (int j = 0; j < 4; ++j) { v0[j] = siluf(v0[j]); v1[j] = siluf(v1[j]); } }
;                         u32x4 w; w.x = cvt_pk_bf16(v0[0], v0[1]); w.y = cvt_pk_bf16(v0[2], v0[3]); w.z = cvt_pk_bf16(v1[0], v1[1]); w.w = cvt_pk_bf16(v1[2], v1[3]);
;                         *(u32x4*)(rowp + bj * 128) = w; } }
	v_exp_f32_e32 v132, v132
	v_exp_f32_e32 v133, v133
	v_exp_f32_e32 v134, v134
	v_exp_f32_e32 v135, v135
	v_exp_f32_e32 v136, v136
	v_exp_f32_e32 v137, v137
	v_pk_add_f32 v[130:131], v[130:131], 1.0 op_sel_hi:[1,0]
	v_pk_add_f32 v[132:133], v[132:133], 1.0 op_sel_hi:[1,0]
	v_pk_add_f32 v[134:135], v[134:135], 1.0 op_sel_hi:[1,0]
	v_pk_add_f32 v[136:137], v[136:137], 1.0 op_sel_hi:[1,0]
	v_rcp_f32_e32 v130, v130
	v_rcp_f32_e32 v131, v131
	v_rcp_f32_e32 v132, v132
	v_rcp_f32_e32 v133, v133
	v_rcp_f32_e32 v134, v134
	v_rcp_f32_e32 v135, v135
	v_rcp_f32_e32 v136, v136
	v_rcp_f32_e32 v137, v137
	v_pk_mul_f32 v[130:131], v[130:131], v[118:119]
	v_pk_mul_f32 v[132:133], v[132:133], v[120:121]
	v_pk_mul_f32 v[134:135], v[134:135], v[114:115]
	v_pk_mul_f32 v[136:137], v[136:137], v[116:117]
	v_pk_mul_f32 v[130:131], v[130:131], v[162:163]
	v_pk_mul_f32 v[132:133], v[132:133], v[162:163]
	v_pk_mul_f32 v[134:135], v[134:135], v[162:163]
	v_pk_mul_f32 v[136:137], v[136:137], v[162:163]
	v_cvt_pk_bf16_f32 v138, v130, v131
	v_cvt_pk_bf16_f32 v139, v132, v133
	v_cvt_pk_bf16_f32 v140, v134, v135
	v_cvt_pk_bf16_f32 v141, v136, v137
	global_store_dwordx4 v159, v[138:141], s[2:3] offset:256
	v_add_u32_e32 v159, 0x8000, v159
	v_pk_mul_f32 v[130:131], v[110:111], v[160:161]
	v_pk_mul_f32 v[132:133], v[112:113], v[160:161]
	v_pk_mul_f32 v[134:135], v[106:107], v[160:161]
	v_pk_mul_f32 v[136:137], v[108:109], v[160:161]
	v_exp_f32_e32 v130, v130
	v_exp_f32_e32 v131, v131
	v_exp_f32_e32 v132, v132
	v_exp_f32_e32 v133, v133
	v_exp_f32_e32 v134, v134
	v_exp_f32_e32 v135, v135
	v_exp_f32_e32 v136, v136
	v_exp_f32_e32 v137, v137
	v_pk_add_f32 v[130:131], v[130:131], 1.0 op_sel_hi:[1,0]
	v_pk_add_f32 v[132:133], v[132:133], 1.0 op_sel_hi:[1,0]
	v_pk_add_f32 v[134:135], v[134:135], 1.0 op_sel_hi:[1,0]
	v_pk_add_f32 v[136:137], v[136:137], 1.0 op_sel_hi:[1,0]
	v_rcp_f32_e32 v130, v130
	v_rcp_f32_e32 v131, v131
	v_rcp_f32_e32 v132, v132
	v_rcp_f32_e32 v133, v133
	v_rcp_f32_e32 v134, v134
	v_rcp_f32_e32 v135, v135
	v_rcp_f32_e32 v136, v136
	v_rcp_f32_e32 v137, v137
	v_pk_mul_f32 v[130:131], v[130:131], v[110:111]
	v_pk_mul_f32 v[132:133], v[132:133], v[112:113]
	v_pk_mul_f32 v[134:135], v[134:135], v[106:107]
	v_pk_mul_f32 v[136:137], v[136:137], v[108:109]
	v_pk_mul_f32 v[130:131], v[130:131], v[162:163]
	v_pk_mul_f32 v[132:133], v[132:133], v[162:163]
	v_pk_mul_f32 v[134:135], v[134:135], v[162:163]
	v_pk_mul_f32 v[136:137], v[136:137], v[162:163]
	v_cvt_pk_bf16_f32 v138, v130, v131
	v_cvt_pk_bf16_f32 v139, v132, v133
	v_cvt_pk_bf16_f32 v140, v134, v135
	v_cvt_pk_bf16_f32 v141, v136, v137
	global_store_dwordx4 v159, v[138:141], s[2:3]
	v_pk_mul_f32 v[130:131], v[102:103], v[160:161]
	v_pk_mul_f32 v[132:133], v[104:105], v[160:161]
	v_pk_mul_f32 v[134:135], v[98:99], v[160:161]
	v_pk_mul_f32 v[136:137], v[100:101], v[160:161]
	v_exp_f32_e32 v130, v130
	v_exp_f32_e32 v131, v131
	v_exp_f32_e32 v132, v132
	v_exp_f32_e32 v133, v133
	v_exp_f32_e32 v134, v134
	v_exp_f32_e32 v135, v135
	v_exp_f32_e32 v136, v136
	v_exp_f32_e32 v137, v137
	v_pk_add_f32 v[130:131], v[130:131], 1.0 op_sel_hi:[1,0]
	v_pk_add_f32 v[132:133], v[132:133], 1.0 op_sel_hi:[1,0]
	v_pk_add_f32 v[134:135], v[134:135], 1.0 op_sel_hi:[1,0]
	v_pk_add_f32 v[136:137], v[136:137], 1.0 op_sel_hi:[1,0]
	v_rcp_f32_e32 v130, v130
	v_rcp_f32_e32 v131, v131
	v_rcp_f32_e32 v132, v132
	v_rcp_f32_e32 v133, v133
	v_rcp_f32_e32 v134, v134
	v_rcp_f32_e32 v135, v135
	v_rcp_f32_e32 v136, v136
	v_rcp_f32_e32 v137, v137
	v_pk_mul_f32 v[130:131], v[130:131], v[102:103]
	v_pk_mul_f32 v[132:133], v[132:133], v[104:105]
	v_pk_mul_f32 v[134:135], v[134:135], v[98:99]
	v_pk_mul_f32 v[136:137], v[136:137], v[100:101]
	v_pk_mul_f32 v[130:131], v[130:131], v[162:163]
	v_pk_mul_f32 v[132:133], v[132:133], v[162:163]
	v_pk_mul_f32 v[134:135], v[134:135], v[162:163]
	v_pk_mul_f32 v[136:137], v[136:137], v[162:163]
	v_cvt_pk_bf16_f32 v138, v130, v131
	v_cvt_pk_bf16_f32 v139, v132, v133
	v_cvt_pk_bf16_f32 v140, v134, v135
	v_cvt_pk_bf16_f32 v141, v136, v137
	global_store_dwordx4 v159, v[138:141], s[2:3] offset:256
	v_add_u32_e32 v159, 0x8000, v159
	v_pk_mul_f32 v[130:131], v[94:95], v[160:161]
	v_pk_mul_f32 v[132:133], v[96:97], v[160:161]
	v_pk_mul_f32 v[134:135], v[90:91], v[160:161]
	v_pk_mul_f32 v[136:137], v[92:93], v[160:161]
	v_exp_f32_e32 v130, v130
	v_exp_f32_e32 v131, v131
	v_exp_f32_e32 v132, v132
	v_exp_f32_e32 v133, v133
	v_exp_f32_e32 v134, v134
	v_exp_f32_e32 v135, v135
	v_exp_f32_e32 v136, v136
	v_exp_f32_e32 v137, v137
	v_pk_add_f32 v[130:131], v[130:131], 1.0 op_sel_hi:[1,0]
	v_pk_add_f32 v[132:133], v[132:133], 1.0 op_sel_hi:[1,0]
	v_pk_add_f32 v[134:135], v[134:135], 1.0 op_sel_hi:[1,0]
	v_pk_add_f32 v[136:137], v[136:137], 1.0 op_sel_hi:[1,0]
	v_rcp_f32_e32 v130, v130
	v_rcp_f32_e32 v131, v131
	v_rcp_f32_e32 v132, v132
	v_rcp_f32_e32 v133, v133
	v_rcp_f32_e32 v134, v134
	v_rcp_f32_e32 v135, v135
	v_rcp_f32_e32 v136, v136
	v_rcp_f32_e32 v137, v137
	v_pk_mul_f32 v[130:131], v[130:131], v[94:95]
	v_pk_mul_f32 v[132:133], v[132:133], v[96:97]
	v_pk_mul_f32 v[134:135], v[134:135], v[90:91]
	v_pk_mul_f32 v[136:137], v[136:137], v[92:93]
	v_pk_mul_f32 v[130:131], v[130:131], v[162:163]
	v_pk_mul_f32 v[132:133], v[132:133], v[162:163]
	v_pk_mul_f32 v[134:135], v[134:135], v[162:163]
	v_pk_mul_f32 v[136:137], v[136:137], v[162:163]
	v_cvt_pk_bf16_f32 v138, v130, v131
	v_cvt_pk_bf16_f32 v139, v132, v133
	v_cvt_pk_bf16_f32 v140, v134, v135
	v_cvt_pk_bf16_f32 v141, v136, v137
	global_store_dwordx4 v159, v[138:141], s[2:3]
	v_pk_mul_f32 v[130:131], v[86:87], v[160:161]
	v_pk_mul_f32 v[132:133], v[88:89], v[160:161]
; __device__ __forceinline__ unsigned cvt_pk_bf16(float lo, float hi) { f32x2 v = {lo, hi}; bf16x2_t b = __builtin_convertvector(v, bf16x2_t); return __builtin_bit_cast(unsigned, b); }
; __device__ __forceinline__ float siluf(float v) { return v / (1.f + __expf(-v)); }
; template <int MODE> __device__ __forceinline__ void gemm_epilogue(f32x4 (&acc)[2][2][4][2], const GD& g, const pg8::Unit& u, int wr, int wc, int fr, int fq, LAS unsigned char* lds, const float (&rsv)[2][4]) {
;     ...
;             for (int ai = 0; ai < 2; ++ai)
; #pragma unroll
;                 for (int m = 0; m < 4; ++m) { bf16_t* rowp = O + (size_t)(rt + ai * 128 + m * 16) * 1024 + col0;
; #pragma unroll
;                     for (int bj = 0; bj < 2; ++bj) { f32x4 v0 = acc[ai][bj][m][0], v1 = acc[ai][bj][m][1];
;                         if (sel == 1) {
; #pragma unroll
;                             for (int j = 0; j < 4; ++j) { v0[j] = siluf(v0[j]) * 0.08838834764831845f; v1[j] = siluf(v1[j]) * 0.08838834764831845f; } }
;                         if (sel == 4) {
; #pragma unroll
;                             for (int j = 0; j < 4; ++j) { v0[j] = siluf(v0[j]); v1[j] = siluf(v1[j]); } }
;                         u32x4 w; w.x = cvt_pk_bf16(v0[0], v0[1]); w.y = cvt_pk_bf16(v0[2], v0[3]); w.z = cvt_pk_bf16(v1[0], v1[1]); w.w = cvt_pk_bf16(v1[2], v1[3]);
;                         *(u32x4*)(rowp + bj * 128) = w; } }
	v_pk_mul_f32 v[134:135], v[82:83], v[160:161]
	v_pk_mul_f32 v[136:137], v[84:85], v[160:161]
	v_exp_f32_e32 v130, v130
	v_exp_f32_e32 v131, v131
	v_exp_f32_e32 v132, v132
	v_exp_f32_e32 v133, v133
	v_exp_f32_e32 v134, v134
	v_exp_f32_e32 v135, v135
	v_exp_f32_e32 v136, v136
	v_exp_f32_e32 v137, v137
	v_pk_add_f32 v[130:131], v[130:131], 1.0 op_sel_hi:[1,0]
	v_pk_add_f32 v[132:133], v[132:133], 1.0 op_sel_hi:[1,0]
	v_pk_add_f32 v[134:135], v[134:135], 1.0 op_sel_hi:[1,0]
	v_pk_add_f32 v[136:137], v[136:137], 1.0 op_sel_hi:[1,0]
	v_rcp_f32_e32 v130, v130
	v_rcp_f32_e32 v131, v131
	v_rcp_f32_e32 v132, v132
	v_rcp_f32_e32 v133, v133
	v_rcp_f32_e32 v134, v134
	v_rcp_f32_e32 v135, v135
	v_rcp_f32_e32 v136, v136
	v_rcp_f32_e32 v137, v137
	v_pk_mul_f32 v[130:131], v[130:131], v[86:87]
	v_pk_mul_f32 v[132:133], v[132:133], v[88:89]
	v_pk_mul_f32 v[134:135], v[134:135], v[82:83]
	v_pk_mul_f32 v[136:137], v[136:137], v[84:85]
	v_pk_mul_f32 v[130:131], v[130:131], v[162:163]
	v_pk_mul_f32 v[132:133], v[132:133], v[162:163]
	v_pk_mul_f32 v[134:135], v[134:135], v[162:163]
	v_pk_mul_f32 v[136:137], v[136:137], v[162:163]
	v_cvt_pk_bf16_f32 v138, v130, v131
	v_cvt_pk_bf16_f32 v139, v132, v133
	v_cvt_pk_bf16_f32 v140, v134, v135
	v_cvt_pk_bf16_f32 v141, v136, v137
	global_store_dwordx4 v159, v[138:141], s[2:3] offset:256
	v_add_u32_e32 v159, 0x8000, v159
	v_pk_mul_f32 v[130:131], v[78:79], v[160:161]
	v_pk_mul_f32 v[132:133], v[80:81], v[160:161]
	v_pk_mul_f32 v[134:135], v[74:75], v[160:161]
	v_pk_mul_f32 v[136:137], v[76:77], v[160:161]
	v_exp_f32_e32 v130, v130
	v_exp_f32_e32 v131, v131
	v_exp_f32_e32 v132, v132
	v_exp_f32_e32 v133, v133
	v_exp_f32_e32 v134, v134
	v_exp_f32_e32 v135, v135
	v_exp_f32_e32 v136, v136
	v_exp_f32_e32 v137, v137
	v_pk_add_f32 v[130:131], v[130:131], 1.0 op_sel_hi:[1,0]
	v_pk_add_f32 v[132:133], v[132:133], 1.0 op_sel_hi:[1,0]
	v_pk_add_f32 v[134:135], v[134:135], 1.0 op_sel_hi:[1,0]
	v_pk_add_f32 v[136:137], v[136:137], 1.0 op_sel_hi:[1,0]
	v_rcp_f32_e32 v130, v130
	v_rcp_f32_e32 v131, v131
	v_rcp_f32_e32 v132, v132
	v_rcp_f32_e32 v133, v133
	v_rcp_f32_e32 v134, v134
	v_rcp_f32_e32 v135, v135
	v_rcp_f32_e32 v136, v136
	v_rcp_f32_e32 v137, v137
	v_pk_mul_f32 v[130:131], v[130:131], v[78:79]
	v_pk_mul_f32 v[132:133], v[132:133], v[80:81]
	v_pk_mul_f32 v[134:135], v[134:135], v[74:75]
	v_pk_mul_f32 v[136:137], v[136:137], v[76:77]
	v_pk_mul_f32 v[130:131], v[130:131], v[162:163]
	v_pk_mul_f32 v[132:133], v[132:133], v[162:163]
	v_pk_mul_f32 v[134:135], v[134:135], v[162:163]
	v_pk_mul_f32 v[136:137], v[136:137], v[162:163]
	v_cvt_pk_bf16_f32 v138, v130, v131
	v_cvt_pk_bf16_f32 v139, v132, v133
	v_cvt_pk_bf16_f32 v140, v134, v135
	v_cvt_pk_bf16_f32 v141, v136, v137
	global_store_dwordx4 v159, v[138:141], s[2:3]
	v_pk_mul_f32 v[130:131], v[70:71], v[160:161]
	v_pk_mul_f32 v[132:133], v[72:73], v[160:161]
	v_pk_mul_f32 v[134:135], v[66:67], v[160:161]
	v_pk_mul_f32 v[136:137], v[68:69], v[160:161]
	v_exp_f32_e32 v130, v130
	v_exp_f32_e32 v131, v131
	v_exp_f32_e32 v132, v132
	v_exp_f32_e32 v133, v133
	v_exp_f32_e32 v134, v134
	v_exp_f32_e32 v135, v135
	v_exp_f32_e32 v136, v136
	v_exp_f32_e32 v137, v137
	v_pk_add_f32 v[130:131], v[130:131], 1.0 op_sel_hi:[1,0]
	v_pk_add_f32 v[132:133], v[132:133], 1.0 op_sel_hi:[1,0]
	v_pk_add_f32 v[134:135], v[134:135], 1.0 op_sel_hi:[1,0]
	v_pk_add_f32 v[136:137], v[136:137], 1.0 op_sel_hi:[1,0]
	v_rcp_f32_e32 v130, v130
	v_rcp_f32_e32 v131, v131
	v_rcp_f32_e32 v132, v132
	v_rcp_f32_e32 v133, v133
	v_rcp_f32_e32 v134, v134
	v_rcp_f32_e32 v135, v135
	v_rcp_f32_e32 v136, v136
	v_rcp_f32_e32 v137, v137
	v_pk_mul_f32 v[130:131], v[130:131], v[70:71]
	v_pk_mul_f32 v[132:133], v[132:133], v[72:73]
	v_pk_mul_f32 v[134:135], v[134:135], v[66:67]
	v_pk_mul_f32 v[136:137], v[136:137], v[68:69]
	v_pk_mul_f32 v[130:131], v[130:131], v[162:163]
	v_pk_mul_f32 v[132:133], v[132:133], v[162:163]
	v_pk_mul_f32 v[134:135], v[134:135], v[162:163]
	v_pk_mul_f32 v[136:137], v[136:137], v[162:163]
	v_cvt_pk_bf16_f32 v138, v130, v131
	v_cvt_pk_bf16_f32 v139, v132, v133
	v_cvt_pk_bf16_f32 v140, v134, v135
	v_cvt_pk_bf16_f32 v141, v136, v137
	global_store_dwordx4 v159, v[138:141], s[2:3] offset:256
	v_add_u32_e32 v159, 0x28000, v159
	v_pk_mul_f32 v[130:131], v[62:63], v[160:161]
	v_pk_mul_f32 v[132:133], v[64:65], v[160:161]
	v_pk_mul_f32 v[134:135], v[58:59], v[160:161]
	v_pk_mul_f32 v[136:137], v[60:61], v[160:161]
	v_exp_f32_e32 v130, v130
	v_exp_f32_e32 v131, v131
	v_exp_f32_e32 v132, v132
	v_exp_f32_e32 v133, v133
	v_exp_f32_e32 v134, v134
	v_exp_f32_e32 v135, v135
	v_exp_f32_e32 v136, v136
	v_exp_f32_e32 v137, v137
	v_pk_add_f32 v[130:131], v[130:131], 1.0 op_sel_hi:[1,0]
	v_pk_add_f32 v[132:133], v[132:133], 1.0 op_sel_hi:[1,0]
	v_pk_add_f32 v[134:135], v[134:135], 1.0 op_sel_hi:[1,0]
	v_pk_add_f32 v[136:137], v[136:137], 1.0 op_sel_hi:[1,0]
	v_rcp_f32_e32 v130, v130
	v_rcp_f32_e32 v131, v131
	v_rcp_f32_e32 v132, v132
	v_rcp_f32_e32 v133, v133
	v_rcp_f32_e32 v134, v134
	v_rcp_f32_e32 v135, v135
	v_rcp_f32_e32 v136, v136
	v_rcp_f32_e32 v137, v137
	v_pk_mul_f32 v[130:131], v[130:131], v[62:63]
	v_pk_mul_f32 v[132:133], v[132:133], v[64:65]
	v_pk_mul_f32 v[134:135], v[134:135], v[58:59]
	v_pk_mul_f32 v[136:137], v[136:137], v[60:61]
	v_pk_mul_f32 v[130:131], v[130:131], v[162:163]
	v_pk_mul_f32 v[132:133], v[132:133], v[162:163]
	v_pk_mul_f32 v[134:135], v[134:135], v[162:163]
	v_pk_mul_f32 v[136:137], v[136:137], v[162:163]
	v_cvt_pk_bf16_f32 v138, v130, v131
	v_cvt_pk_bf16_f32 v139, v132, v133
	v_cvt_pk_bf16_f32 v140, v134, v135
	v_cvt_pk_bf16_f32 v141, v136, v137
	global_store_dwordx4 v159, v[138:141], s[2:3]
; __device__ __forceinline__ unsigned cvt_pk_bf16(float lo, float hi) { f32x2 v = {lo, hi}; bf16x2_t b = __builtin_convertvector(v, bf16x2_t); return __builtin_bit_cast(unsigned, b); }
; __device__ __forceinline__ float siluf(float v) { return v / (1.f + __expf(-v)); }
; template <int MODE> __device__ __forceinline__ void gemm_epilogue(f32x4 (&acc)[2][2][4][2], const GD& g, const pg8::Unit& u, int wr, int wc, int fr, int fq, LAS unsigned char* lds, const float (&rsv)[2][4]) {
;     ...
;             for (int ai = 0; ai < 2; ++ai)
; #pragma unroll
;                 for (int m = 0; m < 4; ++m) { bf16_t* rowp = O + (size_t)(rt + ai * 128 + m * 16) * 1024 + col0;
; #pragma unroll
;                     for (int bj = 0; bj < 2; ++bj) { f32x4 v0 = acc[ai][bj][m][0], v1 = acc[ai][bj][m][1];
;                         if (sel == 1) {
; #pragma unroll
;                             for (int j = 0; j < 4; ++j) { v0[j] = siluf(v0[j]) * 0.08838834764831845f; v1[j] = siluf(v1[j]) * 0.08838834764831845f; } }
;                         if (sel == 4) {
; #pragma unroll
;                             for (int j = 0; j < 4; ++j) { v0[j] = siluf(v0[j]); v1[j] = siluf(v1[j]); } }
;                         u32x4 w; w.x = cvt_pk_bf16(v0[0], v0[1]); w.y = cvt_pk_bf16(v0[2], v0[3]); w.z = cvt_pk_bf16(v1[0], v1[1]); w.w = cvt_pk_bf16(v1[2], v1[3]);
;                         *(u32x4*)(rowp + bj * 128) = w; } }
	v_pk_mul_f32 v[130:131], v[54:55], v[160:161]
	v_pk_mul_f32 v[132:133], v[56:57], v[160:161]
	v_pk_mul_f32 v[134:135], v[50:51], v[160:161]
	v_pk_mul_f32 v[136:137], v[52:53], v[160:161]
	v_exp_f32_e32 v130, v130
	v_exp_f32_e32 v131, v131
	v_exp_f32_e32 v132, v132
	v_exp_f32_e32 v133, v133
	v_exp_f32_e32 v134, v134
	v_exp_f32_e32 v135, v135
	v_exp_f32_e32 v136, v136
	v_exp_f32_e32 v137, v137
	v_pk_add_f32 v[130:131], v[130:131], 1.0 op_sel_hi:[1,0]
	v_pk_add_f32 v[132:133], v[132:133], 1.0 op_sel_hi:[1,0]
	v_pk_add_f32 v[134:135], v[134:135], 1.0 op_sel_hi:[1,0]
	v_pk_add_f32 v[136:137], v[136:137], 1.0 op_sel_hi:[1,0]
	v_rcp_f32_e32 v130, v130
	v_rcp_f32_e32 v131, v131
	v_rcp_f32_e32 v132, v132
	v_rcp_f32_e32 v133, v133
	v_rcp_f32_e32 v134, v134
	v_rcp_f32_e32 v135, v135
	v_rcp_f32_e32 v136, v136
	v_rcp_f32_e32 v137, v137
	v_pk_mul_f32 v[130:131], v[130:131], v[54:55]
	v_pk_mul_f32 v[132:133], v[132:133], v[56:57]
	v_pk_mul_f32 v[134:135], v[134:135], v[50:51]
	v_pk_mul_f32 v[136:137], v[136:137], v[52:53]
	v_pk_mul_f32 v[130:131], v[130:131], v[162:163]
	v_pk_mul_f32 v[132:133], v[132:133], v[162:163]
	v_pk_mul_f32 v[134:135], v[134:135], v[162:163]
	v_pk_mul_f32 v[136:137], v[136:137], v[162:163]
	v_cvt_pk_bf16_f32 v138, v130, v131
	v_cvt_pk_bf16_f32 v139, v132, v133
	v_cvt_pk_bf16_f32 v140, v134, v135
	v_cvt_pk_bf16_f32 v141, v136, v137
	global_store_dwordx4 v159, v[138:141], s[2:3] offset:256
	v_add_u32_e32 v159, 0x8000, v159
	v_pk_mul_f32 v[130:131], v[46:47], v[160:161]
	v_pk_mul_f32 v[132:133], v[48:49], v[160:161]
	v_pk_mul_f32 v[134:135], v[42:43], v[160:161]
	v_pk_mul_f32 v[136:137], v[44:45], v[160:161]
	v_exp_f32_e32 v130, v130
	v_exp_f32_e32 v131, v131
	v_exp_f32_e32 v132, v132
	v_exp_f32_e32 v133, v133
	v_exp_f32_e32 v134, v134
	v_exp_f32_e32 v135, v135
	v_exp_f32_e32 v136, v136
	v_exp_f32_e32 v137, v137
	v_pk_add_f32 v[130:131], v[130:131], 1.0 op_sel_hi:[1,0]
	v_pk_add_f32 v[132:133], v[132:133], 1.0 op_sel_hi:[1,0]
	v_pk_add_f32 v[134:135], v[134:135], 1.0 op_sel_hi:[1,0]
	v_pk_add_f32 v[136:137], v[136:137], 1.0 op_sel_hi:[1,0]
	v_rcp_f32_e32 v130, v130
	v_rcp_f32_e32 v131, v131
	v_rcp_f32_e32 v132, v132
	v_rcp_f32_e32 v133, v133
	v_rcp_f32_e32 v134, v134
	v_rcp_f32_e32 v135, v135
	v_rcp_f32_e32 v136, v136
	v_rcp_f32_e32 v137, v137
	v_pk_mul_f32 v[130:131], v[130:131], v[46:47]
	v_pk_mul_f32 v[132:133], v[132:133], v[48:49]
	v_pk_mul_f32 v[134:135], v[134:135], v[42:43]
	v_pk_mul_f32 v[136:137], v[136:137], v[44:45]
	v_pk_mul_f32 v[130:131], v[130:131], v[162:163]
	v_pk_mul_f32 v[132:133], v[132:133], v[162:163]
	v_pk_mul_f32 v[134:135], v[134:135], v[162:163]
	v_pk_mul_f32 v[136:137], v[136:137], v[162:163]
	v_cvt_pk_bf16_f32 v138, v130, v131
	v_cvt_pk_bf16_f32 v139, v132, v133
	v_cvt_pk_bf16_f32 v140, v134, v135
	v_cvt_pk_bf16_f32 v141, v136, v137
	global_store_dwordx4 v159, v[138:141], s[2:3]
	v_pk_mul_f32 v[130:131], v[38:39], v[160:161]
	v_pk_mul_f32 v[132:133], v[40:41], v[160:161]
	v_pk_mul_f32 v[134:135], v[34:35], v[160:161]
	v_pk_mul_f32 v[136:137], v[36:37], v[160:161]
	v_exp_f32_e32 v130, v130
	v_exp_f32_e32 v131, v131
	v_exp_f32_e32 v132, v132
	v_exp_f32_e32 v133, v133
	v_exp_f32_e32 v134, v134
	v_exp_f32_e32 v135, v135
	v_exp_f32_e32 v136, v136
	v_exp_f32_e32 v137, v137
	v_pk_add_f32 v[130:131], v[130:131], 1.0 op_sel_hi:[1,0]
	v_pk_add_f32 v[132:133], v[132:133], 1.0 op_sel_hi:[1,0]
	v_pk_add_f32 v[134:135], v[134:135], 1.0 op_sel_hi:[1,0]
	v_pk_add_f32 v[136:137], v[136:137], 1.0 op_sel_hi:[1,0]
	v_rcp_f32_e32 v130, v130
	v_rcp_f32_e32 v131, v131
	v_rcp_f32_e32 v132, v132
	v_rcp_f32_e32 v133, v133
	v_rcp_f32_e32 v134, v134
	v_rcp_f32_e32 v135, v135
	v_rcp_f32_e32 v136, v136
	v_rcp_f32_e32 v137, v137
	v_pk_mul_f32 v[130:131], v[130:131], v[38:39]
	v_pk_mul_f32 v[132:133], v[132:133], v[40:41]
	v_pk_mul_f32 v[134:135], v[134:135], v[34:35]
	v_pk_mul_f32 v[136:137], v[136:137], v[36:37]
	v_pk_mul_f32 v[130:131], v[130:131], v[162:163]
	v_pk_mul_f32 v[132:133], v[132:133], v[162:163]
	v_pk_mul_f32 v[134:135], v[134:135], v[162:163]
	v_pk_mul_f32 v[136:137], v[136:137], v[162:163]
	v_cvt_pk_bf16_f32 v138, v130, v131
	v_cvt_pk_bf16_f32 v139, v132, v133
	v_cvt_pk_bf16_f32 v140, v134, v135
	v_cvt_pk_bf16_f32 v141, v136, v137
	global_store_dwordx4 v159, v[138:141], s[2:3] offset:256
	v_add_u32_e32 v159, 0x8000, v159
	v_pk_mul_f32 v[130:131], v[30:31], v[160:161]
	v_pk_mul_f32 v[132:133], v[32:33], v[160:161]
	v_pk_mul_f32 v[134:135], v[26:27], v[160:161]
	v_pk_mul_f32 v[136:137], v[28:29], v[160:161]
	v_exp_f32_e32 v130, v130
	v_exp_f32_e32 v131, v131
	v_exp_f32_e32 v132, v132
	v_exp_f32_e32 v133, v133
	v_exp_f32_e32 v134, v134
	v_exp_f32_e32 v135, v135
	v_exp_f32_e32 v136, v136
	v_exp_f32_e32 v137, v137
	v_pk_add_f32 v[130:131], v[130:131], 1.0 op_sel_hi:[1,0]
	v_pk_add_f32 v[132:133], v[132:133], 1.0 op_sel_hi:[1,0]
	v_pk_add_f32 v[134:135], v[134:135], 1.0 op_sel_hi:[1,0]
	v_pk_add_f32 v[136:137], v[136:137], 1.0 op_sel_hi:[1,0]
	v_rcp_f32_e32 v130, v130
	v_rcp_f32_e32 v131, v131
	v_rcp_f32_e32 v132, v132
	v_rcp_f32_e32 v133, v133
	v_rcp_f32_e32 v134, v134
	v_rcp_f32_e32 v135, v135
	v_rcp_f32_e32 v136, v136
	v_rcp_f32_e32 v137, v137
	v_pk_mul_f32 v[130:131], v[130:131], v[30:31]
	v_pk_mul_f32 v[132:133], v[132:133], v[32:33]
	v_pk_mul_f32 v[134:135], v[134:135], v[26:27]
	v_pk_mul_f32 v[136:137], v[136:137], v[28:29]
	v_pk_mul_f32 v[130:131], v[130:131], v[162:163]
	v_pk_mul_f32 v[132:133], v[132:133], v[162:163]
	v_pk_mul_f32 v[134:135], v[134:135], v[162:163]
	v_pk_mul_f32 v[136:137], v[136:137], v[162:163]
	v_cvt_pk_bf16_f32 v138, v130, v131
	v_cvt_pk_bf16_f32 v139, v132, v133
	v_cvt_pk_bf16_f32 v140, v134, v135
; __device__ __forceinline__ unsigned cvt_pk_bf16(float lo, float hi) { f32x2 v = {lo, hi}; bf16x2_t b = __builtin_convertvector(v, bf16x2_t); return __builtin_bit_cast(unsigned, b); }
; __device__ __forceinline__ float siluf(float v) { return v / (1.f + __expf(-v)); }
; template <int MODE> __device__ __forceinline__ void gemm_epilogue(f32x4 (&acc)[2][2][4][2], const GD& g, const pg8::Unit& u, int wr, int wc, int fr, int fq, LAS unsigned char* lds, const float (&rsv)[2][4]) {
;     ...
;             for (int ai = 0; ai < 2; ++ai)
; #pragma unroll
;                 for (int m = 0; m < 4; ++m) { bf16_t* rowp = O + (size_t)(rt + ai * 128 + m * 16) * 1024 + col0;
; #pragma unroll
;                     for (int bj = 0; bj < 2; ++bj) { f32x4 v0 = acc[ai][bj][m][0], v1 = acc[ai][bj][m][1];
;                         if (sel == 1) {
; #pragma unroll
;                             for (int j = 0; j < 4; ++j) { v0[j] = siluf(v0[j]) * 0.08838834764831845f; v1[j] = siluf(v1[j]) * 0.08838834764831845f; } }
;                         if (sel == 4) {
; #pragma unroll
;                             for (int j = 0; j < 4; ++j) { v0[j] = siluf(v0[j]); v1[j] = siluf(v1[j]); } }
;                         u32x4 w; w.x = cvt_pk_bf16(v0[0], v0[1]); w.y = cvt_pk_bf16(v0[2], v0[3]); w.z = cvt_pk_bf16(v1[0], v1[1]); w.w = cvt_pk_bf16(v1[2], v1[3]);
;                         *(u32x4*)(rowp + bj * 128) = w; } }
	v_cvt_pk_bf16_f32 v141, v136, v137
	global_store_dwordx4 v159, v[138:141], s[2:3]
	v_pk_mul_f32 v[130:131], v[22:23], v[160:161]
	v_pk_mul_f32 v[132:133], v[24:25], v[160:161]
	v_pk_mul_f32 v[134:135], v[18:19], v[160:161]
	v_pk_mul_f32 v[136:137], v[20:21], v[160:161]
	v_exp_f32_e32 v130, v130
	v_exp_f32_e32 v131, v131
	v_exp_f32_e32 v132, v132
	v_exp_f32_e32 v133, v133
	v_exp_f32_e32 v134, v134
	v_exp_f32_e32 v135, v135
	v_exp_f32_e32 v136, v136
	v_exp_f32_e32 v137, v137
	v_pk_add_f32 v[130:131], v[130:131], 1.0 op_sel_hi:[1,0]
	v_pk_add_f32 v[132:133], v[132:133], 1.0 op_sel_hi:[1,0]
	v_pk_add_f32 v[134:135], v[134:135], 1.0 op_sel_hi:[1,0]
	v_pk_add_f32 v[136:137], v[136:137], 1.0 op_sel_hi:[1,0]
	v_rcp_f32_e32 v130, v130
	v_rcp_f32_e32 v131, v131
	v_rcp_f32_e32 v132, v132
	v_rcp_f32_e32 v133, v133
	v_rcp_f32_e32 v134, v134
	v_rcp_f32_e32 v135, v135
	v_rcp_f32_e32 v136, v136
	v_rcp_f32_e32 v137, v137
	v_pk_mul_f32 v[130:131], v[130:131], v[22:23]
	v_pk_mul_f32 v[132:133], v[132:133], v[24:25]
	v_pk_mul_f32 v[134:135], v[134:135], v[18:19]
	v_pk_mul_f32 v[136:137], v[136:137], v[20:21]
	v_pk_mul_f32 v[130:131], v[130:131], v[162:163]
	v_pk_mul_f32 v[132:133], v[132:133], v[162:163]
	v_pk_mul_f32 v[134:135], v[134:135], v[162:163]
	v_pk_mul_f32 v[136:137], v[136:137], v[162:163]
	v_cvt_pk_bf16_f32 v138, v130, v131
	v_cvt_pk_bf16_f32 v139, v132, v133
	v_cvt_pk_bf16_f32 v140, v134, v135
	v_cvt_pk_bf16_f32 v141, v136, v137
	global_store_dwordx4 v159, v[138:141], s[2:3] offset:256
	v_add_u32_e32 v159, 0x8000, v159
	v_pk_mul_f32 v[130:131], v[14:15], v[160:161]
	v_pk_mul_f32 v[132:133], v[16:17], v[160:161]
	v_pk_mul_f32 v[134:135], v[10:11], v[160:161]
	v_pk_mul_f32 v[136:137], v[12:13], v[160:161]
	v_exp_f32_e32 v130, v130
	v_exp_f32_e32 v131, v131
	v_exp_f32_e32 v132, v132
	v_exp_f32_e32 v133, v133
	v_exp_f32_e32 v134, v134
	v_exp_f32_e32 v135, v135
	v_exp_f32_e32 v136, v136
	v_exp_f32_e32 v137, v137
	v_pk_add_f32 v[130:131], v[130:131], 1.0 op_sel_hi:[1,0]
	v_pk_add_f32 v[132:133], v[132:133], 1.0 op_sel_hi:[1,0]
	v_pk_add_f32 v[134:135], v[134:135], 1.0 op_sel_hi:[1,0]
	v_pk_add_f32 v[136:137], v[136:137], 1.0 op_sel_hi:[1,0]
	v_rcp_f32_e32 v130, v130
	v_rcp_f32_e32 v131, v131
	v_rcp_f32_e32 v132, v132
	v_rcp_f32_e32 v133, v133
	v_rcp_f32_e32 v134, v134
	v_rcp_f32_e32 v135, v135
	v_rcp_f32_e32 v136, v136
	v_rcp_f32_e32 v137, v137
	v_pk_mul_f32 v[130:131], v[130:131], v[14:15]
	v_pk_mul_f32 v[132:133], v[132:133], v[16:17]
	v_pk_mul_f32 v[134:135], v[134:135], v[10:11]
	v_pk_mul_f32 v[136:137], v[136:137], v[12:13]
	v_pk_mul_f32 v[130:131], v[130:131], v[162:163]
	v_pk_mul_f32 v[132:133], v[132:133], v[162:163]
	v_pk_mul_f32 v[134:135], v[134:135], v[162:163]
	v_pk_mul_f32 v[136:137], v[136:137], v[162:163]
	v_cvt_pk_bf16_f32 v138, v130, v131
	v_cvt_pk_bf16_f32 v139, v132, v133
	v_cvt_pk_bf16_f32 v140, v134, v135
	v_cvt_pk_bf16_f32 v141, v136, v137
	global_store_dwordx4 v159, v[138:141], s[2:3]
	v_pk_mul_f32 v[130:131], v[6:7], v[160:161]
	v_pk_mul_f32 v[132:133], v[8:9], v[160:161]
	v_pk_mul_f32 v[134:135], v[2:3], v[160:161]
	v_pk_mul_f32 v[136:137], v[4:5], v[160:161]
	v_exp_f32_e32 v130, v130
	v_exp_f32_e32 v131, v131
	v_exp_f32_e32 v132, v132
	v_exp_f32_e32 v133, v133
	v_exp_f32_e32 v134, v134
	v_exp_f32_e32 v135, v135
	v_exp_f32_e32 v136, v136
	v_exp_f32_e32 v137, v137
	v_pk_add_f32 v[130:131], v[130:131], 1.0 op_sel_hi:[1,0]
	v_pk_add_f32 v[132:133], v[132:133], 1.0 op_sel_hi:[1,0]
	v_pk_add_f32 v[134:135], v[134:135], 1.0 op_sel_hi:[1,0]
	v_pk_add_f32 v[136:137], v[136:137], 1.0 op_sel_hi:[1,0]
	v_rcp_f32_e32 v130, v130
	v_rcp_f32_e32 v131, v131
	v_rcp_f32_e32 v132, v132
	v_rcp_f32_e32 v133, v133
	v_rcp_f32_e32 v134, v134
	v_rcp_f32_e32 v135, v135
	v_rcp_f32_e32 v136, v136
	v_rcp_f32_e32 v137, v137
	v_pk_mul_f32 v[130:131], v[130:131], v[6:7]
	v_pk_mul_f32 v[132:133], v[132:133], v[8:9]
	v_pk_mul_f32 v[134:135], v[134:135], v[2:3]
	v_pk_mul_f32 v[136:137], v[136:137], v[4:5]
	v_pk_mul_f32 v[130:131], v[130:131], v[162:163]
	v_pk_mul_f32 v[132:133], v[132:133], v[162:163]
	v_pk_mul_f32 v[134:135], v[134:135], v[162:163]
	v_pk_mul_f32 v[136:137], v[136:137], v[162:163]
	v_cvt_pk_bf16_f32 v138, v130, v131
	v_cvt_pk_bf16_f32 v139, v132, v133
	v_cvt_pk_bf16_f32 v140, v134, v135
	v_cvt_pk_bf16_f32 v141, v136, v137
	global_store_dwordx4 v159, v[138:141], s[2:3] offset:256
	s_branch .Levin_done
; __device__ __forceinline__ unsigned cvt_pk_bf16(float lo, float hi) { f32x2 v = {lo, hi}; bf16x2_t b = __builtin_convertvector(v, bf16x2_t); return __builtin_bit_cast(unsigned, b); }
; __device__ __forceinline__ float siluf(float v) { return v / (1.f + __expf(-v)); }
; template <int MODE> __device__ __forceinline__ void gemm_epilogue(f32x4 (&acc)[2][2][4][2], const GD& g, const pg8::Unit& u, int wr, int wc, int fr, int fq, LAS unsigned char* lds, const float (&rsv)[2][4]) {
;     ...
;             for (int ai = 0; ai < 2; ++ai)
; #pragma unroll
;                 for (int m = 0; m < 4; ++m) { bf16_t* rowp = O + (size_t)(rt + ai * 128 + m * 16) * 1024 + col0;
; #pragma unroll
;                     for (int bj = 0; bj < 2; ++bj) { f32x4 v0 = acc[ai][bj][m][0], v1 = acc[ai][bj][m][1];
;                         if (sel == 1) {
; #pragma unroll
;                             for (int j = 0; j < 4; ++j) { v0[j] = siluf(v0[j]) * 0.08838834764831845f; v1[j] = siluf(v1[j]) * 0.08838834764831845f; } }
;                         if (sel == 4) {
; #pragma unroll
;                             for (int j = 0; j < 4; ++j) { v0[j] = siluf(v0[j]); v1[j] = siluf(v1[j]); } }
;                         u32x4 w; w.x = cvt_pk_bf16(v0[0], v0[1]); w.y = cvt_pk_bf16(v0[2], v0[3]); w.z = cvt_pk_bf16(v1[0], v1[1]); w.w = cvt_pk_bf16(v1[2], v1[3]);
;                         *(u32x4*)(rowp + bj * 128) = w; } }
.Levin_gs:
	v_pk_mul_f32 v[130:131], v[126:127], v[160:161]
	v_pk_mul_f32 v[132:133], v[128:129], v[160:161]
	v_pk_mul_f32 v[134:135], v[122:123], v[160:161]
	v_pk_mul_f32 v[136:137], v[124:125], v[160:161]
	v_exp_f32_e32 v130, v130
	v_exp_f32_e32 v131, v131
	v_exp_f32_e32 v132, v132
	v_exp_f32_e32 v133, v133
	v_exp_f32_e32 v134, v134
	v_exp_f32_e32 v135, v135
	v_exp_f32_e32 v136, v136
	v_exp_f32_e32 v137, v137
	v_pk_add_f32 v[130:131], v[130:131], 1.0 op_sel_hi:[1,0]
	v_pk_add_f32 v[132:133], v[132:133], 1.0 op_sel_hi:[1,0]
	v_pk_add_f32 v[134:135], v[134:135], 1.0 op_sel_hi:[1,0]
	v_pk_add_f32 v[136:137], v[136:137], 1.0 op_sel_hi:[1,0]
	v_rcp_f32_e32 v130, v130
	v_rcp_f32_e32 v131, v131
	v_rcp_f32_e32 v132, v132
	v_rcp_f32_e32 v133, v133
	v_rcp_f32_e32 v134, v134
	v_rcp_f32_e32 v135, v135
	v_rcp_f32_e32 v136, v136
	v_rcp_f32_e32 v137, v137
	v_pk_mul_f32 v[130:131], v[130:131], v[126:127]
	v_pk_mul_f32 v[132:133], v[132:133], v[128:129]
	v_pk_mul_f32 v[134:135], v[134:135], v[122:123]
	v_pk_mul_f32 v[136:137], v[136:137], v[124:125]
	v_cvt_pk_bf16_f32 v138, v130, v131
	v_cvt_pk_bf16_f32 v139, v132, v133
	v_cvt_pk_bf16_f32 v140, v134, v135
	v_cvt_pk_bf16_f32 v141, v136, v137
	global_store_dwordx4 v159, v[138:141], s[2:3]
	v_pk_mul_f32 v[130:131], v[118:119], v[160:161]
	v_pk_mul_f32 v[132:133], v[120:121], v[160:161]
	v_pk_mul_f32 v[134:135], v[114:115], v[160:161]
	v_pk_mul_f32 v[136:137], v[116:117], v[160:161]
	v_exp_f32_e32 v130, v130
	v_exp_f32_e32 v131, v131
	v_exp_f32_e32 v132, v132
	v_exp_f32_e32 v133, v133
	v_exp_f32_e32 v134, v134
	v_exp_f32_e32 v135, v135
	v_exp_f32_e32 v136, v136
	v_exp_f32_e32 v137, v137
	v_pk_add_f32 v[130:131], v[130:131], 1.0 op_sel_hi:[1,0]
	v_pk_add_f32 v[132:133], v[132:133], 1.0 op_sel_hi:[1,0]
	v_pk_add_f32 v[134:135], v[134:135], 1.0 op_sel_hi:[1,0]
	v_pk_add_f32 v[136:137], v[136:137], 1.0 op_sel_hi:[1,0]
	v_rcp_f32_e32 v130, v130
	v_rcp_f32_e32 v131, v131
	v_rcp_f32_e32 v132, v132
	v_rcp_f32_e32 v133, v133
	v_rcp_f32_e32 v134, v134
	v_rcp_f32_e32 v135, v135
	v_rcp_f32_e32 v136, v136
	v_rcp_f32_e32 v137, v137
	v_pk_mul_f32 v[130:131], v[130:131], v[118:119]
	v_pk_mul_f32 v[132:133], v[132:133], v[120:121]
	v_pk_mul_f32 v[134:135], v[134:135], v[114:115]
	v_pk_mul_f32 v[136:137], v[136:137], v[116:117]
	v_cvt_pk_bf16_f32 v138, v130, v131
	v_cvt_pk_bf16_f32 v139, v132, v133
	v_cvt_pk_bf16_f32 v140, v134, v135
	v_cvt_pk_bf16_f32 v141, v136, v137
	global_store_dwordx4 v159, v[138:141], s[2:3] offset:256
	v_add_u32_e32 v159, 0x8000, v159
	v_pk_mul_f32 v[130:131], v[110:111], v[160:161]
	v_pk_mul_f32 v[132:133], v[112:113], v[160:161]
	v_pk_mul_f32 v[134:135], v[106:107], v[160:161]
	v_pk_mul_f32 v[136:137], v[108:109], v[160:161]
	v_exp_f32_e32 v130, v130
	v_exp_f32_e32 v131, v131
	v_exp_f32_e32 v132, v132
	v_exp_f32_e32 v133, v133
	v_exp_f32_e32 v134, v134
	v_exp_f32_e32 v135, v135
	v_exp_f32_e32 v136, v136
	v_exp_f32_e32 v137, v137
	v_pk_add_f32 v[130:131], v[130:131], 1.0 op_sel_hi:[1,0]
	v_pk_add_f32 v[132:133], v[132:133], 1.0 op_sel_hi:[1,0]
	v_pk_add_f32 v[134:135], v[134:135], 1.0 op_sel_hi:[1,0]
	v_pk_add_f32 v[136:137], v[136:137], 1.0 op_sel_hi:[1,0]
	v_rcp_f32_e32 v130, v130
	v_rcp_f32_e32 v131, v131
	v_rcp_f32_e32 v132, v132
	v_rcp_f32_e32 v133, v133
	v_rcp_f32_e32 v134, v134
	v_rcp_f32_e32 v135, v135
	v_rcp_f32_e32 v136, v136
	v_rcp_f32_e32 v137, v137
	v_pk_mul_f32 v[130:131], v[130:131], v[110:111]
	v_pk_mul_f32 v[132:133], v[132:133], v[112:113]
	v_pk_mul_f32 v[134:135], v[134:135], v[106:107]
	v_pk_mul_f32 v[136:137], v[136:137], v[108:109]
	v_cvt_pk_bf16_f32 v138, v130, v131
	v_cvt_pk_bf16_f32 v139, v132, v133
	v_cvt_pk_bf16_f32 v140, v134, v135
	v_cvt_pk_bf16_f32 v141, v136, v137
	global_store_dwordx4 v159, v[138:141], s[2:3]
	v_pk_mul_f32 v[130:131], v[102:103], v[160:161]
	v_pk_mul_f32 v[132:133], v[104:105], v[160:161]
	v_pk_mul_f32 v[134:135], v[98:99], v[160:161]
	v_pk_mul_f32 v[136:137], v[100:101], v[160:161]
	v_exp_f32_e32 v130, v130
	v_exp_f32_e32 v131, v131
	v_exp_f32_e32 v132, v132
	v_exp_f32_e32 v133, v133
	v_exp_f32_e32 v134, v134
	v_exp_f32_e32 v135, v135
	v_exp_f32_e32 v136, v136
	v_exp_f32_e32 v137, v137
	v_pk_add_f32 v[130:131], v[130:131], 1.0 op_sel_hi:[1,0]
	v_pk_add_f32 v[132:133], v[132:133], 1.0 op_sel_hi:[1,0]
	v_pk_add_f32 v[134:135], v[134:135], 1.0 op_sel_hi:[1,0]
	v_pk_add_f32 v[136:137], v[136:137], 1.0 op_sel_hi:[1,0]
	v_rcp_f32_e32 v130, v130
	v_rcp_f32_e32 v131, v131
	v_rcp_f32_e32 v132, v132
	v_rcp_f32_e32 v133, v133
	v_rcp_f32_e32 v134, v134
	v_rcp_f32_e32 v135, v135
	v_rcp_f32_e32 v136, v136
	v_rcp_f32_e32 v137, v137
	v_pk_mul_f32 v[130:131], v[130:131], v[102:103]
	v_pk_mul_f32 v[132:133], v[132:133], v[104:105]
	v_pk_mul_f32 v[134:135], v[134:135], v[98:99]
	v_pk_mul_f32 v[136:137], v[136:137], v[100:101]
	v_cvt_pk_bf16_f32 v138, v130, v131
	v_cvt_pk_bf16_f32 v139, v132, v133
	v_cvt_pk_bf16_f32 v140, v134, v135
	v_cvt_pk_bf16_f32 v141, v136, v137
	global_store_dwordx4 v159, v[138:141], s[2:3] offset:256
	v_add_u32_e32 v159, 0x8000, v159
	v_pk_mul_f32 v[130:131], v[94:95], v[160:161]
	v_pk_mul_f32 v[132:133], v[96:97], v[160:161]
	v_pk_mul_f32 v[134:135], v[90:91], v[160:161]
	v_pk_mul_f32 v[136:137], v[92:93], v[160:161]
	v_exp_f32_e32 v130, v130
	v_exp_f32_e32 v131, v131
	v_exp_f32_e32 v132, v132
	v_exp_f32_e32 v133, v133
	v_exp_f32_e32 v134, v134
	v_exp_f32_e32 v135, v135
	v_exp_f32_e32 v136, v136
	v_exp_f32_e32 v137, v137
	v_pk_add_f32 v[130:131], v[130:131], 1.0 op_sel_hi:[1,0]
	v_pk_add_f32 v[132:133], v[132:133], 1.0 op_sel_hi:[1,0]
	v_pk_add_f32 v[134:135], v[134:135], 1.0 op_sel_hi:[1,0]
	v_pk_add_f32 v[136:137], v[136:137], 1.0 op_sel_hi:[1,0]
; __device__ __forceinline__ unsigned cvt_pk_bf16(float lo, float hi) { f32x2 v = {lo, hi}; bf16x2_t b = __builtin_convertvector(v, bf16x2_t); return __builtin_bit_cast(unsigned, b); }
; __device__ __forceinline__ float siluf(float v) { return v / (1.f + __expf(-v)); }
; template <int MODE> __device__ __forceinline__ void gemm_epilogue(f32x4 (&acc)[2][2][4][2], const GD& g, const pg8::Unit& u, int wr, int wc, int fr, int fq, LAS unsigned char* lds, const float (&rsv)[2][4]) {
;     ...
;             for (int ai = 0; ai < 2; ++ai)
; #pragma unroll
;                 for (int m = 0; m < 4; ++m) { bf16_t* rowp = O + (size_t)(rt + ai * 128 + m * 16) * 1024 + col0;
; #pragma unroll
;                     for (int bj = 0; bj < 2; ++bj) { f32x4 v0 = acc[ai][bj][m][0], v1 = acc[ai][bj][m][1];
;                         if (sel == 1) {
; #pragma unroll
;                             for (int j = 0; j < 4; ++j) { v0[j] = siluf(v0[j]) * 0.08838834764831845f; v1[j] = siluf(v1[j]) * 0.08838834764831845f; } }
;                         if (sel == 4) {
; #pragma unroll
;                             for (int j = 0; j < 4; ++j) { v0[j] = siluf(v0[j]); v1[j] = siluf(v1[j]); } }
;                         u32x4 w; w.x = cvt_pk_bf16(v0[0], v0[1]); w.y = cvt_pk_bf16(v0[2], v0[3]); w.z = cvt_pk_bf16(v1[0], v1[1]); w.w = cvt_pk_bf16(v1[2], v1[3]);
;                         *(u32x4*)(rowp + bj * 128) = w; } }
	v_rcp_f32_e32 v130, v130
	v_rcp_f32_e32 v131, v131
	v_rcp_f32_e32 v132, v132
	v_rcp_f32_e32 v133, v133
	v_rcp_f32_e32 v134, v134
	v_rcp_f32_e32 v135, v135
	v_rcp_f32_e32 v136, v136
	v_rcp_f32_e32 v137, v137
	v_pk_mul_f32 v[130:131], v[130:131], v[94:95]
	v_pk_mul_f32 v[132:133], v[132:133], v[96:97]
	v_pk_mul_f32 v[134:135], v[134:135], v[90:91]
	v_pk_mul_f32 v[136:137], v[136:137], v[92:93]
	v_cvt_pk_bf16_f32 v138, v130, v131
	v_cvt_pk_bf16_f32 v139, v132, v133
	v_cvt_pk_bf16_f32 v140, v134, v135
	v_cvt_pk_bf16_f32 v141, v136, v137
	global_store_dwordx4 v159, v[138:141], s[2:3]
	v_pk_mul_f32 v[130:131], v[86:87], v[160:161]
	v_pk_mul_f32 v[132:133], v[88:89], v[160:161]
	v_pk_mul_f32 v[134:135], v[82:83], v[160:161]
	v_pk_mul_f32 v[136:137], v[84:85], v[160:161]
	v_exp_f32_e32 v130, v130
	v_exp_f32_e32 v131, v131
	v_exp_f32_e32 v132, v132
	v_exp_f32_e32 v133, v133
	v_exp_f32_e32 v134, v134
	v_exp_f32_e32 v135, v135
	v_exp_f32_e32 v136, v136
	v_exp_f32_e32 v137, v137
	v_pk_add_f32 v[130:131], v[130:131], 1.0 op_sel_hi:[1,0]
	v_pk_add_f32 v[132:133], v[132:133], 1.0 op_sel_hi:[1,0]
	v_pk_add_f32 v[134:135], v[134:135], 1.0 op_sel_hi:[1,0]
	v_pk_add_f32 v[136:137], v[136:137], 1.0 op_sel_hi:[1,0]
	v_rcp_f32_e32 v130, v130
	v_rcp_f32_e32 v131, v131
	v_rcp_f32_e32 v132, v132
	v_rcp_f32_e32 v133, v133
	v_rcp_f32_e32 v134, v134
	v_rcp_f32_e32 v135, v135
	v_rcp_f32_e32 v136, v136
	v_rcp_f32_e32 v137, v137
	v_pk_mul_f32 v[130:131], v[130:131], v[86:87]
	v_pk_mul_f32 v[132:133], v[132:133], v[88:89]
	v_pk_mul_f32 v[134:135], v[134:135], v[82:83]
	v_pk_mul_f32 v[136:137], v[136:137], v[84:85]
	v_cvt_pk_bf16_f32 v138, v130, v131
	v_cvt_pk_bf16_f32 v139, v132, v133
	v_cvt_pk_bf16_f32 v140, v134, v135
	v_cvt_pk_bf16_f32 v141, v136, v137
	global_store_dwordx4 v159, v[138:141], s[2:3] offset:256
	v_add_u32_e32 v159, 0x8000, v159
	v_pk_mul_f32 v[130:131], v[78:79], v[160:161]
	v_pk_mul_f32 v[132:133], v[80:81], v[160:161]
	v_pk_mul_f32 v[134:135], v[74:75], v[160:161]
	v_pk_mul_f32 v[136:137], v[76:77], v[160:161]
	v_exp_f32_e32 v130, v130
	v_exp_f32_e32 v131, v131
	v_exp_f32_e32 v132, v132
	v_exp_f32_e32 v133, v133
	v_exp_f32_e32 v134, v134
	v_exp_f32_e32 v135, v135
	v_exp_f32_e32 v136, v136
	v_exp_f32_e32 v137, v137
	v_pk_add_f32 v[130:131], v[130:131], 1.0 op_sel_hi:[1,0]
	v_pk_add_f32 v[132:133], v[132:133], 1.0 op_sel_hi:[1,0]
	v_pk_add_f32 v[134:135], v[134:135], 1.0 op_sel_hi:[1,0]
	v_pk_add_f32 v[136:137], v[136:137], 1.0 op_sel_hi:[1,0]
	v_rcp_f32_e32 v130, v130
	v_rcp_f32_e32 v131, v131
	v_rcp_f32_e32 v132, v132
	v_rcp_f32_e32 v133, v133
	v_rcp_f32_e32 v134, v134
	v_rcp_f32_e32 v135, v135
	v_rcp_f32_e32 v136, v136
	v_rcp_f32_e32 v137, v137
	v_pk_mul_f32 v[130:131], v[130:131], v[78:79]
	v_pk_mul_f32 v[132:133], v[132:133], v[80:81]
	v_pk_mul_f32 v[134:135], v[134:135], v[74:75]
	v_pk_mul_f32 v[136:137], v[136:137], v[76:77]
	v_cvt_pk_bf16_f32 v138, v130, v131
	v_cvt_pk_bf16_f32 v139, v132, v133
	v_cvt_pk_bf16_f32 v140, v134, v135
	v_cvt_pk_bf16_f32 v141, v136, v137
	global_store_dwordx4 v159, v[138:141], s[2:3]
	v_pk_mul_f32 v[130:131], v[70:71], v[160:161]
	v_pk_mul_f32 v[132:133], v[72:73], v[160:161]
	v_pk_mul_f32 v[134:135], v[66:67], v[160:161]
	v_pk_mul_f32 v[136:137], v[68:69], v[160:161]
	v_exp_f32_e32 v130, v130
	v_exp_f32_e32 v131, v131
	v_exp_f32_e32 v132, v132
	v_exp_f32_e32 v133, v133
	v_exp_f32_e32 v134, v134
	v_exp_f32_e32 v135, v135
	v_exp_f32_e32 v136, v136
	v_exp_f32_e32 v137, v137
	v_pk_add_f32 v[130:131], v[130:131], 1.0 op_sel_hi:[1,0]
	v_pk_add_f32 v[132:133], v[132:133], 1.0 op_sel_hi:[1,0]
	v_pk_add_f32 v[134:135], v[134:135], 1.0 op_sel_hi:[1,0]
	v_pk_add_f32 v[136:137], v[136:137], 1.0 op_sel_hi:[1,0]
	v_rcp_f32_e32 v130, v130
	v_rcp_f32_e32 v131, v131
	v_rcp_f32_e32 v132, v132
	v_rcp_f32_e32 v133, v133
	v_rcp_f32_e32 v134, v134
	v_rcp_f32_e32 v135, v135
	v_rcp_f32_e32 v136, v136
	v_rcp_f32_e32 v137, v137
	v_pk_mul_f32 v[130:131], v[130:131], v[70:71]
	v_pk_mul_f32 v[132:133], v[132:133], v[72:73]
	v_pk_mul_f32 v[134:135], v[134:135], v[66:67]
	v_pk_mul_f32 v[136:137], v[136:137], v[68:69]
	v_cvt_pk_bf16_f32 v138, v130, v131
	v_cvt_pk_bf16_f32 v139, v132, v133
	v_cvt_pk_bf16_f32 v140, v134, v135
	v_cvt_pk_bf16_f32 v141, v136, v137
	global_store_dwordx4 v159, v[138:141], s[2:3] offset:256
	v_add_u32_e32 v159, 0x28000, v159
	v_pk_mul_f32 v[130:131], v[62:63], v[160:161]
	v_pk_mul_f32 v[132:133], v[64:65], v[160:161]
	v_pk_mul_f32 v[134:135], v[58:59], v[160:161]
	v_pk_mul_f32 v[136:137], v[60:61], v[160:161]
	v_exp_f32_e32 v130, v130
	v_exp_f32_e32 v131, v131
	v_exp_f32_e32 v132, v132
	v_exp_f32_e32 v133, v133
	v_exp_f32_e32 v134, v134
	v_exp_f32_e32 v135, v135
	v_exp_f32_e32 v136, v136
	v_exp_f32_e32 v137, v137
	v_pk_add_f32 v[130:131], v[130:131], 1.0 op_sel_hi:[1,0]
	v_pk_add_f32 v[132:133], v[132:133], 1.0 op_sel_hi:[1,0]
	v_pk_add_f32 v[134:135], v[134:135], 1.0 op_sel_hi:[1,0]
	v_pk_add_f32 v[136:137], v[136:137], 1.0 op_sel_hi:[1,0]
	v_rcp_f32_e32 v130, v130
	v_rcp_f32_e32 v131, v131
	v_rcp_f32_e32 v132, v132
	v_rcp_f32_e32 v133, v133
	v_rcp_f32_e32 v134, v134
	v_rcp_f32_e32 v135, v135
	v_rcp_f32_e32 v136, v136
	v_rcp_f32_e32 v137, v137
	v_pk_mul_f32 v[130:131], v[130:131], v[62:63]
	v_pk_mul_f32 v[132:133], v[132:133], v[64:65]
	v_pk_mul_f32 v[134:135], v[134:135], v[58:59]
	v_pk_mul_f32 v[136:137], v[136:137], v[60:61]
	v_cvt_pk_bf16_f32 v138, v130, v131
	v_cvt_pk_bf16_f32 v139, v132, v133
	v_cvt_pk_bf16_f32 v140, v134, v135
	v_cvt_pk_bf16_f32 v141, v136, v137
	global_store_dwordx4 v159, v[138:141], s[2:3]
	v_pk_mul_f32 v[130:131], v[54:55], v[160:161]
	v_pk_mul_f32 v[132:133], v[56:57], v[160:161]
; __device__ __forceinline__ unsigned cvt_pk_bf16(float lo, float hi) { f32x2 v = {lo, hi}; bf16x2_t b = __builtin_convertvector(v, bf16x2_t); return __builtin_bit_cast(unsigned, b); }
; __device__ __forceinline__ float siluf(float v) { return v / (1.f + __expf(-v)); }
; template <int MODE> __device__ __forceinline__ void gemm_epilogue(f32x4 (&acc)[2][2][4][2], const GD& g, const pg8::Unit& u, int wr, int wc, int fr, int fq, LAS unsigned char* lds, const float (&rsv)[2][4]) {
;     ...
;             for (int ai = 0; ai < 2; ++ai)
; #pragma unroll
;                 for (int m = 0; m < 4; ++m) { bf16_t* rowp = O + (size_t)(rt + ai * 128 + m * 16) * 1024 + col0;
; #pragma unroll
;                     for (int bj = 0; bj < 2; ++bj) { f32x4 v0 = acc[ai][bj][m][0], v1 = acc[ai][bj][m][1];
;                         if (sel == 1) {
; #pragma unroll
;                             for (int j = 0; j < 4; ++j) { v0[j] = siluf(v0[j]) * 0.08838834764831845f; v1[j] = siluf(v1[j]) * 0.08838834764831845f; } }
;                         if (sel == 4) {
; #pragma unroll
;                             for (int j = 0; j < 4; ++j) { v0[j] = siluf(v0[j]); v1[j] = siluf(v1[j]); } }
;                         u32x4 w; w.x = cvt_pk_bf16(v0[0], v0[1]); w.y = cvt_pk_bf16(v0[2], v0[3]); w.z = cvt_pk_bf16(v1[0], v1[1]); w.w = cvt_pk_bf16(v1[2], v1[3]);
;                         *(u32x4*)(rowp + bj * 128) = w; } }
	v_pk_mul_f32 v[134:135], v[50:51], v[160:161]
	v_pk_mul_f32 v[136:137], v[52:53], v[160:161]
	v_exp_f32_e32 v130, v130
	v_exp_f32_e32 v131, v131
	v_exp_f32_e32 v132, v132
	v_exp_f32_e32 v133, v133
	v_exp_f32_e32 v134, v134
	v_exp_f32_e32 v135, v135
	v_exp_f32_e32 v136, v136
	v_exp_f32_e32 v137, v137
	v_pk_add_f32 v[130:131], v[130:131], 1.0 op_sel_hi:[1,0]
	v_pk_add_f32 v[132:133], v[132:133], 1.0 op_sel_hi:[1,0]
	v_pk_add_f32 v[134:135], v[134:135], 1.0 op_sel_hi:[1,0]
	v_pk_add_f32 v[136:137], v[136:137], 1.0 op_sel_hi:[1,0]
	v_rcp_f32_e32 v130, v130
	v_rcp_f32_e32 v131, v131
	v_rcp_f32_e32 v132, v132
	v_rcp_f32_e32 v133, v133
	v_rcp_f32_e32 v134, v134
	v_rcp_f32_e32 v135, v135
	v_rcp_f32_e32 v136, v136
	v_rcp_f32_e32 v137, v137
	v_pk_mul_f32 v[130:131], v[130:131], v[54:55]
	v_pk_mul_f32 v[132:133], v[132:133], v[56:57]
	v_pk_mul_f32 v[134:135], v[134:135], v[50:51]
	v_pk_mul_f32 v[136:137], v[136:137], v[52:53]
	v_cvt_pk_bf16_f32 v138, v130, v131
	v_cvt_pk_bf16_f32 v139, v132, v133
	v_cvt_pk_bf16_f32 v140, v134, v135
	v_cvt_pk_bf16_f32 v141, v136, v137
	global_store_dwordx4 v159, v[138:141], s[2:3] offset:256
	v_add_u32_e32 v159, 0x8000, v159
	v_pk_mul_f32 v[130:131], v[46:47], v[160:161]
	v_pk_mul_f32 v[132:133], v[48:49], v[160:161]
	v_pk_mul_f32 v[134:135], v[42:43], v[160:161]
	v_pk_mul_f32 v[136:137], v[44:45], v[160:161]
	v_exp_f32_e32 v130, v130
	v_exp_f32_e32 v131, v131
	v_exp_f32_e32 v132, v132
	v_exp_f32_e32 v133, v133
	v_exp_f32_e32 v134, v134
	v_exp_f32_e32 v135, v135
	v_exp_f32_e32 v136, v136
	v_exp_f32_e32 v137, v137
	v_pk_add_f32 v[130:131], v[130:131], 1.0 op_sel_hi:[1,0]
	v_pk_add_f32 v[132:133], v[132:133], 1.0 op_sel_hi:[1,0]
	v_pk_add_f32 v[134:135], v[134:135], 1.0 op_sel_hi:[1,0]
	v_pk_add_f32 v[136:137], v[136:137], 1.0 op_sel_hi:[1,0]
	v_rcp_f32_e32 v130, v130
	v_rcp_f32_e32 v131, v131
	v_rcp_f32_e32 v132, v132
	v_rcp_f32_e32 v133, v133
	v_rcp_f32_e32 v134, v134
	v_rcp_f32_e32 v135, v135
	v_rcp_f32_e32 v136, v136
	v_rcp_f32_e32 v137, v137
	v_pk_mul_f32 v[130:131], v[130:131], v[46:47]
	v_pk_mul_f32 v[132:133], v[132:133], v[48:49]
	v_pk_mul_f32 v[134:135], v[134:135], v[42:43]
	v_pk_mul_f32 v[136:137], v[136:137], v[44:45]
	v_cvt_pk_bf16_f32 v138, v130, v131
	v_cvt_pk_bf16_f32 v139, v132, v133
	v_cvt_pk_bf16_f32 v140, v134, v135
	v_cvt_pk_bf16_f32 v141, v136, v137
	global_store_dwordx4 v159, v[138:141], s[2:3]
	v_pk_mul_f32 v[130:131], v[38:39], v[160:161]
	v_pk_mul_f32 v[132:133], v[40:41], v[160:161]
	v_pk_mul_f32 v[134:135], v[34:35], v[160:161]
	v_pk_mul_f32 v[136:137], v[36:37], v[160:161]
	v_exp_f32_e32 v130, v130
	v_exp_f32_e32 v131, v131
	v_exp_f32_e32 v132, v132
	v_exp_f32_e32 v133, v133
	v_exp_f32_e32 v134, v134
	v_exp_f32_e32 v135, v135
	v_exp_f32_e32 v136, v136
	v_exp_f32_e32 v137, v137
	v_pk_add_f32 v[130:131], v[130:131], 1.0 op_sel_hi:[1,0]
	v_pk_add_f32 v[132:133], v[132:133], 1.0 op_sel_hi:[1,0]
	v_pk_add_f32 v[134:135], v[134:135], 1.0 op_sel_hi:[1,0]
	v_pk_add_f32 v[136:137], v[136:137], 1.0 op_sel_hi:[1,0]
	v_rcp_f32_e32 v130, v130
	v_rcp_f32_e32 v131, v131
	v_rcp_f32_e32 v132, v132
	v_rcp_f32_e32 v133, v133
	v_rcp_f32_e32 v134, v134
	v_rcp_f32_e32 v135, v135
	v_rcp_f32_e32 v136, v136
	v_rcp_f32_e32 v137, v137
	v_pk_mul_f32 v[130:131], v[130:131], v[38:39]
	v_pk_mul_f32 v[132:133], v[132:133], v[40:41]
	v_pk_mul_f32 v[134:135], v[134:135], v[34:35]
	v_pk_mul_f32 v[136:137], v[136:137], v[36:37]
	v_cvt_pk_bf16_f32 v138, v130, v131
	v_cvt_pk_bf16_f32 v139, v132, v133
	v_cvt_pk_bf16_f32 v140, v134, v135
	v_cvt_pk_bf16_f32 v141, v136, v137
	global_store_dwordx4 v159, v[138:141], s[2:3] offset:256
	v_add_u32_e32 v159, 0x8000, v159
	v_pk_mul_f32 v[130:131], v[30:31], v[160:161]
	v_pk_mul_f32 v[132:133], v[32:33], v[160:161]
	v_pk_mul_f32 v[134:135], v[26:27], v[160:161]
	v_pk_mul_f32 v[136:137], v[28:29], v[160:161]
	v_exp_f32_e32 v130, v130
	v_exp_f32_e32 v131, v131
	v_exp_f32_e32 v132, v132
	v_exp_f32_e32 v133, v133
	v_exp_f32_e32 v134, v134
	v_exp_f32_e32 v135, v135
	v_exp_f32_e32 v136, v136
	v_exp_f32_e32 v137, v137
	v_pk_add_f32 v[130:131], v[130:131], 1.0 op_sel_hi:[1,0]
	v_pk_add_f32 v[132:133], v[132:133], 1.0 op_sel_hi:[1,0]
	v_pk_add_f32 v[134:135], v[134:135], 1.0 op_sel_hi:[1,0]
	v_pk_add_f32 v[136:137], v[136:137], 1.0 op_sel_hi:[1,0]
	v_rcp_f32_e32 v130, v130
	v_rcp_f32_e32 v131, v131
	v_rcp_f32_e32 v132, v132
	v_rcp_f32_e32 v133, v133
	v_rcp_f32_e32 v134, v134
	v_rcp_f32_e32 v135, v135
	v_rcp_f32_e32 v136, v136
	v_rcp_f32_e32 v137, v137
	v_pk_mul_f32 v[130:131], v[130:131], v[30:31]
	v_pk_mul_f32 v[132:133], v[132:133], v[32:33]
	v_pk_mul_f32 v[134:135], v[134:135], v[26:27]
	v_pk_mul_f32 v[136:137], v[136:137], v[28:29]
	v_cvt_pk_bf16_f32 v138, v130, v131
	v_cvt_pk_bf16_f32 v139, v132, v133
	v_cvt_pk_bf16_f32 v140, v134, v135
	v_cvt_pk_bf16_f32 v141, v136, v137
	global_store_dwordx4 v159, v[138:141], s[2:3]
	v_pk_mul_f32 v[130:131], v[22:23], v[160:161]
	v_pk_mul_f32 v[132:133], v[24:25], v[160:161]
	v_pk_mul_f32 v[134:135], v[18:19], v[160:161]
	v_pk_mul_f32 v[136:137], v[20:21], v[160:161]
	v_exp_f32_e32 v130, v130
	v_exp_f32_e32 v131, v131
	v_exp_f32_e32 v132, v132
	v_exp_f32_e32 v133, v133
	v_exp_f32_e32 v134, v134
	v_exp_f32_e32 v135, v135
	v_exp_f32_e32 v136, v136
	v_exp_f32_e32 v137, v137
	v_pk_add_f32 v[130:131], v[130:131], 1.0 op_sel_hi:[1,0]
	v_pk_add_f32 v[132:133], v[132:133], 1.0 op_sel_hi:[1,0]
	v_pk_add_f32 v[134:135], v[134:135], 1.0 op_sel_hi:[1,0]
	v_pk_add_f32 v[136:137], v[136:137], 1.0 op_sel_hi:[1,0]
	v_rcp_f32_e32 v130, v130
	v_rcp_f32_e32 v131, v131
	v_rcp_f32_e32 v132, v132
	v_rcp_f32_e32 v133, v133
	v_rcp_f32_e32 v134, v134
	v_rcp_f32_e32 v135, v135
; __device__ __forceinline__ unsigned cvt_pk_bf16(float lo, float hi) { f32x2 v = {lo, hi}; bf16x2_t b = __builtin_convertvector(v, bf16x2_t); return __builtin_bit_cast(unsigned, b); }
; __device__ __forceinline__ float siluf(float v) { return v / (1.f + __expf(-v)); }
; template <int MODE> __device__ __forceinline__ void gemm_epilogue(f32x4 (&acc)[2][2][4][2], const GD& g, const pg8::Unit& u, int wr, int wc, int fr, int fq, LAS unsigned char* lds, const float (&rsv)[2][4]) {
;     ...
;             const float* LB = g.f0; float* LOGF = (float*)g.o2;
;             f32x4 lb[2][2];
; #pragma unroll
;             for (int bj = 0; bj < 2; ++bj)
; #pragma unroll
;                 for (int n = 0; n < 2; ++n) lb[bj][n] = *(const f32x4*)(LB + col0 + bj * 128 + 4 * n);
; #pragma unroll
;             for (int ai = 0; ai < 2; ++ai)
; #pragma unroll
;                 for (int m = 0; m < 4; ++m) { float* rowp = LOGF + (size_t)(rt + ai * 128 + m * 16) * 1024 + col0;
; #pragma unroll
;                     for (int bj = 0; bj < 2; ++bj)
;                     {
; #pragma unroll
;                         for (int n = 0; n < 2; ++n) { f32x4 v = acc[ai][bj][m][n], o;
; #pragma unroll
;                             for (int j = 0; j < 4; ++j) { const float sg = 1.f / (1.f + __expf(-v[j])); const float f = lb[bj][n][j] + (1.f - lb[bj][n][j]) * sg; o[j] = __logf(f); }
;                             *(f32x4*)(rowp + bj * 128 + 4 * n) = o; } } }
;     ...
;             for (int ai = 0; ai < 2; ++ai)
; #pragma unroll
;                 for (int m = 0; m < 4; ++m) { bf16_t* rowp = O + (size_t)(rt + ai * 128 + m * 16) * 1024 + col0;
; #pragma unroll
;                     for (int bj = 0; bj < 2; ++bj) { f32x4 v0 = acc[ai][bj][m][0], v1 = acc[ai][bj][m][1];
;                         if (sel == 1) {
; #pragma unroll
;                             for (int j = 0; j < 4; ++j) { v0[j] = siluf(v0[j]) * 0.08838834764831845f; v1[j] = siluf(v1[j]) * 0.08838834764831845f; } }
;                         if (sel == 4) {
; #pragma unroll
;                             for (int j = 0; j < 4; ++j) { v0[j] = siluf(v0[j]); v1[j] = siluf(v1[j]); } }
;                         u32x4 w; w.x = cvt_pk_bf16(v0[0], v0[1]); w.y = cvt_pk_bf16(v0[2], v0[3]); w.z = cvt_pk_bf16(v1[0], v1[1]); w.w = cvt_pk_bf16(v1[2], v1[3]);
;                         *(u32x4*)(rowp + bj * 128) = w; } }
	v_rcp_f32_e32 v136, v136
	v_rcp_f32_e32 v137, v137
	v_pk_mul_f32 v[130:131], v[130:131], v[22:23]
	v_pk_mul_f32 v[132:133], v[132:133], v[24:25]
	v_pk_mul_f32 v[134:135], v[134:135], v[18:19]
	v_pk_mul_f32 v[136:137], v[136:137], v[20:21]
	v_cvt_pk_bf16_f32 v138, v130, v131
	v_cvt_pk_bf16_f32 v139, v132, v133
	v_cvt_pk_bf16_f32 v140, v134, v135
	v_cvt_pk_bf16_f32 v141, v136, v137
	global_store_dwordx4 v159, v[138:141], s[2:3] offset:256
	v_add_u32_e32 v159, 0x8000, v159
	v_pk_mul_f32 v[130:131], v[14:15], v[160:161]
	v_pk_mul_f32 v[132:133], v[16:17], v[160:161]
	v_pk_mul_f32 v[134:135], v[10:11], v[160:161]
	v_pk_mul_f32 v[136:137], v[12:13], v[160:161]
	v_exp_f32_e32 v130, v130
	v_exp_f32_e32 v131, v131
	v_exp_f32_e32 v132, v132
	v_exp_f32_e32 v133, v133
	v_exp_f32_e32 v134, v134
	v_exp_f32_e32 v135, v135
	v_exp_f32_e32 v136, v136
	v_exp_f32_e32 v137, v137
	v_pk_add_f32 v[130:131], v[130:131], 1.0 op_sel_hi:[1,0]
	v_pk_add_f32 v[132:133], v[132:133], 1.0 op_sel_hi:[1,0]
	v_pk_add_f32 v[134:135], v[134:135], 1.0 op_sel_hi:[1,0]
	v_pk_add_f32 v[136:137], v[136:137], 1.0 op_sel_hi:[1,0]
	v_rcp_f32_e32 v130, v130
	v_rcp_f32_e32 v131, v131
	v_rcp_f32_e32 v132, v132
	v_rcp_f32_e32 v133, v133
	v_rcp_f32_e32 v134, v134
	v_rcp_f32_e32 v135, v135
	v_rcp_f32_e32 v136, v136
	v_rcp_f32_e32 v137, v137
	v_pk_mul_f32 v[130:131], v[130:131], v[14:15]
	v_pk_mul_f32 v[132:133], v[132:133], v[16:17]
	v_pk_mul_f32 v[134:135], v[134:135], v[10:11]
	v_pk_mul_f32 v[136:137], v[136:137], v[12:13]
	v_cvt_pk_bf16_f32 v138, v130, v131
	v_cvt_pk_bf16_f32 v139, v132, v133
	v_cvt_pk_bf16_f32 v140, v134, v135
	v_cvt_pk_bf16_f32 v141, v136, v137
	global_store_dwordx4 v159, v[138:141], s[2:3]
	v_pk_mul_f32 v[130:131], v[6:7], v[160:161]
	v_pk_mul_f32 v[132:133], v[8:9], v[160:161]
	v_pk_mul_f32 v[134:135], v[2:3], v[160:161]
	v_pk_mul_f32 v[136:137], v[4:5], v[160:161]
	v_exp_f32_e32 v130, v130
	v_exp_f32_e32 v131, v131
	v_exp_f32_e32 v132, v132
	v_exp_f32_e32 v133, v133
	v_exp_f32_e32 v134, v134
	v_exp_f32_e32 v135, v135
	v_exp_f32_e32 v136, v136
	v_exp_f32_e32 v137, v137
	v_pk_add_f32 v[130:131], v[130:131], 1.0 op_sel_hi:[1,0]
	v_pk_add_f32 v[132:133], v[132:133], 1.0 op_sel_hi:[1,0]
	v_pk_add_f32 v[134:135], v[134:135], 1.0 op_sel_hi:[1,0]
	v_pk_add_f32 v[136:137], v[136:137], 1.0 op_sel_hi:[1,0]
	v_rcp_f32_e32 v130, v130
	v_rcp_f32_e32 v131, v131
	v_rcp_f32_e32 v132, v132
	v_rcp_f32_e32 v133, v133
	v_rcp_f32_e32 v134, v134
	v_rcp_f32_e32 v135, v135
	v_rcp_f32_e32 v136, v136
	v_rcp_f32_e32 v137, v137
	v_pk_mul_f32 v[130:131], v[130:131], v[6:7]
	v_pk_mul_f32 v[132:133], v[132:133], v[8:9]
	v_pk_mul_f32 v[134:135], v[134:135], v[2:3]
	v_pk_mul_f32 v[136:137], v[136:137], v[4:5]
	v_cvt_pk_bf16_f32 v138, v130, v131
	v_cvt_pk_bf16_f32 v139, v132, v133
	v_cvt_pk_bf16_f32 v140, v134, v135
	v_cvt_pk_bf16_f32 v141, v136, v137
	global_store_dwordx4 v159, v[138:141], s[2:3] offset:256
	s_branch .Levin_done
.Levin_log:
	v_readlane_b32 s0, v254, 48
	v_readlane_b32 s1, v254, 49
	v_readlane_b32 s2, v254, 44
	v_readlane_b32 s3, v254, 45
	v_lshlrev_b32_e32 v159, 12, v158
	v_lshlrev_b32_e32 v1, 2, v1
	v_add_u32_e32 v159, v159, v1
	s_nop 1
	global_load_dwordx4 v[220:223], v1, s[0:1]
	global_load_dwordx4 v[224:227], v1, s[0:1] offset:16
	global_load_dwordx4 v[228:231], v1, s[0:1] offset:512
	global_load_dwordx4 v[232:235], v1, s[0:1] offset:528
	s_waitcnt vmcnt(0)
	v_sub_f32_e32 v178, 1.0, v220
	v_sub_f32_e32 v179, 1.0, v221
	v_sub_f32_e32 v180, 1.0, v222
	v_sub_f32_e32 v181, 1.0, v223
	v_sub_f32_e32 v182, 1.0, v224
	v_sub_f32_e32 v183, 1.0, v225
	v_sub_f32_e32 v184, 1.0, v226
	v_sub_f32_e32 v185, 1.0, v227
	v_sub_f32_e32 v186, 1.0, v228
	v_sub_f32_e32 v187, 1.0, v229
	v_sub_f32_e32 v188, 1.0, v230
	v_sub_f32_e32 v189, 1.0, v231
	v_sub_f32_e32 v190, 1.0, v232
	v_sub_f32_e32 v191, 1.0, v233
	v_sub_f32_e32 v192, 1.0, v234
	v_sub_f32_e32 v193, 1.0, v235
	v_pk_mul_f32 v[130:131], v[126:127], v[160:161]
	v_pk_mul_f32 v[132:133], v[128:129], v[160:161]
	v_pk_mul_f32 v[134:135], v[122:123], v[160:161]
	v_pk_mul_f32 v[136:137], v[124:125], v[160:161]
	v_exp_f32_e32 v130, v130
	v_exp_f32_e32 v131, v131
	v_exp_f32_e32 v132, v132
	v_exp_f32_e32 v133, v133
	v_exp_f32_e32 v134, v134
	v_exp_f32_e32 v135, v135
	v_exp_f32_e32 v136, v136
	v_exp_f32_e32 v137, v137
	v_pk_add_f32 v[130:131], v[130:131], 1.0 op_sel_hi:[1,0]
	v_pk_add_f32 v[132:133], v[132:133], 1.0 op_sel_hi:[1,0]
	v_pk_add_f32 v[134:135], v[134:135], 1.0 op_sel_hi:[1,0]
	v_pk_add_f32 v[136:137], v[136:137], 1.0 op_sel_hi:[1,0]
	v_rcp_f32_e32 v130, v130
	v_rcp_f32_e32 v131, v131
	v_rcp_f32_e32 v132, v132
	v_rcp_f32_e32 v133, v133
	v_rcp_f32_e32 v134, v134
	v_rcp_f32_e32 v135, v135
	v_rcp_f32_e32 v136, v136
	v_rcp_f32_e32 v137, v137
	v_pk_fma_f32 v[130:131], v[130:131], v[178:179], v[220:221]
	v_pk_fma_f32 v[132:133], v[132:133], v[180:181], v[222:223]
	v_pk_fma_f32 v[134:135], v[134:135], v[182:183], v[224:225]
	v_pk_fma_f32 v[136:137], v[136:137], v[184:185], v[226:227]
	v_cmp_gt_f32_e32 vcc, s80, v130
	v_cmp_gt_f32_e64 s[8:9], s80, v131
	v_cmp_gt_f32_e64 s[10:11], s80, v132
	v_cmp_gt_f32_e64 s[42:43], s80, v133
	v_cndmask_b32_e64 v138, 0, 32, vcc
	v_cndmask_b32_e64 v139, 0, 32, s[8:9]
	v_cndmask_b32_e64 v140, 0, 32, s[10:11]
	v_cndmask_b32_e64 v141, 0, 32, s[42:43]
	v_cndmask_b32_e64 v162, 0, v214, vcc
	v_cndmask_b32_e64 v163, 0, v214, s[8:9]
	v_cndmask_b32_e64 v196, 0, v214, s[10:11]
	v_cndmask_b32_e64 v197, 0, v214, s[42:43]
	v_cmp_gt_f32_e32 vcc, s80, v134
	v_cmp_gt_f32_e64 s[8:9], s80, v135
	v_cmp_gt_f32_e64 s[10:11], s80, v136
	v_cmp_gt_f32_e64 s[42:43], s80, v137
	v_cndmask_b32_e64 v142, 0, 32, vcc
	v_cndmask_b32_e64 v143, 0, 32, s[8:9]
; template <int MODE> __device__ __forceinline__ void gemm_epilogue(f32x4 (&acc)[2][2][4][2], const GD& g, const pg8::Unit& u, int wr, int wc, int fr, int fq, LAS unsigned char* lds, const float (&rsv)[2][4]) {
;     ...
;             for (int ai = 0; ai < 2; ++ai)
; #pragma unroll
;                 for (int m = 0; m < 4; ++m) { float* rowp = LOGF + (size_t)(rt + ai * 128 + m * 16) * 1024 + col0;
; #pragma unroll
;                     for (int bj = 0; bj < 2; ++bj)
;                     {
; #pragma unroll
;                         for (int n = 0; n < 2; ++n) { f32x4 v = acc[ai][bj][m][n], o;
; #pragma unroll
;                             for (int j = 0; j < 4; ++j) { const float sg = 1.f / (1.f + __expf(-v[j])); const float f = lb[bj][n][j] + (1.f - lb[bj][n][j]) * sg; o[j] = __logf(f); }
;                             *(f32x4*)(rowp + bj * 128 + 4 * n) = o; } } }
	v_cndmask_b32_e64 v144, 0, 32, s[10:11]
	v_cndmask_b32_e64 v145, 0, 32, s[42:43]
	v_cndmask_b32_e64 v198, 0, v214, vcc
	v_cndmask_b32_e64 v199, 0, v214, s[8:9]
	v_cndmask_b32_e64 v204, 0, v214, s[10:11]
	v_cndmask_b32_e64 v205, 0, v214, s[42:43]
	v_ldexp_f32 v130, v130, v138
	v_ldexp_f32 v131, v131, v139
	v_ldexp_f32 v132, v132, v140
	v_ldexp_f32 v133, v133, v141
	v_ldexp_f32 v134, v134, v142
	v_ldexp_f32 v135, v135, v143
	v_ldexp_f32 v136, v136, v144
	v_ldexp_f32 v137, v137, v145
	v_log_f32_e32 v130, v130
	v_log_f32_e32 v131, v131
	v_log_f32_e32 v132, v132
	v_log_f32_e32 v133, v133
	v_log_f32_e32 v134, v134
	v_log_f32_e32 v135, v135
	v_log_f32_e32 v136, v136
	v_log_f32_e32 v137, v137
	v_mul_f32_e32 v138, 0x3f317217, v130
	v_mul_f32_e32 v139, 0x3f317217, v131
	v_mul_f32_e32 v140, 0x3f317217, v132
	v_mul_f32_e32 v141, 0x3f317217, v133
	v_mul_f32_e32 v142, 0x3f317217, v134
	v_mul_f32_e32 v143, 0x3f317217, v135
	v_mul_f32_e32 v144, 0x3f317217, v136
	v_mul_f32_e32 v145, 0x3f317217, v137
	v_fma_f32 v138, v130, s85, -v138
	v_fma_f32 v139, v131, s85, -v139
	v_fma_f32 v140, v132, s85, -v140
	v_fma_f32 v141, v133, s85, -v141
	v_fma_f32 v142, v134, s85, -v142
	v_fma_f32 v143, v135, s85, -v143
	v_fma_f32 v144, v136, s85, -v144
	v_fma_f32 v145, v137, s85, -v145
	v_fmac_f32_e32 v138, 0x3377d1cf, v130
	v_fmac_f32_e32 v139, 0x3377d1cf, v131
	v_fmac_f32_e32 v140, 0x3377d1cf, v132
	v_fmac_f32_e32 v141, 0x3377d1cf, v133
	v_fmac_f32_e32 v142, 0x3377d1cf, v134
	v_fmac_f32_e32 v143, 0x3377d1cf, v135
	v_fmac_f32_e32 v144, 0x3377d1cf, v136
	v_fmac_f32_e32 v145, 0x3377d1cf, v137
	v_fmac_f32_e32 v138, 0x3f317217, v130
	v_fmac_f32_e32 v139, 0x3f317217, v131
	v_fmac_f32_e32 v140, 0x3f317217, v132
	v_fmac_f32_e32 v141, 0x3f317217, v133
	v_fmac_f32_e32 v142, 0x3f317217, v134
	v_fmac_f32_e32 v143, 0x3f317217, v135
	v_fmac_f32_e32 v144, 0x3f317217, v136
	v_fmac_f32_e32 v145, 0x3f317217, v137
	v_cmp_lt_f32_e64 vcc, |v130|, s55
	v_cmp_lt_f32_e64 s[8:9], |v131|, s55
	v_cmp_lt_f32_e64 s[10:11], |v132|, s55
	v_cmp_lt_f32_e64 s[42:43], |v133|, s55
	v_cndmask_b32_e64 v130, v130, v138, vcc
	v_cndmask_b32_e64 v131, v131, v139, s[8:9]
	v_cndmask_b32_e64 v132, v132, v140, s[10:11]
	v_cndmask_b32_e64 v133, v133, v141, s[42:43]
	v_cmp_lt_f32_e64 vcc, |v134|, s55
	v_cmp_lt_f32_e64 s[8:9], |v135|, s55
	v_cmp_lt_f32_e64 s[10:11], |v136|, s55
	v_cmp_lt_f32_e64 s[42:43], |v137|, s55
	v_cndmask_b32_e64 v134, v134, v142, vcc
	v_cndmask_b32_e64 v135, v135, v143, s[8:9]
	v_cndmask_b32_e64 v136, v136, v144, s[10:11]
	v_cndmask_b32_e64 v137, v137, v145, s[42:43]
	v_sub_f32_e32 v130, v130, v162
	v_sub_f32_e32 v131, v131, v163
	v_sub_f32_e32 v132, v132, v196
	v_sub_f32_e32 v133, v133, v197
	v_sub_f32_e32 v134, v134, v198
	v_sub_f32_e32 v135, v135, v199
	v_sub_f32_e32 v136, v136, v204
	v_sub_f32_e32 v137, v137, v205
	global_store_dwordx4 v159, v[130:133], s[2:3]
	global_store_dwordx4 v159, v[134:137], s[2:3] offset:16
	s_nop 0
	v_pk_mul_f32 v[130:131], v[118:119], v[160:161]
	v_pk_mul_f32 v[132:133], v[120:121], v[160:161]
	v_pk_mul_f32 v[134:135], v[114:115], v[160:161]
	v_pk_mul_f32 v[136:137], v[116:117], v[160:161]
	v_exp_f32_e32 v130, v130
	v_exp_f32_e32 v131, v131
	v_exp_f32_e32 v132, v132
	v_exp_f32_e32 v133, v133
	v_exp_f32_e32 v134, v134
	v_exp_f32_e32 v135, v135
	v_exp_f32_e32 v136, v136
	v_exp_f32_e32 v137, v137
	v_pk_add_f32 v[130:131], v[130:131], 1.0 op_sel_hi:[1,0]
	v_pk_add_f32 v[132:133], v[132:133], 1.0 op_sel_hi:[1,0]
	v_pk_add_f32 v[134:135], v[134:135], 1.0 op_sel_hi:[1,0]
	v_pk_add_f32 v[136:137], v[136:137], 1.0 op_sel_hi:[1,0]
	v_rcp_f32_e32 v130, v130
	v_rcp_f32_e32 v131, v131
	v_rcp_f32_e32 v132, v132
	v_rcp_f32_e32 v133, v133
	v_rcp_f32_e32 v134, v134
	v_rcp_f32_e32 v135, v135
	v_rcp_f32_e32 v136, v136
	v_rcp_f32_e32 v137, v137
	v_pk_fma_f32 v[130:131], v[130:131], v[186:187], v[228:229]
	v_pk_fma_f32 v[132:133], v[132:133], v[188:189], v[230:231]
	v_pk_fma_f32 v[134:135], v[134:135], v[190:191], v[232:233]
	v_pk_fma_f32 v[136:137], v[136:137], v[192:193], v[234:235]
	v_cmp_gt_f32_e32 vcc, s80, v130
	v_cmp_gt_f32_e64 s[8:9], s80, v131
	v_cmp_gt_f32_e64 s[10:11], s80, v132
	v_cmp_gt_f32_e64 s[42:43], s80, v133
	v_cndmask_b32_e64 v138, 0, 32, vcc
	v_cndmask_b32_e64 v139, 0, 32, s[8:9]
	v_cndmask_b32_e64 v140, 0, 32, s[10:11]
	v_cndmask_b32_e64 v141, 0, 32, s[42:43]
	v_cndmask_b32_e64 v162, 0, v214, vcc
	v_cndmask_b32_e64 v163, 0, v214, s[8:9]
	v_cndmask_b32_e64 v196, 0, v214, s[10:11]
	v_cndmask_b32_e64 v197, 0, v214, s[42:43]
	v_cmp_gt_f32_e32 vcc, s80, v134
	v_cmp_gt_f32_e64 s[8:9], s80, v135
	v_cmp_gt_f32_e64 s[10:11], s80, v136
	v_cmp_gt_f32_e64 s[42:43], s80, v137
	v_cndmask_b32_e64 v142, 0, 32, vcc
	v_cndmask_b32_e64 v143, 0, 32, s[8:9]
	v_cndmask_b32_e64 v144, 0, 32, s[10:11]
	v_cndmask_b32_e64 v145, 0, 32, s[42:43]
	v_cndmask_b32_e64 v198, 0, v214, vcc
	v_cndmask_b32_e64 v199, 0, v214, s[8:9]
	v_cndmask_b32_e64 v204, 0, v214, s[10:11]
	v_cndmask_b32_e64 v205, 0, v214, s[42:43]
	v_ldexp_f32 v130, v130, v138
	v_ldexp_f32 v131, v131, v139
	v_ldexp_f32 v132, v132, v140
	v_ldexp_f32 v133, v133, v141
	v_ldexp_f32 v134, v134, v142
	v_ldexp_f32 v135, v135, v143
	v_ldexp_f32 v136, v136, v144
	v_ldexp_f32 v137, v137, v145
	v_log_f32_e32 v130, v130
	v_log_f32_e32 v131, v131
	v_log_f32_e32 v132, v132
	v_log_f32_e32 v133, v133
	v_log_f32_e32 v134, v134
	v_log_f32_e32 v135, v135
	v_log_f32_e32 v136, v136
	v_log_f32_e32 v137, v137
	v_mul_f32_e32 v138, 0x3f317217, v130
	v_mul_f32_e32 v139, 0x3f317217, v131
	v_mul_f32_e32 v140, 0x3f317217, v132
	v_mul_f32_e32 v141, 0x3f317217, v133
	v_mul_f32_e32 v142, 0x3f317217, v134
	v_mul_f32_e32 v143, 0x3f317217, v135
; template <int MODE> __device__ __forceinline__ void gemm_epilogue(f32x4 (&acc)[2][2][4][2], const GD& g, const pg8::Unit& u, int wr, int wc, int fr, int fq, LAS unsigned char* lds, const float (&rsv)[2][4]) {
;     ...
;             for (int ai = 0; ai < 2; ++ai)
; #pragma unroll
;                 for (int m = 0; m < 4; ++m) { float* rowp = LOGF + (size_t)(rt + ai * 128 + m * 16) * 1024 + col0;
; #pragma unroll
;                     for (int bj = 0; bj < 2; ++bj)
;                     {
; #pragma unroll
;                         for (int n = 0; n < 2; ++n) { f32x4 v = acc[ai][bj][m][n], o;
; #pragma unroll
;                             for (int j = 0; j < 4; ++j) { const float sg = 1.f / (1.f + __expf(-v[j])); const float f = lb[bj][n][j] + (1.f - lb[bj][n][j]) * sg; o[j] = __logf(f); }
;                             *(f32x4*)(rowp + bj * 128 + 4 * n) = o; } } }
	v_mul_f32_e32 v144, 0x3f317217, v136
	v_mul_f32_e32 v145, 0x3f317217, v137
	v_fma_f32 v138, v130, s85, -v138
	v_fma_f32 v139, v131, s85, -v139
	v_fma_f32 v140, v132, s85, -v140
	v_fma_f32 v141, v133, s85, -v141
	v_fma_f32 v142, v134, s85, -v142
	v_fma_f32 v143, v135, s85, -v143
	v_fma_f32 v144, v136, s85, -v144
	v_fma_f32 v145, v137, s85, -v145
	v_fmac_f32_e32 v138, 0x3377d1cf, v130
	v_fmac_f32_e32 v139, 0x3377d1cf, v131
	v_fmac_f32_e32 v140, 0x3377d1cf, v132
	v_fmac_f32_e32 v141, 0x3377d1cf, v133
	v_fmac_f32_e32 v142, 0x3377d1cf, v134
	v_fmac_f32_e32 v143, 0x3377d1cf, v135
	v_fmac_f32_e32 v144, 0x3377d1cf, v136
	v_fmac_f32_e32 v145, 0x3377d1cf, v137
	v_fmac_f32_e32 v138, 0x3f317217, v130
	v_fmac_f32_e32 v139, 0x3f317217, v131
	v_fmac_f32_e32 v140, 0x3f317217, v132
	v_fmac_f32_e32 v141, 0x3f317217, v133
	v_fmac_f32_e32 v142, 0x3f317217, v134
	v_fmac_f32_e32 v143, 0x3f317217, v135
	v_fmac_f32_e32 v144, 0x3f317217, v136
	v_fmac_f32_e32 v145, 0x3f317217, v137
	v_cmp_lt_f32_e64 vcc, |v130|, s55
	v_cmp_lt_f32_e64 s[8:9], |v131|, s55
	v_cmp_lt_f32_e64 s[10:11], |v132|, s55
	v_cmp_lt_f32_e64 s[42:43], |v133|, s55
	v_cndmask_b32_e64 v130, v130, v138, vcc
	v_cndmask_b32_e64 v131, v131, v139, s[8:9]
	v_cndmask_b32_e64 v132, v132, v140, s[10:11]
	v_cndmask_b32_e64 v133, v133, v141, s[42:43]
	v_cmp_lt_f32_e64 vcc, |v134|, s55
	v_cmp_lt_f32_e64 s[8:9], |v135|, s55
	v_cmp_lt_f32_e64 s[10:11], |v136|, s55
	v_cmp_lt_f32_e64 s[42:43], |v137|, s55
	v_cndmask_b32_e64 v134, v134, v142, vcc
	v_cndmask_b32_e64 v135, v135, v143, s[8:9]
	v_cndmask_b32_e64 v136, v136, v144, s[10:11]
	v_cndmask_b32_e64 v137, v137, v145, s[42:43]
	v_sub_f32_e32 v130, v130, v162
	v_sub_f32_e32 v131, v131, v163
	v_sub_f32_e32 v132, v132, v196
	v_sub_f32_e32 v133, v133, v197
	v_sub_f32_e32 v134, v134, v198
	v_sub_f32_e32 v135, v135, v199
	v_sub_f32_e32 v136, v136, v204
	v_sub_f32_e32 v137, v137, v205
	global_store_dwordx4 v159, v[130:133], s[2:3] offset:512
	global_store_dwordx4 v159, v[134:137], s[2:3] offset:528
	s_nop 0
	v_add_u32_e32 v159, 0x10000, v159
	v_pk_mul_f32 v[130:131], v[110:111], v[160:161]
	v_pk_mul_f32 v[132:133], v[112:113], v[160:161]
	v_pk_mul_f32 v[134:135], v[106:107], v[160:161]
	v_pk_mul_f32 v[136:137], v[108:109], v[160:161]
	v_exp_f32_e32 v130, v130
	v_exp_f32_e32 v131, v131
	v_exp_f32_e32 v132, v132
	v_exp_f32_e32 v133, v133
	v_exp_f32_e32 v134, v134
	v_exp_f32_e32 v135, v135
	v_exp_f32_e32 v136, v136
	v_exp_f32_e32 v137, v137
	v_pk_add_f32 v[130:131], v[130:131], 1.0 op_sel_hi:[1,0]
	v_pk_add_f32 v[132:133], v[132:133], 1.0 op_sel_hi:[1,0]
	v_pk_add_f32 v[134:135], v[134:135], 1.0 op_sel_hi:[1,0]
	v_pk_add_f32 v[136:137], v[136:137], 1.0 op_sel_hi:[1,0]
	v_rcp_f32_e32 v130, v130
	v_rcp_f32_e32 v131, v131
	v_rcp_f32_e32 v132, v132
	v_rcp_f32_e32 v133, v133
	v_rcp_f32_e32 v134, v134
	v_rcp_f32_e32 v135, v135
	v_rcp_f32_e32 v136, v136
	v_rcp_f32_e32 v137, v137
	v_pk_fma_f32 v[130:131], v[130:131], v[178:179], v[220:221]
	v_pk_fma_f32 v[132:133], v[132:133], v[180:181], v[222:223]
	v_pk_fma_f32 v[134:135], v[134:135], v[182:183], v[224:225]
	v_pk_fma_f32 v[136:137], v[136:137], v[184:185], v[226:227]
	v_cmp_gt_f32_e32 vcc, s80, v130
	v_cmp_gt_f32_e64 s[8:9], s80, v131
	v_cmp_gt_f32_e64 s[10:11], s80, v132
	v_cmp_gt_f32_e64 s[42:43], s80, v133
	v_cndmask_b32_e64 v138, 0, 32, vcc
	v_cndmask_b32_e64 v139, 0, 32, s[8:9]
	v_cndmask_b32_e64 v140, 0, 32, s[10:11]
	v_cndmask_b32_e64 v141, 0, 32, s[42:43]
	v_cndmask_b32_e64 v162, 0, v214, vcc
	v_cndmask_b32_e64 v163, 0, v214, s[8:9]
	v_cndmask_b32_e64 v196, 0, v214, s[10:11]
	v_cndmask_b32_e64 v197, 0, v214, s[42:43]
	v_cmp_gt_f32_e32 vcc, s80, v134
	v_cmp_gt_f32_e64 s[8:9], s80, v135
	v_cmp_gt_f32_e64 s[10:11], s80, v136
	v_cmp_gt_f32_e64 s[42:43], s80, v137
	v_cndmask_b32_e64 v142, 0, 32, vcc
	v_cndmask_b32_e64 v143, 0, 32, s[8:9]
	v_cndmask_b32_e64 v144, 0, 32, s[10:11]
	v_cndmask_b32_e64 v145, 0, 32, s[42:43]
	v_cndmask_b32_e64 v198, 0, v214, vcc
	v_cndmask_b32_e64 v199, 0, v214, s[8:9]
	v_cndmask_b32_e64 v204, 0, v214, s[10:11]
	v_cndmask_b32_e64 v205, 0, v214, s[42:43]
	v_ldexp_f32 v130, v130, v138
	v_ldexp_f32 v131, v131, v139
	v_ldexp_f32 v132, v132, v140
	v_ldexp_f32 v133, v133, v141
	v_ldexp_f32 v134, v134, v142
	v_ldexp_f32 v135, v135, v143
	v_ldexp_f32 v136, v136, v144
	v_ldexp_f32 v137, v137, v145
	v_log_f32_e32 v130, v130
	v_log_f32_e32 v131, v131
	v_log_f32_e32 v132, v132
	v_log_f32_e32 v133, v133
	v_log_f32_e32 v134, v134
	v_log_f32_e32 v135, v135
	v_log_f32_e32 v136, v136
	v_log_f32_e32 v137, v137
	v_mul_f32_e32 v138, 0x3f317217, v130
	v_mul_f32_e32 v139, 0x3f317217, v131
	v_mul_f32_e32 v140, 0x3f317217, v132
	v_mul_f32_e32 v141, 0x3f317217, v133
	v_mul_f32_e32 v142, 0x3f317217, v134
	v_mul_f32_e32 v143, 0x3f317217, v135
	v_mul_f32_e32 v144, 0x3f317217, v136
	v_mul_f32_e32 v145, 0x3f317217, v137
	v_fma_f32 v138, v130, s85, -v138
	v_fma_f32 v139, v131, s85, -v139
	v_fma_f32 v140, v132, s85, -v140
	v_fma_f32 v141, v133, s85, -v141
	v_fma_f32 v142, v134, s85, -v142
	v_fma_f32 v143, v135, s85, -v143
	v_fma_f32 v144, v136, s85, -v144
	v_fma_f32 v145, v137, s85, -v145
	v_fmac_f32_e32 v138, 0x3377d1cf, v130
	v_fmac_f32_e32 v139, 0x3377d1cf, v131
	v_fmac_f32_e32 v140, 0x3377d1cf, v132
	v_fmac_f32_e32 v141, 0x3377d1cf, v133
	v_fmac_f32_e32 v142, 0x3377d1cf, v134
	v_fmac_f32_e32 v143, 0x3377d1cf, v135
	v_fmac_f32_e32 v144, 0x3377d1cf, v136
	v_fmac_f32_e32 v145, 0x3377d1cf, v137
	v_fmac_f32_e32 v138, 0x3f317217, v130
	v_fmac_f32_e32 v139, 0x3f317217, v131
	v_fmac_f32_e32 v140, 0x3f317217, v132
	v_fmac_f32_e32 v141, 0x3f317217, v133
	v_fmac_f32_e32 v142, 0x3f317217, v134
	v_fmac_f32_e32 v143, 0x3f317217, v135
; template <int MODE> __device__ __forceinline__ void gemm_epilogue(f32x4 (&acc)[2][2][4][2], const GD& g, const pg8::Unit& u, int wr, int wc, int fr, int fq, LAS unsigned char* lds, const float (&rsv)[2][4]) {
;     ...
;             for (int ai = 0; ai < 2; ++ai)
; #pragma unroll
;                 for (int m = 0; m < 4; ++m) { float* rowp = LOGF + (size_t)(rt + ai * 128 + m * 16) * 1024 + col0;
; #pragma unroll
;                     for (int bj = 0; bj < 2; ++bj)
;                     {
; #pragma unroll
;                         for (int n = 0; n < 2; ++n) { f32x4 v = acc[ai][bj][m][n], o;
; #pragma unroll
;                             for (int j = 0; j < 4; ++j) { const float sg = 1.f / (1.f + __expf(-v[j])); const float f = lb[bj][n][j] + (1.f - lb[bj][n][j]) * sg; o[j] = __logf(f); }
;                             *(f32x4*)(rowp + bj * 128 + 4 * n) = o; } } }
	v_fmac_f32_e32 v144, 0x3f317217, v136
	v_fmac_f32_e32 v145, 0x3f317217, v137
	v_cmp_lt_f32_e64 vcc, |v130|, s55
	v_cmp_lt_f32_e64 s[8:9], |v131|, s55
	v_cmp_lt_f32_e64 s[10:11], |v132|, s55
	v_cmp_lt_f32_e64 s[42:43], |v133|, s55
	v_cndmask_b32_e64 v130, v130, v138, vcc
	v_cndmask_b32_e64 v131, v131, v139, s[8:9]
	v_cndmask_b32_e64 v132, v132, v140, s[10:11]
	v_cndmask_b32_e64 v133, v133, v141, s[42:43]
	v_cmp_lt_f32_e64 vcc, |v134|, s55
	v_cmp_lt_f32_e64 s[8:9], |v135|, s55
	v_cmp_lt_f32_e64 s[10:11], |v136|, s55
	v_cmp_lt_f32_e64 s[42:43], |v137|, s55
	v_cndmask_b32_e64 v134, v134, v142, vcc
	v_cndmask_b32_e64 v135, v135, v143, s[8:9]
	v_cndmask_b32_e64 v136, v136, v144, s[10:11]
	v_cndmask_b32_e64 v137, v137, v145, s[42:43]
	v_sub_f32_e32 v130, v130, v162
	v_sub_f32_e32 v131, v131, v163
	v_sub_f32_e32 v132, v132, v196
	v_sub_f32_e32 v133, v133, v197
	v_sub_f32_e32 v134, v134, v198
	v_sub_f32_e32 v135, v135, v199
	v_sub_f32_e32 v136, v136, v204
	v_sub_f32_e32 v137, v137, v205
	global_store_dwordx4 v159, v[130:133], s[2:3]
	global_store_dwordx4 v159, v[134:137], s[2:3] offset:16
	s_nop 0
	v_pk_mul_f32 v[130:131], v[102:103], v[160:161]
	v_pk_mul_f32 v[132:133], v[104:105], v[160:161]
	v_pk_mul_f32 v[134:135], v[98:99], v[160:161]
	v_pk_mul_f32 v[136:137], v[100:101], v[160:161]
	v_exp_f32_e32 v130, v130
	v_exp_f32_e32 v131, v131
	v_exp_f32_e32 v132, v132
	v_exp_f32_e32 v133, v133
	v_exp_f32_e32 v134, v134
	v_exp_f32_e32 v135, v135
	v_exp_f32_e32 v136, v136
	v_exp_f32_e32 v137, v137
	v_pk_add_f32 v[130:131], v[130:131], 1.0 op_sel_hi:[1,0]
	v_pk_add_f32 v[132:133], v[132:133], 1.0 op_sel_hi:[1,0]
	v_pk_add_f32 v[134:135], v[134:135], 1.0 op_sel_hi:[1,0]
	v_pk_add_f32 v[136:137], v[136:137], 1.0 op_sel_hi:[1,0]
	v_rcp_f32_e32 v130, v130
	v_rcp_f32_e32 v131, v131
	v_rcp_f32_e32 v132, v132
	v_rcp_f32_e32 v133, v133
	v_rcp_f32_e32 v134, v134
	v_rcp_f32_e32 v135, v135
	v_rcp_f32_e32 v136, v136
	v_rcp_f32_e32 v137, v137
	v_pk_fma_f32 v[130:131], v[130:131], v[186:187], v[228:229]
	v_pk_fma_f32 v[132:133], v[132:133], v[188:189], v[230:231]
	v_pk_fma_f32 v[134:135], v[134:135], v[190:191], v[232:233]
	v_pk_fma_f32 v[136:137], v[136:137], v[192:193], v[234:235]
	v_cmp_gt_f32_e32 vcc, s80, v130
	v_cmp_gt_f32_e64 s[8:9], s80, v131
	v_cmp_gt_f32_e64 s[10:11], s80, v132
	v_cmp_gt_f32_e64 s[42:43], s80, v133
	v_cndmask_b32_e64 v138, 0, 32, vcc
	v_cndmask_b32_e64 v139, 0, 32, s[8:9]
	v_cndmask_b32_e64 v140, 0, 32, s[10:11]
	v_cndmask_b32_e64 v141, 0, 32, s[42:43]
	v_cndmask_b32_e64 v162, 0, v214, vcc
	v_cndmask_b32_e64 v163, 0, v214, s[8:9]
	v_cndmask_b32_e64 v196, 0, v214, s[10:11]
	v_cndmask_b32_e64 v197, 0, v214, s[42:43]
	v_cmp_gt_f32_e32 vcc, s80, v134
	v_cmp_gt_f32_e64 s[8:9], s80, v135
	v_cmp_gt_f32_e64 s[10:11], s80, v136
	v_cmp_gt_f32_e64 s[42:43], s80, v137
	v_cndmask_b32_e64 v142, 0, 32, vcc
	v_cndmask_b32_e64 v143, 0, 32, s[8:9]
	v_cndmask_b32_e64 v144, 0, 32, s[10:11]
	v_cndmask_b32_e64 v145, 0, 32, s[42:43]
	v_cndmask_b32_e64 v198, 0, v214, vcc
	v_cndmask_b32_e64 v199, 0, v214, s[8:9]
	v_cndmask_b32_e64 v204, 0, v214, s[10:11]
	v_cndmask_b32_e64 v205, 0, v214, s[42:43]
	v_ldexp_f32 v130, v130, v138
	v_ldexp_f32 v131, v131, v139
	v_ldexp_f32 v132, v132, v140
	v_ldexp_f32 v133, v133, v141
	v_ldexp_f32 v134, v134, v142
	v_ldexp_f32 v135, v135, v143
	v_ldexp_f32 v136, v136, v144
	v_ldexp_f32 v137, v137, v145
	v_log_f32_e32 v130, v130
	v_log_f32_e32 v131, v131
	v_log_f32_e32 v132, v132
	v_log_f32_e32 v133, v133
	v_log_f32_e32 v134, v134
	v_log_f32_e32 v135, v135
	v_log_f32_e32 v136, v136
	v_log_f32_e32 v137, v137
	v_mul_f32_e32 v138, 0x3f317217, v130
	v_mul_f32_e32 v139, 0x3f317217, v131
	v_mul_f32_e32 v140, 0x3f317217, v132
	v_mul_f32_e32 v141, 0x3f317217, v133
	v_mul_f32_e32 v142, 0x3f317217, v134
	v_mul_f32_e32 v143, 0x3f317217, v135
	v_mul_f32_e32 v144, 0x3f317217, v136
	v_mul_f32_e32 v145, 0x3f317217, v137
	v_fma_f32 v138, v130, s85, -v138
	v_fma_f32 v139, v131, s85, -v139
	v_fma_f32 v140, v132, s85, -v140
	v_fma_f32 v141, v133, s85, -v141
	v_fma_f32 v142, v134, s85, -v142
	v_fma_f32 v143, v135, s85, -v143
	v_fma_f32 v144, v136, s85, -v144
	v_fma_f32 v145, v137, s85, -v145
	v_fmac_f32_e32 v138, 0x3377d1cf, v130
	v_fmac_f32_e32 v139, 0x3377d1cf, v131
	v_fmac_f32_e32 v140, 0x3377d1cf, v132
	v_fmac_f32_e32 v141, 0x3377d1cf, v133
	v_fmac_f32_e32 v142, 0x3377d1cf, v134
	v_fmac_f32_e32 v143, 0x3377d1cf, v135
	v_fmac_f32_e32 v144, 0x3377d1cf, v136
	v_fmac_f32_e32 v145, 0x3377d1cf, v137
	v_fmac_f32_e32 v138, 0x3f317217, v130
	v_fmac_f32_e32 v139, 0x3f317217, v131
	v_fmac_f32_e32 v140, 0x3f317217, v132
	v_fmac_f32_e32 v141, 0x3f317217, v133
	v_fmac_f32_e32 v142, 0x3f317217, v134
	v_fmac_f32_e32 v143, 0x3f317217, v135
	v_fmac_f32_e32 v144, 0x3f317217, v136
	v_fmac_f32_e32 v145, 0x3f317217, v137
	v_cmp_lt_f32_e64 vcc, |v130|, s55
	v_cmp_lt_f32_e64 s[8:9], |v131|, s55
	v_cmp_lt_f32_e64 s[10:11], |v132|, s55
	v_cmp_lt_f32_e64 s[42:43], |v133|, s55
	v_cndmask_b32_e64 v130, v130, v138, vcc
	v_cndmask_b32_e64 v131, v131, v139, s[8:9]
	v_cndmask_b32_e64 v132, v132, v140, s[10:11]
	v_cndmask_b32_e64 v133, v133, v141, s[42:43]
	v_cmp_lt_f32_e64 vcc, |v134|, s55
	v_cmp_lt_f32_e64 s[8:9], |v135|, s55
	v_cmp_lt_f32_e64 s[10:11], |v136|, s55
	v_cmp_lt_f32_e64 s[42:43], |v137|, s55
	v_cndmask_b32_e64 v134, v134, v142, vcc
	v_cndmask_b32_e64 v135, v135, v143, s[8:9]
	v_cndmask_b32_e64 v136, v136, v144, s[10:11]
	v_cndmask_b32_e64 v137, v137, v145, s[42:43]
	v_sub_f32_e32 v130, v130, v162
	v_sub_f32_e32 v131, v131, v163
	v_sub_f32_e32 v132, v132, v196
	v_sub_f32_e32 v133, v133, v197
	v_sub_f32_e32 v134, v134, v198
	v_sub_f32_e32 v135, v135, v199
; template <int MODE> __device__ __forceinline__ void gemm_epilogue(f32x4 (&acc)[2][2][4][2], const GD& g, const pg8::Unit& u, int wr, int wc, int fr, int fq, LAS unsigned char* lds, const float (&rsv)[2][4]) {
;     ...
;             for (int ai = 0; ai < 2; ++ai)
; #pragma unroll
;                 for (int m = 0; m < 4; ++m) { float* rowp = LOGF + (size_t)(rt + ai * 128 + m * 16) * 1024 + col0;
; #pragma unroll
;                     for (int bj = 0; bj < 2; ++bj)
;                     {
; #pragma unroll
;                         for (int n = 0; n < 2; ++n) { f32x4 v = acc[ai][bj][m][n], o;
; #pragma unroll
;                             for (int j = 0; j < 4; ++j) { const float sg = 1.f / (1.f + __expf(-v[j])); const float f = lb[bj][n][j] + (1.f - lb[bj][n][j]) * sg; o[j] = __logf(f); }
;                             *(f32x4*)(rowp + bj * 128 + 4 * n) = o; } } }
	v_sub_f32_e32 v136, v136, v204
	v_sub_f32_e32 v137, v137, v205
	global_store_dwordx4 v159, v[130:133], s[2:3] offset:512
	global_store_dwordx4 v159, v[134:137], s[2:3] offset:528
	s_nop 0
	v_add_u32_e32 v159, 0x10000, v159
	v_pk_mul_f32 v[130:131], v[94:95], v[160:161]
	v_pk_mul_f32 v[132:133], v[96:97], v[160:161]
	v_pk_mul_f32 v[134:135], v[90:91], v[160:161]
	v_pk_mul_f32 v[136:137], v[92:93], v[160:161]
	v_exp_f32_e32 v130, v130
	v_exp_f32_e32 v131, v131
	v_exp_f32_e32 v132, v132
	v_exp_f32_e32 v133, v133
	v_exp_f32_e32 v134, v134
	v_exp_f32_e32 v135, v135
	v_exp_f32_e32 v136, v136
	v_exp_f32_e32 v137, v137
	v_pk_add_f32 v[130:131], v[130:131], 1.0 op_sel_hi:[1,0]
	v_pk_add_f32 v[132:133], v[132:133], 1.0 op_sel_hi:[1,0]
	v_pk_add_f32 v[134:135], v[134:135], 1.0 op_sel_hi:[1,0]
	v_pk_add_f32 v[136:137], v[136:137], 1.0 op_sel_hi:[1,0]
	v_rcp_f32_e32 v130, v130
	v_rcp_f32_e32 v131, v131
	v_rcp_f32_e32 v132, v132
	v_rcp_f32_e32 v133, v133
	v_rcp_f32_e32 v134, v134
	v_rcp_f32_e32 v135, v135
	v_rcp_f32_e32 v136, v136
	v_rcp_f32_e32 v137, v137
	v_pk_fma_f32 v[130:131], v[130:131], v[178:179], v[220:221]
	v_pk_fma_f32 v[132:133], v[132:133], v[180:181], v[222:223]
	v_pk_fma_f32 v[134:135], v[134:135], v[182:183], v[224:225]
	v_pk_fma_f32 v[136:137], v[136:137], v[184:185], v[226:227]
	v_cmp_gt_f32_e32 vcc, s80, v130
	v_cmp_gt_f32_e64 s[8:9], s80, v131
	v_cmp_gt_f32_e64 s[10:11], s80, v132
	v_cmp_gt_f32_e64 s[42:43], s80, v133
	v_cndmask_b32_e64 v138, 0, 32, vcc
	v_cndmask_b32_e64 v139, 0, 32, s[8:9]
	v_cndmask_b32_e64 v140, 0, 32, s[10:11]
	v_cndmask_b32_e64 v141, 0, 32, s[42:43]
	v_cndmask_b32_e64 v162, 0, v214, vcc
	v_cndmask_b32_e64 v163, 0, v214, s[8:9]
	v_cndmask_b32_e64 v196, 0, v214, s[10:11]
	v_cndmask_b32_e64 v197, 0, v214, s[42:43]
	v_cmp_gt_f32_e32 vcc, s80, v134
	v_cmp_gt_f32_e64 s[8:9], s80, v135
	v_cmp_gt_f32_e64 s[10:11], s80, v136
	v_cmp_gt_f32_e64 s[42:43], s80, v137
	v_cndmask_b32_e64 v142, 0, 32, vcc
	v_cndmask_b32_e64 v143, 0, 32, s[8:9]
	v_cndmask_b32_e64 v144, 0, 32, s[10:11]
	v_cndmask_b32_e64 v145, 0, 32, s[42:43]
	v_cndmask_b32_e64 v198, 0, v214, vcc
	v_cndmask_b32_e64 v199, 0, v214, s[8:9]
	v_cndmask_b32_e64 v204, 0, v214, s[10:11]
	v_cndmask_b32_e64 v205, 0, v214, s[42:43]
	v_ldexp_f32 v130, v130, v138
	v_ldexp_f32 v131, v131, v139
	v_ldexp_f32 v132, v132, v140
	v_ldexp_f32 v133, v133, v141
	v_ldexp_f32 v134, v134, v142
	v_ldexp_f32 v135, v135, v143
	v_ldexp_f32 v136, v136, v144
	v_ldexp_f32 v137, v137, v145
	v_log_f32_e32 v130, v130
	v_log_f32_e32 v131, v131
	v_log_f32_e32 v132, v132
	v_log_f32_e32 v133, v133
	v_log_f32_e32 v134, v134
	v_log_f32_e32 v135, v135
	v_log_f32_e32 v136, v136
	v_log_f32_e32 v137, v137
	v_mul_f32_e32 v138, 0x3f317217, v130
	v_mul_f32_e32 v139, 0x3f317217, v131
	v_mul_f32_e32 v140, 0x3f317217, v132
	v_mul_f32_e32 v141, 0x3f317217, v133
	v_mul_f32_e32 v142, 0x3f317217, v134
	v_mul_f32_e32 v143, 0x3f317217, v135
	v_mul_f32_e32 v144, 0x3f317217, v136
	v_mul_f32_e32 v145, 0x3f317217, v137
	v_fma_f32 v138, v130, s85, -v138
	v_fma_f32 v139, v131, s85, -v139
	v_fma_f32 v140, v132, s85, -v140
	v_fma_f32 v141, v133, s85, -v141
	v_fma_f32 v142, v134, s85, -v142
	v_fma_f32 v143, v135, s85, -v143
	v_fma_f32 v144, v136, s85, -v144
	v_fma_f32 v145, v137, s85, -v145
	v_fmac_f32_e32 v138, 0x3377d1cf, v130
	v_fmac_f32_e32 v139, 0x3377d1cf, v131
	v_fmac_f32_e32 v140, 0x3377d1cf, v132
	v_fmac_f32_e32 v141, 0x3377d1cf, v133
	v_fmac_f32_e32 v142, 0x3377d1cf, v134
	v_fmac_f32_e32 v143, 0x3377d1cf, v135
	v_fmac_f32_e32 v144, 0x3377d1cf, v136
	v_fmac_f32_e32 v145, 0x3377d1cf, v137
	v_fmac_f32_e32 v138, 0x3f317217, v130
	v_fmac_f32_e32 v139, 0x3f317217, v131
	v_fmac_f32_e32 v140, 0x3f317217, v132
	v_fmac_f32_e32 v141, 0x3f317217, v133
	v_fmac_f32_e32 v142, 0x3f317217, v134
	v_fmac_f32_e32 v143, 0x3f317217, v135
	v_fmac_f32_e32 v144, 0x3f317217, v136
	v_fmac_f32_e32 v145, 0x3f317217, v137
	v_cmp_lt_f32_e64 vcc, |v130|, s55
	v_cmp_lt_f32_e64 s[8:9], |v131|, s55
	v_cmp_lt_f32_e64 s[10:11], |v132|, s55
	v_cmp_lt_f32_e64 s[42:43], |v133|, s55
	v_cndmask_b32_e64 v130, v130, v138, vcc
	v_cndmask_b32_e64 v131, v131, v139, s[8:9]
	v_cndmask_b32_e64 v132, v132, v140, s[10:11]
	v_cndmask_b32_e64 v133, v133, v141, s[42:43]
	v_cmp_lt_f32_e64 vcc, |v134|, s55
	v_cmp_lt_f32_e64 s[8:9], |v135|, s55
	v_cmp_lt_f32_e64 s[10:11], |v136|, s55
	v_cmp_lt_f32_e64 s[42:43], |v137|, s55
	v_cndmask_b32_e64 v134, v134, v142, vcc
	v_cndmask_b32_e64 v135, v135, v143, s[8:9]
	v_cndmask_b32_e64 v136, v136, v144, s[10:11]
	v_cndmask_b32_e64 v137, v137, v145, s[42:43]
	v_sub_f32_e32 v130, v130, v162
	v_sub_f32_e32 v131, v131, v163
	v_sub_f32_e32 v132, v132, v196
	v_sub_f32_e32 v133, v133, v197
	v_sub_f32_e32 v134, v134, v198
	v_sub_f32_e32 v135, v135, v199
	v_sub_f32_e32 v136, v136, v204
	v_sub_f32_e32 v137, v137, v205
	global_store_dwordx4 v159, v[130:133], s[2:3]
	global_store_dwordx4 v159, v[134:137], s[2:3] offset:16
	s_nop 0
	v_pk_mul_f32 v[130:131], v[86:87], v[160:161]
	v_pk_mul_f32 v[132:133], v[88:89], v[160:161]
	v_pk_mul_f32 v[134:135], v[82:83], v[160:161]
	v_pk_mul_f32 v[136:137], v[84:85], v[160:161]
	v_exp_f32_e32 v130, v130
	v_exp_f32_e32 v131, v131
	v_exp_f32_e32 v132, v132
	v_exp_f32_e32 v133, v133
	v_exp_f32_e32 v134, v134
	v_exp_f32_e32 v135, v135
	v_exp_f32_e32 v136, v136
	v_exp_f32_e32 v137, v137
	v_pk_add_f32 v[130:131], v[130:131], 1.0 op_sel_hi:[1,0]
	v_pk_add_f32 v[132:133], v[132:133], 1.0 op_sel_hi:[1,0]
	v_pk_add_f32 v[134:135], v[134:135], 1.0 op_sel_hi:[1,0]
	v_pk_add_f32 v[136:137], v[136:137], 1.0 op_sel_hi:[1,0]
	v_rcp_f32_e32 v130, v130
	v_rcp_f32_e32 v131, v131
	v_rcp_f32_e32 v132, v132
	v_rcp_f32_e32 v133, v133
; template <int MODE> __device__ __forceinline__ void gemm_epilogue(f32x4 (&acc)[2][2][4][2], const GD& g, const pg8::Unit& u, int wr, int wc, int fr, int fq, LAS unsigned char* lds, const float (&rsv)[2][4]) {
;     ...
;             for (int ai = 0; ai < 2; ++ai)
; #pragma unroll
;                 for (int m = 0; m < 4; ++m) { float* rowp = LOGF + (size_t)(rt + ai * 128 + m * 16) * 1024 + col0;
; #pragma unroll
;                     for (int bj = 0; bj < 2; ++bj)
;                     {
; #pragma unroll
;                         for (int n = 0; n < 2; ++n) { f32x4 v = acc[ai][bj][m][n], o;
; #pragma unroll
;                             for (int j = 0; j < 4; ++j) { const float sg = 1.f / (1.f + __expf(-v[j])); const float f = lb[bj][n][j] + (1.f - lb[bj][n][j]) * sg; o[j] = __logf(f); }
;                             *(f32x4*)(rowp + bj * 128 + 4 * n) = o; } } }
	v_rcp_f32_e32 v134, v134
	v_rcp_f32_e32 v135, v135
	v_rcp_f32_e32 v136, v136
	v_rcp_f32_e32 v137, v137
	v_pk_fma_f32 v[130:131], v[130:131], v[186:187], v[228:229]
	v_pk_fma_f32 v[132:133], v[132:133], v[188:189], v[230:231]
	v_pk_fma_f32 v[134:135], v[134:135], v[190:191], v[232:233]
	v_pk_fma_f32 v[136:137], v[136:137], v[192:193], v[234:235]
	v_cmp_gt_f32_e32 vcc, s80, v130
	v_cmp_gt_f32_e64 s[8:9], s80, v131
	v_cmp_gt_f32_e64 s[10:11], s80, v132
	v_cmp_gt_f32_e64 s[42:43], s80, v133
	v_cndmask_b32_e64 v138, 0, 32, vcc
	v_cndmask_b32_e64 v139, 0, 32, s[8:9]
	v_cndmask_b32_e64 v140, 0, 32, s[10:11]
	v_cndmask_b32_e64 v141, 0, 32, s[42:43]
	v_cndmask_b32_e64 v162, 0, v214, vcc
	v_cndmask_b32_e64 v163, 0, v214, s[8:9]
	v_cndmask_b32_e64 v196, 0, v214, s[10:11]
	v_cndmask_b32_e64 v197, 0, v214, s[42:43]
	v_cmp_gt_f32_e32 vcc, s80, v134
	v_cmp_gt_f32_e64 s[8:9], s80, v135
	v_cmp_gt_f32_e64 s[10:11], s80, v136
	v_cmp_gt_f32_e64 s[42:43], s80, v137
	v_cndmask_b32_e64 v142, 0, 32, vcc
	v_cndmask_b32_e64 v143, 0, 32, s[8:9]
	v_cndmask_b32_e64 v144, 0, 32, s[10:11]
	v_cndmask_b32_e64 v145, 0, 32, s[42:43]
	v_cndmask_b32_e64 v198, 0, v214, vcc
	v_cndmask_b32_e64 v199, 0, v214, s[8:9]
	v_cndmask_b32_e64 v204, 0, v214, s[10:11]
	v_cndmask_b32_e64 v205, 0, v214, s[42:43]
	v_ldexp_f32 v130, v130, v138
	v_ldexp_f32 v131, v131, v139
	v_ldexp_f32 v132, v132, v140
	v_ldexp_f32 v133, v133, v141
	v_ldexp_f32 v134, v134, v142
	v_ldexp_f32 v135, v135, v143
	v_ldexp_f32 v136, v136, v144
	v_ldexp_f32 v137, v137, v145
	v_log_f32_e32 v130, v130
	v_log_f32_e32 v131, v131
	v_log_f32_e32 v132, v132
	v_log_f32_e32 v133, v133
	v_log_f32_e32 v134, v134
	v_log_f32_e32 v135, v135
	v_log_f32_e32 v136, v136
	v_log_f32_e32 v137, v137
	v_mul_f32_e32 v138, 0x3f317217, v130
	v_mul_f32_e32 v139, 0x3f317217, v131
	v_mul_f32_e32 v140, 0x3f317217, v132
	v_mul_f32_e32 v141, 0x3f317217, v133
	v_mul_f32_e32 v142, 0x3f317217, v134
	v_mul_f32_e32 v143, 0x3f317217, v135
	v_mul_f32_e32 v144, 0x3f317217, v136
	v_mul_f32_e32 v145, 0x3f317217, v137
	v_fma_f32 v138, v130, s85, -v138
	v_fma_f32 v139, v131, s85, -v139
	v_fma_f32 v140, v132, s85, -v140
	v_fma_f32 v141, v133, s85, -v141
	v_fma_f32 v142, v134, s85, -v142
	v_fma_f32 v143, v135, s85, -v143
	v_fma_f32 v144, v136, s85, -v144
	v_fma_f32 v145, v137, s85, -v145
	v_fmac_f32_e32 v138, 0x3377d1cf, v130
	v_fmac_f32_e32 v139, 0x3377d1cf, v131
	v_fmac_f32_e32 v140, 0x3377d1cf, v132
	v_fmac_f32_e32 v141, 0x3377d1cf, v133
	v_fmac_f32_e32 v142, 0x3377d1cf, v134
	v_fmac_f32_e32 v143, 0x3377d1cf, v135
	v_fmac_f32_e32 v144, 0x3377d1cf, v136
	v_fmac_f32_e32 v145, 0x3377d1cf, v137
	v_fmac_f32_e32 v138, 0x3f317217, v130
	v_fmac_f32_e32 v139, 0x3f317217, v131
	v_fmac_f32_e32 v140, 0x3f317217, v132
	v_fmac_f32_e32 v141, 0x3f317217, v133
	v_fmac_f32_e32 v142, 0x3f317217, v134
	v_fmac_f32_e32 v143, 0x3f317217, v135
	v_fmac_f32_e32 v144, 0x3f317217, v136
	v_fmac_f32_e32 v145, 0x3f317217, v137
	v_cmp_lt_f32_e64 vcc, |v130|, s55
	v_cmp_lt_f32_e64 s[8:9], |v131|, s55
	v_cmp_lt_f32_e64 s[10:11], |v132|, s55
	v_cmp_lt_f32_e64 s[42:43], |v133|, s55
	v_cndmask_b32_e64 v130, v130, v138, vcc
	v_cndmask_b32_e64 v131, v131, v139, s[8:9]
	v_cndmask_b32_e64 v132, v132, v140, s[10:11]
	v_cndmask_b32_e64 v133, v133, v141, s[42:43]
	v_cmp_lt_f32_e64 vcc, |v134|, s55
	v_cmp_lt_f32_e64 s[8:9], |v135|, s55
	v_cmp_lt_f32_e64 s[10:11], |v136|, s55
	v_cmp_lt_f32_e64 s[42:43], |v137|, s55
	v_cndmask_b32_e64 v134, v134, v142, vcc
	v_cndmask_b32_e64 v135, v135, v143, s[8:9]
	v_cndmask_b32_e64 v136, v136, v144, s[10:11]
	v_cndmask_b32_e64 v137, v137, v145, s[42:43]
	v_sub_f32_e32 v130, v130, v162
	v_sub_f32_e32 v131, v131, v163
	v_sub_f32_e32 v132, v132, v196
	v_sub_f32_e32 v133, v133, v197
	v_sub_f32_e32 v134, v134, v198
	v_sub_f32_e32 v135, v135, v199
	v_sub_f32_e32 v136, v136, v204
	v_sub_f32_e32 v137, v137, v205
	global_store_dwordx4 v159, v[130:133], s[2:3] offset:512
	global_store_dwordx4 v159, v[134:137], s[2:3] offset:528
	s_nop 0
	v_add_u32_e32 v159, 0x10000, v159
	v_pk_mul_f32 v[130:131], v[78:79], v[160:161]
	v_pk_mul_f32 v[132:133], v[80:81], v[160:161]
	v_pk_mul_f32 v[134:135], v[74:75], v[160:161]
	v_pk_mul_f32 v[136:137], v[76:77], v[160:161]
	v_exp_f32_e32 v130, v130
	v_exp_f32_e32 v131, v131
	v_exp_f32_e32 v132, v132
	v_exp_f32_e32 v133, v133
	v_exp_f32_e32 v134, v134
	v_exp_f32_e32 v135, v135
	v_exp_f32_e32 v136, v136
	v_exp_f32_e32 v137, v137
	v_pk_add_f32 v[130:131], v[130:131], 1.0 op_sel_hi:[1,0]
	v_pk_add_f32 v[132:133], v[132:133], 1.0 op_sel_hi:[1,0]
	v_pk_add_f32 v[134:135], v[134:135], 1.0 op_sel_hi:[1,0]
	v_pk_add_f32 v[136:137], v[136:137], 1.0 op_sel_hi:[1,0]
	v_rcp_f32_e32 v130, v130
	v_rcp_f32_e32 v131, v131
	v_rcp_f32_e32 v132, v132
	v_rcp_f32_e32 v133, v133
	v_rcp_f32_e32 v134, v134
	v_rcp_f32_e32 v135, v135
	v_rcp_f32_e32 v136, v136
	v_rcp_f32_e32 v137, v137
	v_pk_fma_f32 v[130:131], v[130:131], v[178:179], v[220:221]
	v_pk_fma_f32 v[132:133], v[132:133], v[180:181], v[222:223]
	v_pk_fma_f32 v[134:135], v[134:135], v[182:183], v[224:225]
	v_pk_fma_f32 v[136:137], v[136:137], v[184:185], v[226:227]
	v_cmp_gt_f32_e32 vcc, s80, v130
	v_cmp_gt_f32_e64 s[8:9], s80, v131
	v_cmp_gt_f32_e64 s[10:11], s80, v132
	v_cmp_gt_f32_e64 s[42:43], s80, v133
	v_cndmask_b32_e64 v138, 0, 32, vcc
	v_cndmask_b32_e64 v139, 0, 32, s[8:9]
	v_cndmask_b32_e64 v140, 0, 32, s[10:11]
	v_cndmask_b32_e64 v141, 0, 32, s[42:43]
	v_cndmask_b32_e64 v162, 0, v214, vcc
	v_cndmask_b32_e64 v163, 0, v214, s[8:9]
	v_cndmask_b32_e64 v196, 0, v214, s[10:11]
	v_cndmask_b32_e64 v197, 0, v214, s[42:43]
	v_cmp_gt_f32_e32 vcc, s80, v134
	v_cmp_gt_f32_e64 s[8:9], s80, v135
; template <int MODE> __device__ __forceinline__ void gemm_epilogue(f32x4 (&acc)[2][2][4][2], const GD& g, const pg8::Unit& u, int wr, int wc, int fr, int fq, LAS unsigned char* lds, const float (&rsv)[2][4]) {
;     ...
;             for (int ai = 0; ai < 2; ++ai)
; #pragma unroll
;                 for (int m = 0; m < 4; ++m) { float* rowp = LOGF + (size_t)(rt + ai * 128 + m * 16) * 1024 + col0;
; #pragma unroll
;                     for (int bj = 0; bj < 2; ++bj)
;                     {
; #pragma unroll
;                         for (int n = 0; n < 2; ++n) { f32x4 v = acc[ai][bj][m][n], o;
; #pragma unroll
;                             for (int j = 0; j < 4; ++j) { const float sg = 1.f / (1.f + __expf(-v[j])); const float f = lb[bj][n][j] + (1.f - lb[bj][n][j]) * sg; o[j] = __logf(f); }
;                             *(f32x4*)(rowp + bj * 128 + 4 * n) = o; } } }
	v_cmp_gt_f32_e64 s[10:11], s80, v136
	v_cmp_gt_f32_e64 s[42:43], s80, v137
	v_cndmask_b32_e64 v142, 0, 32, vcc
	v_cndmask_b32_e64 v143, 0, 32, s[8:9]
	v_cndmask_b32_e64 v144, 0, 32, s[10:11]
	v_cndmask_b32_e64 v145, 0, 32, s[42:43]
	v_cndmask_b32_e64 v198, 0, v214, vcc
	v_cndmask_b32_e64 v199, 0, v214, s[8:9]
	v_cndmask_b32_e64 v204, 0, v214, s[10:11]
	v_cndmask_b32_e64 v205, 0, v214, s[42:43]
	v_ldexp_f32 v130, v130, v138
	v_ldexp_f32 v131, v131, v139
	v_ldexp_f32 v132, v132, v140
	v_ldexp_f32 v133, v133, v141
	v_ldexp_f32 v134, v134, v142
	v_ldexp_f32 v135, v135, v143
	v_ldexp_f32 v136, v136, v144
	v_ldexp_f32 v137, v137, v145
	v_log_f32_e32 v130, v130
	v_log_f32_e32 v131, v131
	v_log_f32_e32 v132, v132
	v_log_f32_e32 v133, v133
	v_log_f32_e32 v134, v134
	v_log_f32_e32 v135, v135
	v_log_f32_e32 v136, v136
	v_log_f32_e32 v137, v137
	v_mul_f32_e32 v138, 0x3f317217, v130
	v_mul_f32_e32 v139, 0x3f317217, v131
	v_mul_f32_e32 v140, 0x3f317217, v132
	v_mul_f32_e32 v141, 0x3f317217, v133
	v_mul_f32_e32 v142, 0x3f317217, v134
	v_mul_f32_e32 v143, 0x3f317217, v135
	v_mul_f32_e32 v144, 0x3f317217, v136
	v_mul_f32_e32 v145, 0x3f317217, v137
	v_fma_f32 v138, v130, s85, -v138
	v_fma_f32 v139, v131, s85, -v139
	v_fma_f32 v140, v132, s85, -v140
	v_fma_f32 v141, v133, s85, -v141
	v_fma_f32 v142, v134, s85, -v142
	v_fma_f32 v143, v135, s85, -v143
	v_fma_f32 v144, v136, s85, -v144
	v_fma_f32 v145, v137, s85, -v145
	v_fmac_f32_e32 v138, 0x3377d1cf, v130
	v_fmac_f32_e32 v139, 0x3377d1cf, v131
	v_fmac_f32_e32 v140, 0x3377d1cf, v132
	v_fmac_f32_e32 v141, 0x3377d1cf, v133
	v_fmac_f32_e32 v142, 0x3377d1cf, v134
	v_fmac_f32_e32 v143, 0x3377d1cf, v135
	v_fmac_f32_e32 v144, 0x3377d1cf, v136
	v_fmac_f32_e32 v145, 0x3377d1cf, v137
	v_fmac_f32_e32 v138, 0x3f317217, v130
	v_fmac_f32_e32 v139, 0x3f317217, v131
	v_fmac_f32_e32 v140, 0x3f317217, v132
	v_fmac_f32_e32 v141, 0x3f317217, v133
	v_fmac_f32_e32 v142, 0x3f317217, v134
	v_fmac_f32_e32 v143, 0x3f317217, v135
	v_fmac_f32_e32 v144, 0x3f317217, v136
	v_fmac_f32_e32 v145, 0x3f317217, v137
	v_cmp_lt_f32_e64 vcc, |v130|, s55
	v_cmp_lt_f32_e64 s[8:9], |v131|, s55
	v_cmp_lt_f32_e64 s[10:11], |v132|, s55
	v_cmp_lt_f32_e64 s[42:43], |v133|, s55
	v_cndmask_b32_e64 v130, v130, v138, vcc
	v_cndmask_b32_e64 v131, v131, v139, s[8:9]
	v_cndmask_b32_e64 v132, v132, v140, s[10:11]
	v_cndmask_b32_e64 v133, v133, v141, s[42:43]
	v_cmp_lt_f32_e64 vcc, |v134|, s55
	v_cmp_lt_f32_e64 s[8:9], |v135|, s55
	v_cmp_lt_f32_e64 s[10:11], |v136|, s55
	v_cmp_lt_f32_e64 s[42:43], |v137|, s55
	v_cndmask_b32_e64 v134, v134, v142, vcc
	v_cndmask_b32_e64 v135, v135, v143, s[8:9]
	v_cndmask_b32_e64 v136, v136, v144, s[10:11]
	v_cndmask_b32_e64 v137, v137, v145, s[42:43]
	v_sub_f32_e32 v130, v130, v162
	v_sub_f32_e32 v131, v131, v163
	v_sub_f32_e32 v132, v132, v196
	v_sub_f32_e32 v133, v133, v197
	v_sub_f32_e32 v134, v134, v198
	v_sub_f32_e32 v135, v135, v199
	v_sub_f32_e32 v136, v136, v204
	v_sub_f32_e32 v137, v137, v205
	global_store_dwordx4 v159, v[130:133], s[2:3]
	global_store_dwordx4 v159, v[134:137], s[2:3] offset:16
	s_nop 0
	v_pk_mul_f32 v[130:131], v[70:71], v[160:161]
	v_pk_mul_f32 v[132:133], v[72:73], v[160:161]
	v_pk_mul_f32 v[134:135], v[66:67], v[160:161]
	v_pk_mul_f32 v[136:137], v[68:69], v[160:161]
	v_exp_f32_e32 v130, v130
	v_exp_f32_e32 v131, v131
	v_exp_f32_e32 v132, v132
	v_exp_f32_e32 v133, v133
	v_exp_f32_e32 v134, v134
	v_exp_f32_e32 v135, v135
	v_exp_f32_e32 v136, v136
	v_exp_f32_e32 v137, v137
	v_pk_add_f32 v[130:131], v[130:131], 1.0 op_sel_hi:[1,0]
	v_pk_add_f32 v[132:133], v[132:133], 1.0 op_sel_hi:[1,0]
	v_pk_add_f32 v[134:135], v[134:135], 1.0 op_sel_hi:[1,0]
	v_pk_add_f32 v[136:137], v[136:137], 1.0 op_sel_hi:[1,0]
	v_rcp_f32_e32 v130, v130
	v_rcp_f32_e32 v131, v131
	v_rcp_f32_e32 v132, v132
	v_rcp_f32_e32 v133, v133
	v_rcp_f32_e32 v134, v134
	v_rcp_f32_e32 v135, v135
	v_rcp_f32_e32 v136, v136
	v_rcp_f32_e32 v137, v137
	v_pk_fma_f32 v[130:131], v[130:131], v[186:187], v[228:229]
	v_pk_fma_f32 v[132:133], v[132:133], v[188:189], v[230:231]
	v_pk_fma_f32 v[134:135], v[134:135], v[190:191], v[232:233]
	v_pk_fma_f32 v[136:137], v[136:137], v[192:193], v[234:235]
	v_cmp_gt_f32_e32 vcc, s80, v130
	v_cmp_gt_f32_e64 s[8:9], s80, v131
	v_cmp_gt_f32_e64 s[10:11], s80, v132
	v_cmp_gt_f32_e64 s[42:43], s80, v133
	v_cndmask_b32_e64 v138, 0, 32, vcc
	v_cndmask_b32_e64 v139, 0, 32, s[8:9]
	v_cndmask_b32_e64 v140, 0, 32, s[10:11]
	v_cndmask_b32_e64 v141, 0, 32, s[42:43]
	v_cndmask_b32_e64 v162, 0, v214, vcc
	v_cndmask_b32_e64 v163, 0, v214, s[8:9]
	v_cndmask_b32_e64 v196, 0, v214, s[10:11]
	v_cndmask_b32_e64 v197, 0, v214, s[42:43]
	v_cmp_gt_f32_e32 vcc, s80, v134
	v_cmp_gt_f32_e64 s[8:9], s80, v135
	v_cmp_gt_f32_e64 s[10:11], s80, v136
	v_cmp_gt_f32_e64 s[42:43], s80, v137
	v_cndmask_b32_e64 v142, 0, 32, vcc
	v_cndmask_b32_e64 v143, 0, 32, s[8:9]
	v_cndmask_b32_e64 v144, 0, 32, s[10:11]
	v_cndmask_b32_e64 v145, 0, 32, s[42:43]
	v_cndmask_b32_e64 v198, 0, v214, vcc
	v_cndmask_b32_e64 v199, 0, v214, s[8:9]
	v_cndmask_b32_e64 v204, 0, v214, s[10:11]
	v_cndmask_b32_e64 v205, 0, v214, s[42:43]
	v_ldexp_f32 v130, v130, v138
	v_ldexp_f32 v131, v131, v139
	v_ldexp_f32 v132, v132, v140
	v_ldexp_f32 v133, v133, v141
	v_ldexp_f32 v134, v134, v142
	v_ldexp_f32 v135, v135, v143
	v_ldexp_f32 v136, v136, v144
	v_ldexp_f32 v137, v137, v145
	v_log_f32_e32 v130, v130
	v_log_f32_e32 v131, v131
	v_log_f32_e32 v132, v132
	v_log_f32_e32 v133, v133
	v_log_f32_e32 v134, v134
	v_log_f32_e32 v135, v135
	v_log_f32_e32 v136, v136
	v_log_f32_e32 v137, v137
	v_mul_f32_e32 v138, 0x3f317217, v130
	v_mul_f32_e32 v139, 0x3f317217, v131
	v_mul_f32_e32 v140, 0x3f317217, v132
; template <int MODE> __device__ __forceinline__ void gemm_epilogue(f32x4 (&acc)[2][2][4][2], const GD& g, const pg8::Unit& u, int wr, int wc, int fr, int fq, LAS unsigned char* lds, const float (&rsv)[2][4]) {
;     ...
;             for (int ai = 0; ai < 2; ++ai)
; #pragma unroll
;                 for (int m = 0; m < 4; ++m) { float* rowp = LOGF + (size_t)(rt + ai * 128 + m * 16) * 1024 + col0;
; #pragma unroll
;                     for (int bj = 0; bj < 2; ++bj)
;                     {
; #pragma unroll
;                         for (int n = 0; n < 2; ++n) { f32x4 v = acc[ai][bj][m][n], o;
; #pragma unroll
;                             for (int j = 0; j < 4; ++j) { const float sg = 1.f / (1.f + __expf(-v[j])); const float f = lb[bj][n][j] + (1.f - lb[bj][n][j]) * sg; o[j] = __logf(f); }
;                             *(f32x4*)(rowp + bj * 128 + 4 * n) = o; } } }
	v_mul_f32_e32 v141, 0x3f317217, v133
	v_mul_f32_e32 v142, 0x3f317217, v134
	v_mul_f32_e32 v143, 0x3f317217, v135
	v_mul_f32_e32 v144, 0x3f317217, v136
	v_mul_f32_e32 v145, 0x3f317217, v137
	v_fma_f32 v138, v130, s85, -v138
	v_fma_f32 v139, v131, s85, -v139
	v_fma_f32 v140, v132, s85, -v140
	v_fma_f32 v141, v133, s85, -v141
	v_fma_f32 v142, v134, s85, -v142
	v_fma_f32 v143, v135, s85, -v143
	v_fma_f32 v144, v136, s85, -v144
	v_fma_f32 v145, v137, s85, -v145
	v_fmac_f32_e32 v138, 0x3377d1cf, v130
	v_fmac_f32_e32 v139, 0x3377d1cf, v131
	v_fmac_f32_e32 v140, 0x3377d1cf, v132
	v_fmac_f32_e32 v141, 0x3377d1cf, v133
	v_fmac_f32_e32 v142, 0x3377d1cf, v134
	v_fmac_f32_e32 v143, 0x3377d1cf, v135
	v_fmac_f32_e32 v144, 0x3377d1cf, v136
	v_fmac_f32_e32 v145, 0x3377d1cf, v137
	v_fmac_f32_e32 v138, 0x3f317217, v130
	v_fmac_f32_e32 v139, 0x3f317217, v131
	v_fmac_f32_e32 v140, 0x3f317217, v132
	v_fmac_f32_e32 v141, 0x3f317217, v133
	v_fmac_f32_e32 v142, 0x3f317217, v134
	v_fmac_f32_e32 v143, 0x3f317217, v135
	v_fmac_f32_e32 v144, 0x3f317217, v136
	v_fmac_f32_e32 v145, 0x3f317217, v137
	v_cmp_lt_f32_e64 vcc, |v130|, s55
	v_cmp_lt_f32_e64 s[8:9], |v131|, s55
	v_cmp_lt_f32_e64 s[10:11], |v132|, s55
	v_cmp_lt_f32_e64 s[42:43], |v133|, s55
	v_cndmask_b32_e64 v130, v130, v138, vcc
	v_cndmask_b32_e64 v131, v131, v139, s[8:9]
	v_cndmask_b32_e64 v132, v132, v140, s[10:11]
	v_cndmask_b32_e64 v133, v133, v141, s[42:43]
	v_cmp_lt_f32_e64 vcc, |v134|, s55
	v_cmp_lt_f32_e64 s[8:9], |v135|, s55
	v_cmp_lt_f32_e64 s[10:11], |v136|, s55
	v_cmp_lt_f32_e64 s[42:43], |v137|, s55
	v_cndmask_b32_e64 v134, v134, v142, vcc
	v_cndmask_b32_e64 v135, v135, v143, s[8:9]
	v_cndmask_b32_e64 v136, v136, v144, s[10:11]
	v_cndmask_b32_e64 v137, v137, v145, s[42:43]
	v_sub_f32_e32 v130, v130, v162
	v_sub_f32_e32 v131, v131, v163
	v_sub_f32_e32 v132, v132, v196
	v_sub_f32_e32 v133, v133, v197
	v_sub_f32_e32 v134, v134, v198
	v_sub_f32_e32 v135, v135, v199
	v_sub_f32_e32 v136, v136, v204
	v_sub_f32_e32 v137, v137, v205
	global_store_dwordx4 v159, v[130:133], s[2:3] offset:512
	global_store_dwordx4 v159, v[134:137], s[2:3] offset:528
	s_nop 0
	v_add_u32_e32 v159, 0x50000, v159
	v_pk_mul_f32 v[130:131], v[62:63], v[160:161]
	v_pk_mul_f32 v[132:133], v[64:65], v[160:161]
	v_pk_mul_f32 v[134:135], v[58:59], v[160:161]
	v_pk_mul_f32 v[136:137], v[60:61], v[160:161]
	v_exp_f32_e32 v130, v130
	v_exp_f32_e32 v131, v131
	v_exp_f32_e32 v132, v132
	v_exp_f32_e32 v133, v133
	v_exp_f32_e32 v134, v134
	v_exp_f32_e32 v135, v135
	v_exp_f32_e32 v136, v136
	v_exp_f32_e32 v137, v137
	v_pk_add_f32 v[130:131], v[130:131], 1.0 op_sel_hi:[1,0]
	v_pk_add_f32 v[132:133], v[132:133], 1.0 op_sel_hi:[1,0]
	v_pk_add_f32 v[134:135], v[134:135], 1.0 op_sel_hi:[1,0]
	v_pk_add_f32 v[136:137], v[136:137], 1.0 op_sel_hi:[1,0]
	v_rcp_f32_e32 v130, v130
	v_rcp_f32_e32 v131, v131
	v_rcp_f32_e32 v132, v132
	v_rcp_f32_e32 v133, v133
	v_rcp_f32_e32 v134, v134
	v_rcp_f32_e32 v135, v135
	v_rcp_f32_e32 v136, v136
	v_rcp_f32_e32 v137, v137
	v_pk_fma_f32 v[130:131], v[130:131], v[178:179], v[220:221]
	v_pk_fma_f32 v[132:133], v[132:133], v[180:181], v[222:223]
	v_pk_fma_f32 v[134:135], v[134:135], v[182:183], v[224:225]
	v_pk_fma_f32 v[136:137], v[136:137], v[184:185], v[226:227]
	v_cmp_gt_f32_e32 vcc, s80, v130
	v_cmp_gt_f32_e64 s[8:9], s80, v131
	v_cmp_gt_f32_e64 s[10:11], s80, v132
	v_cmp_gt_f32_e64 s[42:43], s80, v133
	v_cndmask_b32_e64 v138, 0, 32, vcc
	v_cndmask_b32_e64 v139, 0, 32, s[8:9]
	v_cndmask_b32_e64 v140, 0, 32, s[10:11]
	v_cndmask_b32_e64 v141, 0, 32, s[42:43]
	v_cndmask_b32_e64 v162, 0, v214, vcc
	v_cndmask_b32_e64 v163, 0, v214, s[8:9]
	v_cndmask_b32_e64 v196, 0, v214, s[10:11]
	v_cndmask_b32_e64 v197, 0, v214, s[42:43]
	v_cmp_gt_f32_e32 vcc, s80, v134
	v_cmp_gt_f32_e64 s[8:9], s80, v135
	v_cmp_gt_f32_e64 s[10:11], s80, v136
	v_cmp_gt_f32_e64 s[42:43], s80, v137
	v_cndmask_b32_e64 v142, 0, 32, vcc
	v_cndmask_b32_e64 v143, 0, 32, s[8:9]
	v_cndmask_b32_e64 v144, 0, 32, s[10:11]
	v_cndmask_b32_e64 v145, 0, 32, s[42:43]
	v_cndmask_b32_e64 v198, 0, v214, vcc
	v_cndmask_b32_e64 v199, 0, v214, s[8:9]
	v_cndmask_b32_e64 v204, 0, v214, s[10:11]
	v_cndmask_b32_e64 v205, 0, v214, s[42:43]
	v_ldexp_f32 v130, v130, v138
	v_ldexp_f32 v131, v131, v139
	v_ldexp_f32 v132, v132, v140
	v_ldexp_f32 v133, v133, v141
	v_ldexp_f32 v134, v134, v142
	v_ldexp_f32 v135, v135, v143
	v_ldexp_f32 v136, v136, v144
	v_ldexp_f32 v137, v137, v145
	v_log_f32_e32 v130, v130
	v_log_f32_e32 v131, v131
	v_log_f32_e32 v132, v132
	v_log_f32_e32 v133, v133
	v_log_f32_e32 v134, v134
	v_log_f32_e32 v135, v135
	v_log_f32_e32 v136, v136
	v_log_f32_e32 v137, v137
	v_mul_f32_e32 v138, 0x3f317217, v130
	v_mul_f32_e32 v139, 0x3f317217, v131
	v_mul_f32_e32 v140, 0x3f317217, v132
	v_mul_f32_e32 v141, 0x3f317217, v133
	v_mul_f32_e32 v142, 0x3f317217, v134
	v_mul_f32_e32 v143, 0x3f317217, v135
	v_mul_f32_e32 v144, 0x3f317217, v136
	v_mul_f32_e32 v145, 0x3f317217, v137
	v_fma_f32 v138, v130, s85, -v138
	v_fma_f32 v139, v131, s85, -v139
	v_fma_f32 v140, v132, s85, -v140
	v_fma_f32 v141, v133, s85, -v141
	v_fma_f32 v142, v134, s85, -v142
	v_fma_f32 v143, v135, s85, -v143
	v_fma_f32 v144, v136, s85, -v144
	v_fma_f32 v145, v137, s85, -v145
	v_fmac_f32_e32 v138, 0x3377d1cf, v130
	v_fmac_f32_e32 v139, 0x3377d1cf, v131
	v_fmac_f32_e32 v140, 0x3377d1cf, v132
	v_fmac_f32_e32 v141, 0x3377d1cf, v133
	v_fmac_f32_e32 v142, 0x3377d1cf, v134
	v_fmac_f32_e32 v143, 0x3377d1cf, v135
	v_fmac_f32_e32 v144, 0x3377d1cf, v136
	v_fmac_f32_e32 v145, 0x3377d1cf, v137
	v_fmac_f32_e32 v138, 0x3f317217, v130
	v_fmac_f32_e32 v139, 0x3f317217, v131
	v_fmac_f32_e32 v140, 0x3f317217, v132
; template <int MODE> __device__ __forceinline__ void gemm_epilogue(f32x4 (&acc)[2][2][4][2], const GD& g, const pg8::Unit& u, int wr, int wc, int fr, int fq, LAS unsigned char* lds, const float (&rsv)[2][4]) {
;     ...
;             for (int ai = 0; ai < 2; ++ai)
; #pragma unroll
;                 for (int m = 0; m < 4; ++m) { float* rowp = LOGF + (size_t)(rt + ai * 128 + m * 16) * 1024 + col0;
; #pragma unroll
;                     for (int bj = 0; bj < 2; ++bj)
;                     {
; #pragma unroll
;                         for (int n = 0; n < 2; ++n) { f32x4 v = acc[ai][bj][m][n], o;
; #pragma unroll
;                             for (int j = 0; j < 4; ++j) { const float sg = 1.f / (1.f + __expf(-v[j])); const float f = lb[bj][n][j] + (1.f - lb[bj][n][j]) * sg; o[j] = __logf(f); }
;                             *(f32x4*)(rowp + bj * 128 + 4 * n) = o; } } }
	v_fmac_f32_e32 v141, 0x3f317217, v133
	v_fmac_f32_e32 v142, 0x3f317217, v134
	v_fmac_f32_e32 v143, 0x3f317217, v135
	v_fmac_f32_e32 v144, 0x3f317217, v136
	v_fmac_f32_e32 v145, 0x3f317217, v137
	v_cmp_lt_f32_e64 vcc, |v130|, s55
	v_cmp_lt_f32_e64 s[8:9], |v131|, s55
	v_cmp_lt_f32_e64 s[10:11], |v132|, s55
	v_cmp_lt_f32_e64 s[42:43], |v133|, s55
	v_cndmask_b32_e64 v130, v130, v138, vcc
	v_cndmask_b32_e64 v131, v131, v139, s[8:9]
	v_cndmask_b32_e64 v132, v132, v140, s[10:11]
	v_cndmask_b32_e64 v133, v133, v141, s[42:43]
	v_cmp_lt_f32_e64 vcc, |v134|, s55
	v_cmp_lt_f32_e64 s[8:9], |v135|, s55
	v_cmp_lt_f32_e64 s[10:11], |v136|, s55
	v_cmp_lt_f32_e64 s[42:43], |v137|, s55
	v_cndmask_b32_e64 v134, v134, v142, vcc
	v_cndmask_b32_e64 v135, v135, v143, s[8:9]
	v_cndmask_b32_e64 v136, v136, v144, s[10:11]
	v_cndmask_b32_e64 v137, v137, v145, s[42:43]
	v_sub_f32_e32 v130, v130, v162
	v_sub_f32_e32 v131, v131, v163
	v_sub_f32_e32 v132, v132, v196
	v_sub_f32_e32 v133, v133, v197
	v_sub_f32_e32 v134, v134, v198
	v_sub_f32_e32 v135, v135, v199
	v_sub_f32_e32 v136, v136, v204
	v_sub_f32_e32 v137, v137, v205
	global_store_dwordx4 v159, v[130:133], s[2:3]
	global_store_dwordx4 v159, v[134:137], s[2:3] offset:16
	s_nop 0
	v_pk_mul_f32 v[130:131], v[54:55], v[160:161]
	v_pk_mul_f32 v[132:133], v[56:57], v[160:161]
	v_pk_mul_f32 v[134:135], v[50:51], v[160:161]
	v_pk_mul_f32 v[136:137], v[52:53], v[160:161]
	v_exp_f32_e32 v130, v130
	v_exp_f32_e32 v131, v131
	v_exp_f32_e32 v132, v132
	v_exp_f32_e32 v133, v133
	v_exp_f32_e32 v134, v134
	v_exp_f32_e32 v135, v135
	v_exp_f32_e32 v136, v136
	v_exp_f32_e32 v137, v137
	v_pk_add_f32 v[130:131], v[130:131], 1.0 op_sel_hi:[1,0]
	v_pk_add_f32 v[132:133], v[132:133], 1.0 op_sel_hi:[1,0]
	v_pk_add_f32 v[134:135], v[134:135], 1.0 op_sel_hi:[1,0]
	v_pk_add_f32 v[136:137], v[136:137], 1.0 op_sel_hi:[1,0]
	v_rcp_f32_e32 v130, v130
	v_rcp_f32_e32 v131, v131
	v_rcp_f32_e32 v132, v132
	v_rcp_f32_e32 v133, v133
	v_rcp_f32_e32 v134, v134
	v_rcp_f32_e32 v135, v135
	v_rcp_f32_e32 v136, v136
	v_rcp_f32_e32 v137, v137
	v_pk_fma_f32 v[130:131], v[130:131], v[186:187], v[228:229]
	v_pk_fma_f32 v[132:133], v[132:133], v[188:189], v[230:231]
	v_pk_fma_f32 v[134:135], v[134:135], v[190:191], v[232:233]
	v_pk_fma_f32 v[136:137], v[136:137], v[192:193], v[234:235]
	v_cmp_gt_f32_e32 vcc, s80, v130
	v_cmp_gt_f32_e64 s[8:9], s80, v131
	v_cmp_gt_f32_e64 s[10:11], s80, v132
	v_cmp_gt_f32_e64 s[42:43], s80, v133
	v_cndmask_b32_e64 v138, 0, 32, vcc
	v_cndmask_b32_e64 v139, 0, 32, s[8:9]
	v_cndmask_b32_e64 v140, 0, 32, s[10:11]
	v_cndmask_b32_e64 v141, 0, 32, s[42:43]
	v_cndmask_b32_e64 v162, 0, v214, vcc
	v_cndmask_b32_e64 v163, 0, v214, s[8:9]
	v_cndmask_b32_e64 v196, 0, v214, s[10:11]
	v_cndmask_b32_e64 v197, 0, v214, s[42:43]
	v_cmp_gt_f32_e32 vcc, s80, v134
	v_cmp_gt_f32_e64 s[8:9], s80, v135
	v_cmp_gt_f32_e64 s[10:11], s80, v136
	v_cmp_gt_f32_e64 s[42:43], s80, v137
	v_cndmask_b32_e64 v142, 0, 32, vcc
	v_cndmask_b32_e64 v143, 0, 32, s[8:9]
	v_cndmask_b32_e64 v144, 0, 32, s[10:11]
	v_cndmask_b32_e64 v145, 0, 32, s[42:43]
	v_cndmask_b32_e64 v198, 0, v214, vcc
	v_cndmask_b32_e64 v199, 0, v214, s[8:9]
	v_cndmask_b32_e64 v204, 0, v214, s[10:11]
	v_cndmask_b32_e64 v205, 0, v214, s[42:43]
	v_ldexp_f32 v130, v130, v138
	v_ldexp_f32 v131, v131, v139
	v_ldexp_f32 v132, v132, v140
	v_ldexp_f32 v133, v133, v141
	v_ldexp_f32 v134, v134, v142
	v_ldexp_f32 v135, v135, v143
	v_ldexp_f32 v136, v136, v144
	v_ldexp_f32 v137, v137, v145
	v_log_f32_e32 v130, v130
	v_log_f32_e32 v131, v131
	v_log_f32_e32 v132, v132
	v_log_f32_e32 v133, v133
	v_log_f32_e32 v134, v134
	v_log_f32_e32 v135, v135
	v_log_f32_e32 v136, v136
	v_log_f32_e32 v137, v137
	v_mul_f32_e32 v138, 0x3f317217, v130
	v_mul_f32_e32 v139, 0x3f317217, v131
	v_mul_f32_e32 v140, 0x3f317217, v132
	v_mul_f32_e32 v141, 0x3f317217, v133
	v_mul_f32_e32 v142, 0x3f317217, v134
	v_mul_f32_e32 v143, 0x3f317217, v135
	v_mul_f32_e32 v144, 0x3f317217, v136
	v_mul_f32_e32 v145, 0x3f317217, v137
	v_fma_f32 v138, v130, s85, -v138
	v_fma_f32 v139, v131, s85, -v139
	v_fma_f32 v140, v132, s85, -v140
	v_fma_f32 v141, v133, s85, -v141
	v_fma_f32 v142, v134, s85, -v142
	v_fma_f32 v143, v135, s85, -v143
	v_fma_f32 v144, v136, s85, -v144
	v_fma_f32 v145, v137, s85, -v145
	v_fmac_f32_e32 v138, 0x3377d1cf, v130
	v_fmac_f32_e32 v139, 0x3377d1cf, v131
	v_fmac_f32_e32 v140, 0x3377d1cf, v132
	v_fmac_f32_e32 v141, 0x3377d1cf, v133
	v_fmac_f32_e32 v142, 0x3377d1cf, v134
	v_fmac_f32_e32 v143, 0x3377d1cf, v135
	v_fmac_f32_e32 v144, 0x3377d1cf, v136
	v_fmac_f32_e32 v145, 0x3377d1cf, v137
	v_fmac_f32_e32 v138, 0x3f317217, v130
	v_fmac_f32_e32 v139, 0x3f317217, v131
	v_fmac_f32_e32 v140, 0x3f317217, v132
	v_fmac_f32_e32 v141, 0x3f317217, v133
	v_fmac_f32_e32 v142, 0x3f317217, v134
	v_fmac_f32_e32 v143, 0x3f317217, v135
	v_fmac_f32_e32 v144, 0x3f317217, v136
	v_fmac_f32_e32 v145, 0x3f317217, v137
	v_cmp_lt_f32_e64 vcc, |v130|, s55
	v_cmp_lt_f32_e64 s[8:9], |v131|, s55
	v_cmp_lt_f32_e64 s[10:11], |v132|, s55
	v_cmp_lt_f32_e64 s[42:43], |v133|, s55
	v_cndmask_b32_e64 v130, v130, v138, vcc
	v_cndmask_b32_e64 v131, v131, v139, s[8:9]
	v_cndmask_b32_e64 v132, v132, v140, s[10:11]
	v_cndmask_b32_e64 v133, v133, v141, s[42:43]
	v_cmp_lt_f32_e64 vcc, |v134|, s55
	v_cmp_lt_f32_e64 s[8:9], |v135|, s55
	v_cmp_lt_f32_e64 s[10:11], |v136|, s55
	v_cmp_lt_f32_e64 s[42:43], |v137|, s55
	v_cndmask_b32_e64 v134, v134, v142, vcc
	v_cndmask_b32_e64 v135, v135, v143, s[8:9]
	v_cndmask_b32_e64 v136, v136, v144, s[10:11]
	v_cndmask_b32_e64 v137, v137, v145, s[42:43]
	v_sub_f32_e32 v130, v130, v162
	v_sub_f32_e32 v131, v131, v163
	v_sub_f32_e32 v132, v132, v196
; template <int MODE> __device__ __forceinline__ void gemm_epilogue(f32x4 (&acc)[2][2][4][2], const GD& g, const pg8::Unit& u, int wr, int wc, int fr, int fq, LAS unsigned char* lds, const float (&rsv)[2][4]) {
;     ...
;                 for (int m = 0; m < 4; ++m) { float* rowp = LOGF + (size_t)(rt + ai * 128 + m * 16) * 1024 + col0;
; #pragma unroll
;                     for (int bj = 0; bj < 2; ++bj)
;                     {
; #pragma unroll
;                         for (int n = 0; n < 2; ++n) { f32x4 v = acc[ai][bj][m][n], o;
; #pragma unroll
;                             for (int j = 0; j < 4; ++j) { const float sg = 1.f / (1.f + __expf(-v[j])); const float f = lb[bj][n][j] + (1.f - lb[bj][n][j]) * sg; o[j] = __logf(f); }
;                             *(f32x4*)(rowp + bj * 128 + 4 * n) = o; } } }
	v_sub_f32_e32 v133, v133, v197
	v_sub_f32_e32 v134, v134, v198
	v_sub_f32_e32 v135, v135, v199
	v_sub_f32_e32 v136, v136, v204
	v_sub_f32_e32 v137, v137, v205
	global_store_dwordx4 v159, v[130:133], s[2:3] offset:512
	global_store_dwordx4 v159, v[134:137], s[2:3] offset:528
	s_nop 0
	v_add_u32_e32 v159, 0x10000, v159
	v_pk_mul_f32 v[130:131], v[46:47], v[160:161]
	v_pk_mul_f32 v[132:133], v[48:49], v[160:161]
	v_pk_mul_f32 v[134:135], v[42:43], v[160:161]
	v_pk_mul_f32 v[136:137], v[44:45], v[160:161]
	v_exp_f32_e32 v130, v130
	v_exp_f32_e32 v131, v131
	v_exp_f32_e32 v132, v132
	v_exp_f32_e32 v133, v133
	v_exp_f32_e32 v134, v134
	v_exp_f32_e32 v135, v135
	v_exp_f32_e32 v136, v136
	v_exp_f32_e32 v137, v137
	v_pk_add_f32 v[130:131], v[130:131], 1.0 op_sel_hi:[1,0]
	v_pk_add_f32 v[132:133], v[132:133], 1.0 op_sel_hi:[1,0]
	v_pk_add_f32 v[134:135], v[134:135], 1.0 op_sel_hi:[1,0]
	v_pk_add_f32 v[136:137], v[136:137], 1.0 op_sel_hi:[1,0]
	v_rcp_f32_e32 v130, v130
	v_rcp_f32_e32 v131, v131
	v_rcp_f32_e32 v132, v132
	v_rcp_f32_e32 v133, v133
	v_rcp_f32_e32 v134, v134
	v_rcp_f32_e32 v135, v135
	v_rcp_f32_e32 v136, v136
	v_rcp_f32_e32 v137, v137
	v_pk_fma_f32 v[130:131], v[130:131], v[178:179], v[220:221]
	v_pk_fma_f32 v[132:133], v[132:133], v[180:181], v[222:223]
	v_pk_fma_f32 v[134:135], v[134:135], v[182:183], v[224:225]
	v_pk_fma_f32 v[136:137], v[136:137], v[184:185], v[226:227]
	v_cmp_gt_f32_e32 vcc, s80, v130
	v_cmp_gt_f32_e64 s[8:9], s80, v131
	v_cmp_gt_f32_e64 s[10:11], s80, v132
	v_cmp_gt_f32_e64 s[42:43], s80, v133
	v_cndmask_b32_e64 v138, 0, 32, vcc
	v_cndmask_b32_e64 v139, 0, 32, s[8:9]
	v_cndmask_b32_e64 v140, 0, 32, s[10:11]
	v_cndmask_b32_e64 v141, 0, 32, s[42:43]
	v_cndmask_b32_e64 v162, 0, v214, vcc
	v_cndmask_b32_e64 v163, 0, v214, s[8:9]
	v_cndmask_b32_e64 v196, 0, v214, s[10:11]
	v_cndmask_b32_e64 v197, 0, v214, s[42:43]
	v_cmp_gt_f32_e32 vcc, s80, v134
	v_cmp_gt_f32_e64 s[8:9], s80, v135
	v_cmp_gt_f32_e64 s[10:11], s80, v136
	v_cmp_gt_f32_e64 s[42:43], s80, v137
	v_cndmask_b32_e64 v142, 0, 32, vcc
	v_cndmask_b32_e64 v143, 0, 32, s[8:9]
	v_cndmask_b32_e64 v144, 0, 32, s[10:11]
	v_cndmask_b32_e64 v145, 0, 32, s[42:43]
	v_cndmask_b32_e64 v198, 0, v214, vcc
	v_cndmask_b32_e64 v199, 0, v214, s[8:9]
	v_cndmask_b32_e64 v204, 0, v214, s[10:11]
	v_cndmask_b32_e64 v205, 0, v214, s[42:43]
	v_ldexp_f32 v130, v130, v138
	v_ldexp_f32 v131, v131, v139
	v_ldexp_f32 v132, v132, v140
	v_ldexp_f32 v133, v133, v141
	v_ldexp_f32 v134, v134, v142
	v_ldexp_f32 v135, v135, v143
	v_ldexp_f32 v136, v136, v144
	v_ldexp_f32 v137, v137, v145
	v_log_f32_e32 v130, v130
	v_log_f32_e32 v131, v131
	v_log_f32_e32 v132, v132
	v_log_f32_e32 v133, v133
	v_log_f32_e32 v134, v134
	v_log_f32_e32 v135, v135
	v_log_f32_e32 v136, v136
	v_log_f32_e32 v137, v137
	v_mul_f32_e32 v138, 0x3f317217, v130
	v_mul_f32_e32 v139, 0x3f317217, v131
	v_mul_f32_e32 v140, 0x3f317217, v132
	v_mul_f32_e32 v141, 0x3f317217, v133
	v_mul_f32_e32 v142, 0x3f317217, v134
	v_mul_f32_e32 v143, 0x3f317217, v135
	v_mul_f32_e32 v144, 0x3f317217, v136
	v_mul_f32_e32 v145, 0x3f317217, v137
	v_fma_f32 v138, v130, s85, -v138
	v_fma_f32 v139, v131, s85, -v139
	v_fma_f32 v140, v132, s85, -v140
	v_fma_f32 v141, v133, s85, -v141
	v_fma_f32 v142, v134, s85, -v142
	v_fma_f32 v143, v135, s85, -v143
	v_fma_f32 v144, v136, s85, -v144
	v_fma_f32 v145, v137, s85, -v145
	v_fmac_f32_e32 v138, 0x3377d1cf, v130
	v_fmac_f32_e32 v139, 0x3377d1cf, v131
	v_fmac_f32_e32 v140, 0x3377d1cf, v132
	v_fmac_f32_e32 v141, 0x3377d1cf, v133
	v_fmac_f32_e32 v142, 0x3377d1cf, v134
	v_fmac_f32_e32 v143, 0x3377d1cf, v135
	v_fmac_f32_e32 v144, 0x3377d1cf, v136
	v_fmac_f32_e32 v145, 0x3377d1cf, v137
	v_fmac_f32_e32 v138, 0x3f317217, v130
	v_fmac_f32_e32 v139, 0x3f317217, v131
	v_fmac_f32_e32 v140, 0x3f317217, v132
	v_fmac_f32_e32 v141, 0x3f317217, v133
	v_fmac_f32_e32 v142, 0x3f317217, v134
	v_fmac_f32_e32 v143, 0x3f317217, v135
	v_fmac_f32_e32 v144, 0x3f317217, v136
	v_fmac_f32_e32 v145, 0x3f317217, v137
	v_cmp_lt_f32_e64 vcc, |v130|, s55
	v_cmp_lt_f32_e64 s[8:9], |v131|, s55
	v_cmp_lt_f32_e64 s[10:11], |v132|, s55
	v_cmp_lt_f32_e64 s[42:43], |v133|, s55
	v_cndmask_b32_e64 v130, v130, v138, vcc
	v_cndmask_b32_e64 v131, v131, v139, s[8:9]
	v_cndmask_b32_e64 v132, v132, v140, s[10:11]
	v_cndmask_b32_e64 v133, v133, v141, s[42:43]
	v_cmp_lt_f32_e64 vcc, |v134|, s55
	v_cmp_lt_f32_e64 s[8:9], |v135|, s55
	v_cmp_lt_f32_e64 s[10:11], |v136|, s55
	v_cmp_lt_f32_e64 s[42:43], |v137|, s55
	v_cndmask_b32_e64 v134, v134, v142, vcc
	v_cndmask_b32_e64 v135, v135, v143, s[8:9]
	v_cndmask_b32_e64 v136, v136, v144, s[10:11]
	v_cndmask_b32_e64 v137, v137, v145, s[42:43]
	v_sub_f32_e32 v130, v130, v162
	v_sub_f32_e32 v131, v131, v163
	v_sub_f32_e32 v132, v132, v196
	v_sub_f32_e32 v133, v133, v197
	v_sub_f32_e32 v134, v134, v198
	v_sub_f32_e32 v135, v135, v199
	v_sub_f32_e32 v136, v136, v204
	v_sub_f32_e32 v137, v137, v205
	global_store_dwordx4 v159, v[130:133], s[2:3]
	global_store_dwordx4 v159, v[134:137], s[2:3] offset:16
	s_nop 0
	v_pk_mul_f32 v[130:131], v[38:39], v[160:161]
	v_pk_mul_f32 v[132:133], v[40:41], v[160:161]
	v_pk_mul_f32 v[134:135], v[34:35], v[160:161]
	v_pk_mul_f32 v[136:137], v[36:37], v[160:161]
	v_exp_f32_e32 v130, v130
	v_exp_f32_e32 v131, v131
	v_exp_f32_e32 v132, v132
	v_exp_f32_e32 v133, v133
	v_exp_f32_e32 v134, v134
	v_exp_f32_e32 v135, v135
	v_exp_f32_e32 v136, v136
	v_exp_f32_e32 v137, v137
	v_pk_add_f32 v[130:131], v[130:131], 1.0 op_sel_hi:[1,0]
	v_pk_add_f32 v[132:133], v[132:133], 1.0 op_sel_hi:[1,0]
	v_pk_add_f32 v[134:135], v[134:135], 1.0 op_sel_hi:[1,0]
	v_pk_add_f32 v[136:137], v[136:137], 1.0 op_sel_hi:[1,0]
; template <int MODE> __device__ __forceinline__ void gemm_epilogue(f32x4 (&acc)[2][2][4][2], const GD& g, const pg8::Unit& u, int wr, int wc, int fr, int fq, LAS unsigned char* lds, const float (&rsv)[2][4]) {
;     ...
;                 for (int m = 0; m < 4; ++m) { float* rowp = LOGF + (size_t)(rt + ai * 128 + m * 16) * 1024 + col0;
; #pragma unroll
;                     for (int bj = 0; bj < 2; ++bj)
;                     {
; #pragma unroll
;                         for (int n = 0; n < 2; ++n) { f32x4 v = acc[ai][bj][m][n], o;
; #pragma unroll
;                             for (int j = 0; j < 4; ++j) { const float sg = 1.f / (1.f + __expf(-v[j])); const float f = lb[bj][n][j] + (1.f - lb[bj][n][j]) * sg; o[j] = __logf(f); }
;                             *(f32x4*)(rowp + bj * 128 + 4 * n) = o; } } }
	v_rcp_f32_e32 v130, v130
	v_rcp_f32_e32 v131, v131
	v_rcp_f32_e32 v132, v132
	v_rcp_f32_e32 v133, v133
	v_rcp_f32_e32 v134, v134
	v_rcp_f32_e32 v135, v135
	v_rcp_f32_e32 v136, v136
	v_rcp_f32_e32 v137, v137
	v_pk_fma_f32 v[130:131], v[130:131], v[186:187], v[228:229]
	v_pk_fma_f32 v[132:133], v[132:133], v[188:189], v[230:231]
	v_pk_fma_f32 v[134:135], v[134:135], v[190:191], v[232:233]
	v_pk_fma_f32 v[136:137], v[136:137], v[192:193], v[234:235]
	v_cmp_gt_f32_e32 vcc, s80, v130
	v_cmp_gt_f32_e64 s[8:9], s80, v131
	v_cmp_gt_f32_e64 s[10:11], s80, v132
	v_cmp_gt_f32_e64 s[42:43], s80, v133
	v_cndmask_b32_e64 v138, 0, 32, vcc
	v_cndmask_b32_e64 v139, 0, 32, s[8:9]
	v_cndmask_b32_e64 v140, 0, 32, s[10:11]
	v_cndmask_b32_e64 v141, 0, 32, s[42:43]
	v_cndmask_b32_e64 v162, 0, v214, vcc
	v_cndmask_b32_e64 v163, 0, v214, s[8:9]
	v_cndmask_b32_e64 v196, 0, v214, s[10:11]
	v_cndmask_b32_e64 v197, 0, v214, s[42:43]
	v_cmp_gt_f32_e32 vcc, s80, v134
	v_cmp_gt_f32_e64 s[8:9], s80, v135
	v_cmp_gt_f32_e64 s[10:11], s80, v136
	v_cmp_gt_f32_e64 s[42:43], s80, v137
	v_cndmask_b32_e64 v142, 0, 32, vcc
	v_cndmask_b32_e64 v143, 0, 32, s[8:9]
	v_cndmask_b32_e64 v144, 0, 32, s[10:11]
	v_cndmask_b32_e64 v145, 0, 32, s[42:43]
	v_cndmask_b32_e64 v198, 0, v214, vcc
	v_cndmask_b32_e64 v199, 0, v214, s[8:9]
	v_cndmask_b32_e64 v204, 0, v214, s[10:11]
	v_cndmask_b32_e64 v205, 0, v214, s[42:43]
	v_ldexp_f32 v130, v130, v138
	v_ldexp_f32 v131, v131, v139
	v_ldexp_f32 v132, v132, v140
	v_ldexp_f32 v133, v133, v141
	v_ldexp_f32 v134, v134, v142
	v_ldexp_f32 v135, v135, v143
	v_ldexp_f32 v136, v136, v144
	v_ldexp_f32 v137, v137, v145
	v_log_f32_e32 v130, v130
	v_log_f32_e32 v131, v131
	v_log_f32_e32 v132, v132
	v_log_f32_e32 v133, v133
	v_log_f32_e32 v134, v134
	v_log_f32_e32 v135, v135
	v_log_f32_e32 v136, v136
	v_log_f32_e32 v137, v137
	v_mul_f32_e32 v138, 0x3f317217, v130
	v_mul_f32_e32 v139, 0x3f317217, v131
	v_mul_f32_e32 v140, 0x3f317217, v132
	v_mul_f32_e32 v141, 0x3f317217, v133
	v_mul_f32_e32 v142, 0x3f317217, v134
	v_mul_f32_e32 v143, 0x3f317217, v135
	v_mul_f32_e32 v144, 0x3f317217, v136
	v_mul_f32_e32 v145, 0x3f317217, v137
	v_fma_f32 v138, v130, s85, -v138
	v_fma_f32 v139, v131, s85, -v139
	v_fma_f32 v140, v132, s85, -v140
	v_fma_f32 v141, v133, s85, -v141
	v_fma_f32 v142, v134, s85, -v142
	v_fma_f32 v143, v135, s85, -v143
	v_fma_f32 v144, v136, s85, -v144
	v_fma_f32 v145, v137, s85, -v145
	v_fmac_f32_e32 v138, 0x3377d1cf, v130
	v_fmac_f32_e32 v139, 0x3377d1cf, v131
	v_fmac_f32_e32 v140, 0x3377d1cf, v132
	v_fmac_f32_e32 v141, 0x3377d1cf, v133
	v_fmac_f32_e32 v142, 0x3377d1cf, v134
	v_fmac_f32_e32 v143, 0x3377d1cf, v135
	v_fmac_f32_e32 v144, 0x3377d1cf, v136
	v_fmac_f32_e32 v145, 0x3377d1cf, v137
	v_fmac_f32_e32 v138, 0x3f317217, v130
	v_fmac_f32_e32 v139, 0x3f317217, v131
	v_fmac_f32_e32 v140, 0x3f317217, v132
	v_fmac_f32_e32 v141, 0x3f317217, v133
	v_fmac_f32_e32 v142, 0x3f317217, v134
	v_fmac_f32_e32 v143, 0x3f317217, v135
	v_fmac_f32_e32 v144, 0x3f317217, v136
	v_fmac_f32_e32 v145, 0x3f317217, v137
	v_cmp_lt_f32_e64 vcc, |v130|, s55
	v_cmp_lt_f32_e64 s[8:9], |v131|, s55
	v_cmp_lt_f32_e64 s[10:11], |v132|, s55
	v_cmp_lt_f32_e64 s[42:43], |v133|, s55
	v_cndmask_b32_e64 v130, v130, v138, vcc
	v_cndmask_b32_e64 v131, v131, v139, s[8:9]
	v_cndmask_b32_e64 v132, v132, v140, s[10:11]
	v_cndmask_b32_e64 v133, v133, v141, s[42:43]
	v_cmp_lt_f32_e64 vcc, |v134|, s55
	v_cmp_lt_f32_e64 s[8:9], |v135|, s55
	v_cmp_lt_f32_e64 s[10:11], |v136|, s55
	v_cmp_lt_f32_e64 s[42:43], |v137|, s55
	v_cndmask_b32_e64 v134, v134, v142, vcc
	v_cndmask_b32_e64 v135, v135, v143, s[8:9]
	v_cndmask_b32_e64 v136, v136, v144, s[10:11]
	v_cndmask_b32_e64 v137, v137, v145, s[42:43]
	v_sub_f32_e32 v130, v130, v162
	v_sub_f32_e32 v131, v131, v163
	v_sub_f32_e32 v132, v132, v196
	v_sub_f32_e32 v133, v133, v197
	v_sub_f32_e32 v134, v134, v198
	v_sub_f32_e32 v135, v135, v199
	v_sub_f32_e32 v136, v136, v204
	v_sub_f32_e32 v137, v137, v205
	global_store_dwordx4 v159, v[130:133], s[2:3] offset:512
	global_store_dwordx4 v159, v[134:137], s[2:3] offset:528
	s_nop 0
	v_add_u32_e32 v159, 0x10000, v159
	v_pk_mul_f32 v[130:131], v[30:31], v[160:161]
	v_pk_mul_f32 v[132:133], v[32:33], v[160:161]
	v_pk_mul_f32 v[134:135], v[26:27], v[160:161]
	v_pk_mul_f32 v[136:137], v[28:29], v[160:161]
	v_exp_f32_e32 v130, v130
	v_exp_f32_e32 v131, v131
	v_exp_f32_e32 v132, v132
	v_exp_f32_e32 v133, v133
	v_exp_f32_e32 v134, v134
	v_exp_f32_e32 v135, v135
	v_exp_f32_e32 v136, v136
	v_exp_f32_e32 v137, v137
	v_pk_add_f32 v[130:131], v[130:131], 1.0 op_sel_hi:[1,0]
	v_pk_add_f32 v[132:133], v[132:133], 1.0 op_sel_hi:[1,0]
	v_pk_add_f32 v[134:135], v[134:135], 1.0 op_sel_hi:[1,0]
	v_pk_add_f32 v[136:137], v[136:137], 1.0 op_sel_hi:[1,0]
	v_rcp_f32_e32 v130, v130
	v_rcp_f32_e32 v131, v131
	v_rcp_f32_e32 v132, v132
	v_rcp_f32_e32 v133, v133
	v_rcp_f32_e32 v134, v134
	v_rcp_f32_e32 v135, v135
	v_rcp_f32_e32 v136, v136
	v_rcp_f32_e32 v137, v137
	v_pk_fma_f32 v[130:131], v[130:131], v[178:179], v[220:221]
	v_pk_fma_f32 v[132:133], v[132:133], v[180:181], v[222:223]
	v_pk_fma_f32 v[134:135], v[134:135], v[182:183], v[224:225]
	v_pk_fma_f32 v[136:137], v[136:137], v[184:185], v[226:227]
	v_cmp_gt_f32_e32 vcc, s80, v130
	v_cmp_gt_f32_e64 s[8:9], s80, v131
	v_cmp_gt_f32_e64 s[10:11], s80, v132
	v_cmp_gt_f32_e64 s[42:43], s80, v133
	v_cndmask_b32_e64 v138, 0, 32, vcc
	v_cndmask_b32_e64 v139, 0, 32, s[8:9]
	v_cndmask_b32_e64 v140, 0, 32, s[10:11]
	v_cndmask_b32_e64 v141, 0, 32, s[42:43]
	v_cndmask_b32_e64 v162, 0, v214, vcc
	v_cndmask_b32_e64 v163, 0, v214, s[8:9]
	v_cndmask_b32_e64 v196, 0, v214, s[10:11]
	v_cndmask_b32_e64 v197, 0, v214, s[42:43]
; template <int MODE> __device__ __forceinline__ void gemm_epilogue(f32x4 (&acc)[2][2][4][2], const GD& g, const pg8::Unit& u, int wr, int wc, int fr, int fq, LAS unsigned char* lds, const float (&rsv)[2][4]) {
;     ...
;                 for (int m = 0; m < 4; ++m) { float* rowp = LOGF + (size_t)(rt + ai * 128 + m * 16) * 1024 + col0;
; #pragma unroll
;                     for (int bj = 0; bj < 2; ++bj)
;                     {
; #pragma unroll
;                         for (int n = 0; n < 2; ++n) { f32x4 v = acc[ai][bj][m][n], o;
; #pragma unroll
;                             for (int j = 0; j < 4; ++j) { const float sg = 1.f / (1.f + __expf(-v[j])); const float f = lb[bj][n][j] + (1.f - lb[bj][n][j]) * sg; o[j] = __logf(f); }
;                             *(f32x4*)(rowp + bj * 128 + 4 * n) = o; } } }
	v_cmp_gt_f32_e32 vcc, s80, v134
	v_cmp_gt_f32_e64 s[8:9], s80, v135
	v_cmp_gt_f32_e64 s[10:11], s80, v136
	v_cmp_gt_f32_e64 s[42:43], s80, v137
	v_cndmask_b32_e64 v142, 0, 32, vcc
	v_cndmask_b32_e64 v143, 0, 32, s[8:9]
	v_cndmask_b32_e64 v144, 0, 32, s[10:11]
	v_cndmask_b32_e64 v145, 0, 32, s[42:43]
	v_cndmask_b32_e64 v198, 0, v214, vcc
	v_cndmask_b32_e64 v199, 0, v214, s[8:9]
	v_cndmask_b32_e64 v204, 0, v214, s[10:11]
	v_cndmask_b32_e64 v205, 0, v214, s[42:43]
	v_ldexp_f32 v130, v130, v138
	v_ldexp_f32 v131, v131, v139
	v_ldexp_f32 v132, v132, v140
	v_ldexp_f32 v133, v133, v141
	v_ldexp_f32 v134, v134, v142
	v_ldexp_f32 v135, v135, v143
	v_ldexp_f32 v136, v136, v144
	v_ldexp_f32 v137, v137, v145
	v_log_f32_e32 v130, v130
	v_log_f32_e32 v131, v131
	v_log_f32_e32 v132, v132
	v_log_f32_e32 v133, v133
	v_log_f32_e32 v134, v134
	v_log_f32_e32 v135, v135
	v_log_f32_e32 v136, v136
	v_log_f32_e32 v137, v137
	v_mul_f32_e32 v138, 0x3f317217, v130
	v_mul_f32_e32 v139, 0x3f317217, v131
	v_mul_f32_e32 v140, 0x3f317217, v132
	v_mul_f32_e32 v141, 0x3f317217, v133
	v_mul_f32_e32 v142, 0x3f317217, v134
	v_mul_f32_e32 v143, 0x3f317217, v135
	v_mul_f32_e32 v144, 0x3f317217, v136
	v_mul_f32_e32 v145, 0x3f317217, v137
	v_fma_f32 v138, v130, s85, -v138
	v_fma_f32 v139, v131, s85, -v139
	v_fma_f32 v140, v132, s85, -v140
	v_fma_f32 v141, v133, s85, -v141
	v_fma_f32 v142, v134, s85, -v142
	v_fma_f32 v143, v135, s85, -v143
	v_fma_f32 v144, v136, s85, -v144
	v_fma_f32 v145, v137, s85, -v145
	v_fmac_f32_e32 v138, 0x3377d1cf, v130
	v_fmac_f32_e32 v139, 0x3377d1cf, v131
	v_fmac_f32_e32 v140, 0x3377d1cf, v132
	v_fmac_f32_e32 v141, 0x3377d1cf, v133
	v_fmac_f32_e32 v142, 0x3377d1cf, v134
	v_fmac_f32_e32 v143, 0x3377d1cf, v135
	v_fmac_f32_e32 v144, 0x3377d1cf, v136
	v_fmac_f32_e32 v145, 0x3377d1cf, v137
	v_fmac_f32_e32 v138, 0x3f317217, v130
	v_fmac_f32_e32 v139, 0x3f317217, v131
	v_fmac_f32_e32 v140, 0x3f317217, v132
	v_fmac_f32_e32 v141, 0x3f317217, v133
	v_fmac_f32_e32 v142, 0x3f317217, v134
	v_fmac_f32_e32 v143, 0x3f317217, v135
	v_fmac_f32_e32 v144, 0x3f317217, v136
	v_fmac_f32_e32 v145, 0x3f317217, v137
	v_cmp_lt_f32_e64 vcc, |v130|, s55
	v_cmp_lt_f32_e64 s[8:9], |v131|, s55
	v_cmp_lt_f32_e64 s[10:11], |v132|, s55
	v_cmp_lt_f32_e64 s[42:43], |v133|, s55
	v_cndmask_b32_e64 v130, v130, v138, vcc
	v_cndmask_b32_e64 v131, v131, v139, s[8:9]
	v_cndmask_b32_e64 v132, v132, v140, s[10:11]
	v_cndmask_b32_e64 v133, v133, v141, s[42:43]
	v_cmp_lt_f32_e64 vcc, |v134|, s55
	v_cmp_lt_f32_e64 s[8:9], |v135|, s55
	v_cmp_lt_f32_e64 s[10:11], |v136|, s55
	v_cmp_lt_f32_e64 s[42:43], |v137|, s55
	v_cndmask_b32_e64 v134, v134, v142, vcc
	v_cndmask_b32_e64 v135, v135, v143, s[8:9]
	v_cndmask_b32_e64 v136, v136, v144, s[10:11]
	v_cndmask_b32_e64 v137, v137, v145, s[42:43]
	v_sub_f32_e32 v130, v130, v162
	v_sub_f32_e32 v131, v131, v163
	v_sub_f32_e32 v132, v132, v196
	v_sub_f32_e32 v133, v133, v197
	v_sub_f32_e32 v134, v134, v198
	v_sub_f32_e32 v135, v135, v199
	v_sub_f32_e32 v136, v136, v204
	v_sub_f32_e32 v137, v137, v205
	global_store_dwordx4 v159, v[130:133], s[2:3]
	global_store_dwordx4 v159, v[134:137], s[2:3] offset:16
	s_nop 0
	v_pk_mul_f32 v[130:131], v[22:23], v[160:161]
	v_pk_mul_f32 v[132:133], v[24:25], v[160:161]
	v_pk_mul_f32 v[134:135], v[18:19], v[160:161]
	v_pk_mul_f32 v[136:137], v[20:21], v[160:161]
	v_exp_f32_e32 v130, v130
	v_exp_f32_e32 v131, v131
	v_exp_f32_e32 v132, v132
	v_exp_f32_e32 v133, v133
	v_exp_f32_e32 v134, v134
	v_exp_f32_e32 v135, v135
	v_exp_f32_e32 v136, v136
	v_exp_f32_e32 v137, v137
	v_pk_add_f32 v[130:131], v[130:131], 1.0 op_sel_hi:[1,0]
	v_pk_add_f32 v[132:133], v[132:133], 1.0 op_sel_hi:[1,0]
	v_pk_add_f32 v[134:135], v[134:135], 1.0 op_sel_hi:[1,0]
	v_pk_add_f32 v[136:137], v[136:137], 1.0 op_sel_hi:[1,0]
	v_rcp_f32_e32 v130, v130
	v_rcp_f32_e32 v131, v131
	v_rcp_f32_e32 v132, v132
	v_rcp_f32_e32 v133, v133
	v_rcp_f32_e32 v134, v134
	v_rcp_f32_e32 v135, v135
	v_rcp_f32_e32 v136, v136
	v_rcp_f32_e32 v137, v137
	v_pk_fma_f32 v[130:131], v[130:131], v[186:187], v[228:229]
	v_pk_fma_f32 v[132:133], v[132:133], v[188:189], v[230:231]
	v_pk_fma_f32 v[134:135], v[134:135], v[190:191], v[232:233]
	v_pk_fma_f32 v[136:137], v[136:137], v[192:193], v[234:235]
	v_cmp_gt_f32_e32 vcc, s80, v130
	v_cmp_gt_f32_e64 s[8:9], s80, v131
	v_cmp_gt_f32_e64 s[10:11], s80, v132
	v_cmp_gt_f32_e64 s[42:43], s80, v133
	v_cndmask_b32_e64 v138, 0, 32, vcc
	v_cndmask_b32_e64 v139, 0, 32, s[8:9]
	v_cndmask_b32_e64 v140, 0, 32, s[10:11]
	v_cndmask_b32_e64 v141, 0, 32, s[42:43]
	v_cndmask_b32_e64 v162, 0, v214, vcc
	v_cndmask_b32_e64 v163, 0, v214, s[8:9]
	v_cndmask_b32_e64 v196, 0, v214, s[10:11]
	v_cndmask_b32_e64 v197, 0, v214, s[42:43]
	v_cmp_gt_f32_e32 vcc, s80, v134
	v_cmp_gt_f32_e64 s[8:9], s80, v135
	v_cmp_gt_f32_e64 s[10:11], s80, v136
	v_cmp_gt_f32_e64 s[42:43], s80, v137
	v_cndmask_b32_e64 v142, 0, 32, vcc
	v_cndmask_b32_e64 v143, 0, 32, s[8:9]
	v_cndmask_b32_e64 v144, 0, 32, s[10:11]
	v_cndmask_b32_e64 v145, 0, 32, s[42:43]
	v_cndmask_b32_e64 v198, 0, v214, vcc
	v_cndmask_b32_e64 v199, 0, v214, s[8:9]
	v_cndmask_b32_e64 v204, 0, v214, s[10:11]
	v_cndmask_b32_e64 v205, 0, v214, s[42:43]
	v_ldexp_f32 v130, v130, v138
	v_ldexp_f32 v131, v131, v139
	v_ldexp_f32 v132, v132, v140
	v_ldexp_f32 v133, v133, v141
	v_ldexp_f32 v134, v134, v142
	v_ldexp_f32 v135, v135, v143
	v_ldexp_f32 v136, v136, v144
	v_ldexp_f32 v137, v137, v145
	v_log_f32_e32 v130, v130
	v_log_f32_e32 v131, v131
	v_log_f32_e32 v132, v132
	v_log_f32_e32 v133, v133
	v_log_f32_e32 v134, v134
	v_log_f32_e32 v135, v135
	v_log_f32_e32 v136, v136
	v_log_f32_e32 v137, v137
	v_mul_f32_e32 v138, 0x3f317217, v130
; template <int MODE> __device__ __forceinline__ void gemm_epilogue(f32x4 (&acc)[2][2][4][2], const GD& g, const pg8::Unit& u, int wr, int wc, int fr, int fq, LAS unsigned char* lds, const float (&rsv)[2][4]) {
;     ...
;                 for (int m = 0; m < 4; ++m) { float* rowp = LOGF + (size_t)(rt + ai * 128 + m * 16) * 1024 + col0;
; #pragma unroll
;                     for (int bj = 0; bj < 2; ++bj)
;                     {
; #pragma unroll
;                         for (int n = 0; n < 2; ++n) { f32x4 v = acc[ai][bj][m][n], o;
; #pragma unroll
;                             for (int j = 0; j < 4; ++j) { const float sg = 1.f / (1.f + __expf(-v[j])); const float f = lb[bj][n][j] + (1.f - lb[bj][n][j]) * sg; o[j] = __logf(f); }
;                             *(f32x4*)(rowp + bj * 128 + 4 * n) = o; } } }
	v_mul_f32_e32 v139, 0x3f317217, v131
	v_mul_f32_e32 v140, 0x3f317217, v132
	v_mul_f32_e32 v141, 0x3f317217, v133
	v_mul_f32_e32 v142, 0x3f317217, v134
	v_mul_f32_e32 v143, 0x3f317217, v135
	v_mul_f32_e32 v144, 0x3f317217, v136
	v_mul_f32_e32 v145, 0x3f317217, v137
	v_fma_f32 v138, v130, s85, -v138
	v_fma_f32 v139, v131, s85, -v139
	v_fma_f32 v140, v132, s85, -v140
	v_fma_f32 v141, v133, s85, -v141
	v_fma_f32 v142, v134, s85, -v142
	v_fma_f32 v143, v135, s85, -v143
	v_fma_f32 v144, v136, s85, -v144
	v_fma_f32 v145, v137, s85, -v145
	v_fmac_f32_e32 v138, 0x3377d1cf, v130
	v_fmac_f32_e32 v139, 0x3377d1cf, v131
	v_fmac_f32_e32 v140, 0x3377d1cf, v132
	v_fmac_f32_e32 v141, 0x3377d1cf, v133
	v_fmac_f32_e32 v142, 0x3377d1cf, v134
	v_fmac_f32_e32 v143, 0x3377d1cf, v135
	v_fmac_f32_e32 v144, 0x3377d1cf, v136
	v_fmac_f32_e32 v145, 0x3377d1cf, v137
	v_fmac_f32_e32 v138, 0x3f317217, v130
	v_fmac_f32_e32 v139, 0x3f317217, v131
	v_fmac_f32_e32 v140, 0x3f317217, v132
	v_fmac_f32_e32 v141, 0x3f317217, v133
	v_fmac_f32_e32 v142, 0x3f317217, v134
	v_fmac_f32_e32 v143, 0x3f317217, v135
	v_fmac_f32_e32 v144, 0x3f317217, v136
	v_fmac_f32_e32 v145, 0x3f317217, v137
	v_cmp_lt_f32_e64 vcc, |v130|, s55
	v_cmp_lt_f32_e64 s[8:9], |v131|, s55
	v_cmp_lt_f32_e64 s[10:11], |v132|, s55
	v_cmp_lt_f32_e64 s[42:43], |v133|, s55
	v_cndmask_b32_e64 v130, v130, v138, vcc
	v_cndmask_b32_e64 v131, v131, v139, s[8:9]
	v_cndmask_b32_e64 v132, v132, v140, s[10:11]
	v_cndmask_b32_e64 v133, v133, v141, s[42:43]
	v_cmp_lt_f32_e64 vcc, |v134|, s55
	v_cmp_lt_f32_e64 s[8:9], |v135|, s55
	v_cmp_lt_f32_e64 s[10:11], |v136|, s55
	v_cmp_lt_f32_e64 s[42:43], |v137|, s55
	v_cndmask_b32_e64 v134, v134, v142, vcc
	v_cndmask_b32_e64 v135, v135, v143, s[8:9]
	v_cndmask_b32_e64 v136, v136, v144, s[10:11]
	v_cndmask_b32_e64 v137, v137, v145, s[42:43]
	v_sub_f32_e32 v130, v130, v162
	v_sub_f32_e32 v131, v131, v163
	v_sub_f32_e32 v132, v132, v196
	v_sub_f32_e32 v133, v133, v197
	v_sub_f32_e32 v134, v134, v198
	v_sub_f32_e32 v135, v135, v199
	v_sub_f32_e32 v136, v136, v204
	v_sub_f32_e32 v137, v137, v205
	global_store_dwordx4 v159, v[130:133], s[2:3] offset:512
	global_store_dwordx4 v159, v[134:137], s[2:3] offset:528
	s_nop 0
	v_add_u32_e32 v159, 0x10000, v159
	v_pk_mul_f32 v[130:131], v[14:15], v[160:161]
	v_pk_mul_f32 v[132:133], v[16:17], v[160:161]
	v_pk_mul_f32 v[134:135], v[10:11], v[160:161]
	v_pk_mul_f32 v[136:137], v[12:13], v[160:161]
	v_exp_f32_e32 v130, v130
	v_exp_f32_e32 v131, v131
	v_exp_f32_e32 v132, v132
	v_exp_f32_e32 v133, v133
	v_exp_f32_e32 v134, v134
	v_exp_f32_e32 v135, v135
	v_exp_f32_e32 v136, v136
	v_exp_f32_e32 v137, v137
	v_pk_add_f32 v[130:131], v[130:131], 1.0 op_sel_hi:[1,0]
	v_pk_add_f32 v[132:133], v[132:133], 1.0 op_sel_hi:[1,0]
	v_pk_add_f32 v[134:135], v[134:135], 1.0 op_sel_hi:[1,0]
	v_pk_add_f32 v[136:137], v[136:137], 1.0 op_sel_hi:[1,0]
	v_rcp_f32_e32 v130, v130
	v_rcp_f32_e32 v131, v131
	v_rcp_f32_e32 v132, v132
	v_rcp_f32_e32 v133, v133
	v_rcp_f32_e32 v134, v134
	v_rcp_f32_e32 v135, v135
	v_rcp_f32_e32 v136, v136
	v_rcp_f32_e32 v137, v137
	v_pk_fma_f32 v[130:131], v[130:131], v[178:179], v[220:221]
	v_pk_fma_f32 v[132:133], v[132:133], v[180:181], v[222:223]
	v_pk_fma_f32 v[134:135], v[134:135], v[182:183], v[224:225]
	v_pk_fma_f32 v[136:137], v[136:137], v[184:185], v[226:227]
	v_cmp_gt_f32_e32 vcc, s80, v130
	v_cmp_gt_f32_e64 s[8:9], s80, v131
	v_cmp_gt_f32_e64 s[10:11], s80, v132
	v_cmp_gt_f32_e64 s[42:43], s80, v133
	v_cndmask_b32_e64 v138, 0, 32, vcc
	v_cndmask_b32_e64 v139, 0, 32, s[8:9]
	v_cndmask_b32_e64 v140, 0, 32, s[10:11]
	v_cndmask_b32_e64 v141, 0, 32, s[42:43]
	v_cndmask_b32_e64 v162, 0, v214, vcc
	v_cndmask_b32_e64 v163, 0, v214, s[8:9]
	v_cndmask_b32_e64 v196, 0, v214, s[10:11]
	v_cndmask_b32_e64 v197, 0, v214, s[42:43]
	v_cmp_gt_f32_e32 vcc, s80, v134
	v_cmp_gt_f32_e64 s[8:9], s80, v135
	v_cmp_gt_f32_e64 s[10:11], s80, v136
	v_cmp_gt_f32_e64 s[42:43], s80, v137
	v_cndmask_b32_e64 v142, 0, 32, vcc
	v_cndmask_b32_e64 v143, 0, 32, s[8:9]
	v_cndmask_b32_e64 v144, 0, 32, s[10:11]
	v_cndmask_b32_e64 v145, 0, 32, s[42:43]
	v_cndmask_b32_e64 v198, 0, v214, vcc
	v_cndmask_b32_e64 v199, 0, v214, s[8:9]
	v_cndmask_b32_e64 v204, 0, v214, s[10:11]
	v_cndmask_b32_e64 v205, 0, v214, s[42:43]
	v_ldexp_f32 v130, v130, v138
	v_ldexp_f32 v131, v131, v139
	v_ldexp_f32 v132, v132, v140
	v_ldexp_f32 v133, v133, v141
	v_ldexp_f32 v134, v134, v142
	v_ldexp_f32 v135, v135, v143
	v_ldexp_f32 v136, v136, v144
	v_ldexp_f32 v137, v137, v145
	v_log_f32_e32 v130, v130
	v_log_f32_e32 v131, v131
	v_log_f32_e32 v132, v132
	v_log_f32_e32 v133, v133
	v_log_f32_e32 v134, v134
	v_log_f32_e32 v135, v135
	v_log_f32_e32 v136, v136
	v_log_f32_e32 v137, v137
	v_mul_f32_e32 v138, 0x3f317217, v130
	v_mul_f32_e32 v139, 0x3f317217, v131
	v_mul_f32_e32 v140, 0x3f317217, v132
	v_mul_f32_e32 v141, 0x3f317217, v133
	v_mul_f32_e32 v142, 0x3f317217, v134
	v_mul_f32_e32 v143, 0x3f317217, v135
	v_mul_f32_e32 v144, 0x3f317217, v136
	v_mul_f32_e32 v145, 0x3f317217, v137
	v_fma_f32 v138, v130, s85, -v138
	v_fma_f32 v139, v131, s85, -v139
	v_fma_f32 v140, v132, s85, -v140
	v_fma_f32 v141, v133, s85, -v141
	v_fma_f32 v142, v134, s85, -v142
	v_fma_f32 v143, v135, s85, -v143
	v_fma_f32 v144, v136, s85, -v144
	v_fma_f32 v145, v137, s85, -v145
	v_fmac_f32_e32 v138, 0x3377d1cf, v130
	v_fmac_f32_e32 v139, 0x3377d1cf, v131
	v_fmac_f32_e32 v140, 0x3377d1cf, v132
	v_fmac_f32_e32 v141, 0x3377d1cf, v133
	v_fmac_f32_e32 v142, 0x3377d1cf, v134
	v_fmac_f32_e32 v143, 0x3377d1cf, v135
	v_fmac_f32_e32 v144, 0x3377d1cf, v136
	v_fmac_f32_e32 v145, 0x3377d1cf, v137
	v_fmac_f32_e32 v138, 0x3f317217, v130
; template <int MODE> __device__ __forceinline__ void gemm_epilogue(f32x4 (&acc)[2][2][4][2], const GD& g, const pg8::Unit& u, int wr, int wc, int fr, int fq, LAS unsigned char* lds, const float (&rsv)[2][4]) {
;     ...
;                 for (int m = 0; m < 4; ++m) { float* rowp = LOGF + (size_t)(rt + ai * 128 + m * 16) * 1024 + col0;
; #pragma unroll
;                     for (int bj = 0; bj < 2; ++bj)
;                     {
; #pragma unroll
;                         for (int n = 0; n < 2; ++n) { f32x4 v = acc[ai][bj][m][n], o;
; #pragma unroll
;                             for (int j = 0; j < 4; ++j) { const float sg = 1.f / (1.f + __expf(-v[j])); const float f = lb[bj][n][j] + (1.f - lb[bj][n][j]) * sg; o[j] = __logf(f); }
;                             *(f32x4*)(rowp + bj * 128 + 4 * n) = o; } } }
	v_fmac_f32_e32 v139, 0x3f317217, v131
	v_fmac_f32_e32 v140, 0x3f317217, v132
	v_fmac_f32_e32 v141, 0x3f317217, v133
	v_fmac_f32_e32 v142, 0x3f317217, v134
	v_fmac_f32_e32 v143, 0x3f317217, v135
	v_fmac_f32_e32 v144, 0x3f317217, v136
	v_fmac_f32_e32 v145, 0x3f317217, v137
	v_cmp_lt_f32_e64 vcc, |v130|, s55
	v_cmp_lt_f32_e64 s[8:9], |v131|, s55
	v_cmp_lt_f32_e64 s[10:11], |v132|, s55
	v_cmp_lt_f32_e64 s[42:43], |v133|, s55
	v_cndmask_b32_e64 v130, v130, v138, vcc
	v_cndmask_b32_e64 v131, v131, v139, s[8:9]
	v_cndmask_b32_e64 v132, v132, v140, s[10:11]
	v_cndmask_b32_e64 v133, v133, v141, s[42:43]
	v_cmp_lt_f32_e64 vcc, |v134|, s55
	v_cmp_lt_f32_e64 s[8:9], |v135|, s55
	v_cmp_lt_f32_e64 s[10:11], |v136|, s55
	v_cmp_lt_f32_e64 s[42:43], |v137|, s55
	v_cndmask_b32_e64 v134, v134, v142, vcc
	v_cndmask_b32_e64 v135, v135, v143, s[8:9]
	v_cndmask_b32_e64 v136, v136, v144, s[10:11]
	v_cndmask_b32_e64 v137, v137, v145, s[42:43]
	v_sub_f32_e32 v130, v130, v162
	v_sub_f32_e32 v131, v131, v163
	v_sub_f32_e32 v132, v132, v196
	v_sub_f32_e32 v133, v133, v197
	v_sub_f32_e32 v134, v134, v198
	v_sub_f32_e32 v135, v135, v199
	v_sub_f32_e32 v136, v136, v204
	v_sub_f32_e32 v137, v137, v205
	global_store_dwordx4 v159, v[130:133], s[2:3]
	global_store_dwordx4 v159, v[134:137], s[2:3] offset:16
	s_nop 0
	v_pk_mul_f32 v[130:131], v[6:7], v[160:161]
	v_pk_mul_f32 v[132:133], v[8:9], v[160:161]
	v_pk_mul_f32 v[134:135], v[2:3], v[160:161]
	v_pk_mul_f32 v[136:137], v[4:5], v[160:161]
	v_exp_f32_e32 v130, v130
	v_exp_f32_e32 v131, v131
	v_exp_f32_e32 v132, v132
	v_exp_f32_e32 v133, v133
	v_exp_f32_e32 v134, v134
	v_exp_f32_e32 v135, v135
	v_exp_f32_e32 v136, v136
	v_exp_f32_e32 v137, v137
	v_pk_add_f32 v[130:131], v[130:131], 1.0 op_sel_hi:[1,0]
	v_pk_add_f32 v[132:133], v[132:133], 1.0 op_sel_hi:[1,0]
	v_pk_add_f32 v[134:135], v[134:135], 1.0 op_sel_hi:[1,0]
	v_pk_add_f32 v[136:137], v[136:137], 1.0 op_sel_hi:[1,0]
	v_rcp_f32_e32 v130, v130
	v_rcp_f32_e32 v131, v131
	v_rcp_f32_e32 v132, v132
	v_rcp_f32_e32 v133, v133
	v_rcp_f32_e32 v134, v134
	v_rcp_f32_e32 v135, v135
	v_rcp_f32_e32 v136, v136
	v_rcp_f32_e32 v137, v137
	v_pk_fma_f32 v[130:131], v[130:131], v[186:187], v[228:229]
	v_pk_fma_f32 v[132:133], v[132:133], v[188:189], v[230:231]
	v_pk_fma_f32 v[134:135], v[134:135], v[190:191], v[232:233]
	v_pk_fma_f32 v[136:137], v[136:137], v[192:193], v[234:235]
	v_cmp_gt_f32_e32 vcc, s80, v130
	v_cmp_gt_f32_e64 s[8:9], s80, v131
	v_cmp_gt_f32_e64 s[10:11], s80, v132
	v_cmp_gt_f32_e64 s[42:43], s80, v133
	v_cndmask_b32_e64 v138, 0, 32, vcc
	v_cndmask_b32_e64 v139, 0, 32, s[8:9]
	v_cndmask_b32_e64 v140, 0, 32, s[10:11]
	v_cndmask_b32_e64 v141, 0, 32, s[42:43]
	v_cndmask_b32_e64 v162, 0, v214, vcc
	v_cndmask_b32_e64 v163, 0, v214, s[8:9]
	v_cndmask_b32_e64 v196, 0, v214, s[10:11]
	v_cndmask_b32_e64 v197, 0, v214, s[42:43]
	v_cmp_gt_f32_e32 vcc, s80, v134
	v_cmp_gt_f32_e64 s[8:9], s80, v135
	v_cmp_gt_f32_e64 s[10:11], s80, v136
	v_cmp_gt_f32_e64 s[42:43], s80, v137
	v_cndmask_b32_e64 v142, 0, 32, vcc
	v_cndmask_b32_e64 v143, 0, 32, s[8:9]
	v_cndmask_b32_e64 v144, 0, 32, s[10:11]
	v_cndmask_b32_e64 v145, 0, 32, s[42:43]
	v_cndmask_b32_e64 v198, 0, v214, vcc
	v_cndmask_b32_e64 v199, 0, v214, s[8:9]
	v_cndmask_b32_e64 v204, 0, v214, s[10:11]
	v_cndmask_b32_e64 v205, 0, v214, s[42:43]
	v_ldexp_f32 v130, v130, v138
	v_ldexp_f32 v131, v131, v139
	v_ldexp_f32 v132, v132, v140
	v_ldexp_f32 v133, v133, v141
	v_ldexp_f32 v134, v134, v142
	v_ldexp_f32 v135, v135, v143
	v_ldexp_f32 v136, v136, v144
	v_ldexp_f32 v137, v137, v145
	v_log_f32_e32 v130, v130
	v_log_f32_e32 v131, v131
	v_log_f32_e32 v132, v132
	v_log_f32_e32 v133, v133
	v_log_f32_e32 v134, v134
	v_log_f32_e32 v135, v135
	v_log_f32_e32 v136, v136
	v_log_f32_e32 v137, v137
	v_mul_f32_e32 v138, 0x3f317217, v130
	v_mul_f32_e32 v139, 0x3f317217, v131
	v_mul_f32_e32 v140, 0x3f317217, v132
	v_mul_f32_e32 v141, 0x3f317217, v133
	v_mul_f32_e32 v142, 0x3f317217, v134
	v_mul_f32_e32 v143, 0x3f317217, v135
	v_mul_f32_e32 v144, 0x3f317217, v136
	v_mul_f32_e32 v145, 0x3f317217, v137
	v_fma_f32 v138, v130, s85, -v138
	v_fma_f32 v139, v131, s85, -v139
	v_fma_f32 v140, v132, s85, -v140
	v_fma_f32 v141, v133, s85, -v141
	v_fma_f32 v142, v134, s85, -v142
	v_fma_f32 v143, v135, s85, -v143
	v_fma_f32 v144, v136, s85, -v144
	v_fma_f32 v145, v137, s85, -v145
	v_fmac_f32_e32 v138, 0x3377d1cf, v130
	v_fmac_f32_e32 v139, 0x3377d1cf, v131
	v_fmac_f32_e32 v140, 0x3377d1cf, v132
	v_fmac_f32_e32 v141, 0x3377d1cf, v133
	v_fmac_f32_e32 v142, 0x3377d1cf, v134
	v_fmac_f32_e32 v143, 0x3377d1cf, v135
	v_fmac_f32_e32 v144, 0x3377d1cf, v136
	v_fmac_f32_e32 v145, 0x3377d1cf, v137
	v_fmac_f32_e32 v138, 0x3f317217, v130
	v_fmac_f32_e32 v139, 0x3f317217, v131
	v_fmac_f32_e32 v140, 0x3f317217, v132
	v_fmac_f32_e32 v141, 0x3f317217, v133
	v_fmac_f32_e32 v142, 0x3f317217, v134
	v_fmac_f32_e32 v143, 0x3f317217, v135
	v_fmac_f32_e32 v144, 0x3f317217, v136
	v_fmac_f32_e32 v145, 0x3f317217, v137
	v_cmp_lt_f32_e64 vcc, |v130|, s55
	v_cmp_lt_f32_e64 s[8:9], |v131|, s55
	v_cmp_lt_f32_e64 s[10:11], |v132|, s55
	v_cmp_lt_f32_e64 s[42:43], |v133|, s55
	v_cndmask_b32_e64 v130, v130, v138, vcc
	v_cndmask_b32_e64 v131, v131, v139, s[8:9]
	v_cndmask_b32_e64 v132, v132, v140, s[10:11]
	v_cndmask_b32_e64 v133, v133, v141, s[42:43]
	v_cmp_lt_f32_e64 vcc, |v134|, s55
	v_cmp_lt_f32_e64 s[8:9], |v135|, s55
	v_cmp_lt_f32_e64 s[10:11], |v136|, s55
	v_cmp_lt_f32_e64 s[42:43], |v137|, s55
	v_cndmask_b32_e64 v134, v134, v142, vcc
	v_cndmask_b32_e64 v135, v135, v143, s[8:9]
	v_cndmask_b32_e64 v136, v136, v144, s[10:11]
	v_cndmask_b32_e64 v137, v137, v145, s[42:43]
	v_sub_f32_e32 v130, v130, v162
	v_sub_f32_e32 v131, v131, v163
	v_sub_f32_e32 v132, v132, v196
	v_sub_f32_e32 v133, v133, v197
	v_sub_f32_e32 v134, v134, v198
	v_sub_f32_e32 v135, v135, v199
	v_sub_f32_e32 v136, v136, v204
	v_sub_f32_e32 v137, v137, v205
	global_store_dwordx4 v159, v[130:133], s[2:3] offset:512
	global_store_dwordx4 v159, v[134:137], s[2:3] offset:528
	s_nop 0
; __device__ __forceinline__ void rsv_load(float (&rsv)[2][4], const GD& g, const pg8::Unit& u, int wr, int fr) {
;     if (g.f2) { const int rg = (u.z / g.nz2) * g.ro1 + u.pm * 256 + wr * 64 + fr;
; #pragma unroll
;         for (int ai = 0; ai < 2; ++ai)
; #pragma unroll
;             for (int m = 0; m < 4; ++m) rsv[ai][m] = g.f2[rg + ai * 128 + m * 16]; }
; template <int MODE> __device__ __forceinline__ void gemm_phase(LAS unsigned char* lds, const GD& g, const int tid) {
;     ...
;         if (!has_next) break;
; #pragma unroll
;         for (int a = 0; a < 2; ++a)
; #pragma unroll
;             for (int b = 0; b < 2; ++b)
; #pragma unroll
;                 for (int m = 0; m < 4; ++m)
; #pragma unroll
;                     for (int n = 0; n < 2; ++n) acc[a][b][m][n] = (f32x4){0.f, 0.f, 0.f, 0.f};
;         cur = nxt; cA = nA; cB = nB; ++ui; rsv_load(rsv, g, cur, wr, fr);
.Levin_done:
	s_andn2_b64 vcc, exec, s[86:87]
	s_mov_b64 s[2:3], -1
	s_cbranch_vccnz .LBB0_380
.LBB0_479:
	s_and_b64 vcc, exec, s[6:7]
	s_cbranch_vccnz .LBB0_481
	s_ashr_i32 s0, s31, 31
	v_readlane_b32 s1, v254, 63
	s_xor_b32 s0, s0, s1
	s_abs_i32 s1, s31
	v_readlane_b32 s2, v255, 2
	s_mul_hi_u32 s2, s1, s2
	s_mul_i32 s3, s2, s30
	s_sub_i32 s1, s1, s3
	s_add_i32 s3, s2, 1
	s_sub_i32 s6, s1, s30
	s_cmp_ge_u32 s1, s30
	s_cselect_b32 s2, s3, s2
	s_cselect_b32 s1, s6, s1
	s_add_i32 s3, s2, 1
	s_cmp_ge_u32 s1, s30
	s_cselect_b32 s1, s3, s2
	s_xor_b32 s1, s1, s0
	s_sub_i32 s0, s1, s0
	v_readlane_b32 s1, v254, 59
	s_mul_i32 s0, s0, s1
	s_lshl_b32 s1, s92, 8
	s_add_i32 s0, s0, s1
	v_add_u32_e32 v2, s0, v164
	v_readlane_b32 s0, v254, 52
	v_ashrrev_i32_e32 v3, 31, v2
	v_readlane_b32 s1, v254, 53
	s_nop 1
	v_lshl_add_u64 v[2:3], v[2:3], 2, s[0:1]
	flat_load_dword v165, v[2:3]
	flat_load_dword v166, v[2:3] offset:64
	flat_load_dword v167, v[2:3] offset:128
	flat_load_dword v168, v[2:3] offset:192
	flat_load_dword v169, v[2:3] offset:512
	flat_load_dword v170, v[2:3] offset:576
	flat_load_dword v171, v[2:3] offset:640
	flat_load_dword v172, v[2:3] offset:704
